# removed 30 compiler-inserted vmcnt(0) before ds_reads in the 5 GEMM K-loops (LDS-DMA stays in flight across barriers as the 8-phase design intends)
# speedup vs baseline: 1.0547x; 1.0547x over previous
; #define G8_STAGE(bufoff, gbase) do { _Pragma("unroll") for (int _i = 0; _i < 2; ++_i) \
;     __builtin_amdgcn_global_load_lds((const unsigned*)((const char*)(gbase) + voffA[_i]), (LAS unsigned*)(lds + (bufoff) + ldsw + _i * 8192), 16, 0, 0); } while (0)
; #define G8_LDA(dst, b, h) do { _Pragma("unroll") for (int m = 0; m < 4; ++m) _Pragma("unroll") for (int k = 0; k < 2; ++k) dst[m][k] = *(const LAS h16x8*)(lds + G8_SA(b, h) + aoff + m * 2048 + k * 1024); } while (0)
; #define G8_LDB(dst, b, h) do { _Pragma("unroll") for (int n = 0; n < 2; ++n) _Pragma("unroll") for (int k = 0; k < 2; ++k) dst[n][k] = *(const LAS h16x8*)(lds + G8_SB(b, h) + boff + n * 2048 + k * 1024); } while (0)
; #define G8_MMA(ai, bj, At, Bt_) do { __builtin_amdgcn_s_setprio(1); _Pragma("unroll") for (int m = 0; m < 4; ++m) _Pragma("unroll") for (int n = 0; n < 2; ++n) _Pragma("unroll") for (int k = 0; k < 2; ++k) \
;     acc[ai][bj][m][n] = __builtin_amdgcn_mfma_f32_16x16x32_f16(Bt_[n][k], At[m][k], acc[ai][bj][m][n], 0, 0, 0); __builtin_amdgcn_s_setprio(0); } while (0)
; #define G8_WAIT_V(n) asm volatile("s_waitcnt vmcnt(" #n ")" ::: "memory")
; #define G8_WAIT_L(n) asm volatile("s_waitcnt lgkmcnt(" #n ")" ::: "memory")
; #define G8_BAR __builtin_amdgcn_s_barrier()
; #define G8_SCHED __builtin_amdgcn_sched_barrier(0)
; template <class Epi>
; __device__ __forceinline__ void gemm_phase(LAS unsigned char* lds, const h16* A, const h16* Bt, int K, const Order& S, const Epi& E) {
;     ...
;       const bool last = (t == nt - 2);
;       const char* a1 = cA + (size_t)(t + 1) * kstep;
;       const char* a2 = last ? nA : cA + (size_t)(t + 2) * kstep;
;       const char* b2 = last ? nB : cB + (size_t)(t + 2) * kstep;
;       const char* a3 = a2 + kstep;
;       const char* b3 = b2 + kstep;
;       if (Epi::MID_T >= 0 && t == Epi::MID_T) E.mid(acc, ui, wr, fr);
;       G8_LDB(B0, 0, 0); G8_SCHED; G8_LDA(At, 0, 0); G8_STAGE(G8_SA(1, 1), a1 + hstep);
;       G8_WAIT_L(8); G8_BAR; G8_WAIT_L(0); G8_MMA(0, 0, At, B0); G8_BAR; G8_SCHED;
;       G8_LDB(B1, 0, 1); G8_STAGE(G8_SB(0, 0), b2);
;       G8_BAR; G8_WAIT_L(0); G8_MMA(0, 1, At, B1); G8_BAR;
;       G8_LDA(At, 0, 1); G8_STAGE(G8_SA(0, 0), a2);
;       G8_BAR; G8_WAIT_L(0); G8_MMA(1, 0, At, B0); G8_BAR; G8_SCHED;
;       G8_STAGE(G8_SB(0, 1), b2 + hstep);
;       G8_WAIT_V(6); G8_BAR; G8_MMA(1, 1, At, B1); G8_BAR;
.LBB0_195:
	ds_read_b128 v[152:155], v161
	ds_read_b128 v[178:181], v162
	ds_read_b128 v[182:185], v163
	ds_read_b128 v[186:189], v164
	s_add_u32 s12, s10, 0xfffc0080
	s_addc_u32 s13, s11, -1
	s_cmp_eq_u32 s54, 12
	s_cselect_b32 s15, s19, s13
	s_cselect_b32 s14, s25, s12
	s_cselect_b32 s13, s17, s53
	s_cselect_b32 s12, s26, s27
	s_mov_b32 m0, s50
	v_lshl_add_u64 v[140:141], s[10:11], 0, v[136:137]
	ds_read_b128 v[202:205], v159
	ds_read_b128 v[206:209], v159 offset:1024
	ds_read_b128 v[210:213], v159 offset:2048
	ds_read_b128 v[214:217], v159 offset:3072
	ds_read_b128 v[218:221], v159 offset:4096
	ds_read_b128 v[222:225], v159 offset:5120
	ds_read_b128 v[226:229], v159 offset:6144
	ds_read_b128 v[230:233], v159 offset:7168
	global_load_lds_dwordx4 v[140:141], off
	v_lshl_add_u64 v[140:141], s[10:11], 0, v[138:139]
	s_mov_b32 m0, s51
	s_nop 0
	global_load_lds_dwordx4 v[140:141], off
	s_waitcnt lgkmcnt(8)
	s_barrier
	s_waitcnt lgkmcnt(0)
	s_setprio 1
	s_waitcnt lgkmcnt(0)
	v_mfma_f32_16x16x32_f16 v[126:129], v[152:155], v[202:205], v[126:129]
	v_mfma_f32_16x16x32_f16 v[122:125], v[182:185], v[202:205], v[122:125]
	v_mfma_f32_16x16x32_f16 v[110:113], v[152:155], v[210:213], v[110:113]
	v_mfma_f32_16x16x32_f16 v[106:109], v[182:185], v[210:213], v[106:109]
	v_mfma_f32_16x16x32_f16 v[94:97], v[152:155], v[218:221], v[94:97]
	v_mfma_f32_16x16x32_f16 v[90:93], v[182:185], v[218:221], v[90:93]
	v_mfma_f32_16x16x32_f16 v[78:81], v[152:155], v[226:229], v[78:81]
	v_mfma_f32_16x16x32_f16 v[74:77], v[182:185], v[226:229], v[74:77]
	v_mfma_f32_16x16x32_f16 v[126:129], v[178:181], v[206:209], v[126:129]
	v_mfma_f32_16x16x32_f16 v[122:125], v[186:189], v[206:209], v[122:125]
	v_mfma_f32_16x16x32_f16 v[110:113], v[178:181], v[214:217], v[110:113]
	v_mfma_f32_16x16x32_f16 v[106:109], v[186:189], v[214:217], v[106:109]
	v_mfma_f32_16x16x32_f16 v[94:97], v[178:181], v[222:225], v[94:97]
	v_mfma_f32_16x16x32_f16 v[90:93], v[186:189], v[222:225], v[90:93]
	v_mfma_f32_16x16x32_f16 v[78:81], v[178:181], v[230:233], v[78:81]
	v_mfma_f32_16x16x32_f16 v[74:77], v[186:189], v[230:233], v[74:77]
	s_setprio 0
	s_barrier
	s_mov_b32 m0, s36
	v_lshl_add_u64 v[140:141], s[12:13], 0, v[132:133]
	ds_read_b128 v[234:237], v165
	ds_read_b128 v[238:241], v166
	ds_read_b128 v[242:245], v167
	ds_read_b128 v[246:249], v168
	global_load_lds_dwordx4 v[140:141], off
	v_lshl_add_u64 v[156:157], s[12:13], 0, v[130:131]
	s_mov_b32 m0, s37
	s_nop 0
	global_load_lds_dwordx4 v[156:157], off
	s_barrier
	s_waitcnt lgkmcnt(0)
	s_setprio 1
	s_waitcnt lgkmcnt(0)
	v_mfma_f32_16x16x32_f16 v[118:121], v[234:237], v[202:205], v[118:121]
	v_mfma_f32_16x16x32_f16 v[114:117], v[242:245], v[202:205], v[114:117]
	v_mfma_f32_16x16x32_f16 v[102:105], v[234:237], v[210:213], v[102:105]
	v_mfma_f32_16x16x32_f16 v[98:101], v[242:245], v[210:213], v[98:101]
	v_mfma_f32_16x16x32_f16 v[86:89], v[234:237], v[218:221], v[86:89]
	v_mfma_f32_16x16x32_f16 v[82:85], v[242:245], v[218:221], v[82:85]
	v_mfma_f32_16x16x32_f16 v[70:73], v[234:237], v[226:229], v[70:73]
	v_mfma_f32_16x16x32_f16 v[66:69], v[242:245], v[226:229], v[66:69]
	v_mfma_f32_16x16x32_f16 v[118:121], v[238:241], v[206:209], v[118:121]
	v_mfma_f32_16x16x32_f16 v[114:117], v[246:249], v[206:209], v[114:117]
	v_mfma_f32_16x16x32_f16 v[102:105], v[238:241], v[214:217], v[102:105]
	v_mfma_f32_16x16x32_f16 v[98:101], v[246:249], v[214:217], v[98:101]
	v_mfma_f32_16x16x32_f16 v[86:89], v[238:241], v[222:225], v[86:89]
	v_mfma_f32_16x16x32_f16 v[82:85], v[246:249], v[222:225], v[82:85]
	v_mfma_f32_16x16x32_f16 v[70:73], v[238:241], v[230:233], v[70:73]
	v_mfma_f32_16x16x32_f16 v[66:69], v[246:249], v[230:233], v[66:69]
	s_setprio 0
	s_mov_b32 m0, s35
	v_lshl_add_u64 v[250:251], s[14:15], 0, v[132:133]
	s_barrier
	ds_read_b128 v[202:205], v159 offset:16384
	ds_read_b128 v[206:209], v159 offset:17408
	ds_read_b128 v[210:213], v159 offset:18432
	ds_read_b128 v[214:217], v159 offset:19456
	ds_read_b128 v[218:221], v159 offset:20480
	ds_read_b128 v[222:225], v159 offset:21504
	ds_read_b128 v[226:229], v159 offset:22528
	ds_read_b128 v[230:233], v159 offset:23552
	global_load_lds_dwordx4 v[250:251], off
	v_lshl_add_u64 v[252:253], s[14:15], 0, v[130:131]
	s_mov_b32 m0, s38
	s_nop 0
	global_load_lds_dwordx4 v[252:253], off
	s_barrier
	s_waitcnt lgkmcnt(0)
	s_setprio 1
	s_waitcnt lgkmcnt(0)
	v_mfma_f32_16x16x32_f16 v[62:65], v[152:155], v[202:205], v[62:65]
	v_mfma_f32_16x16x32_f16 v[58:61], v[182:185], v[202:205], v[58:61]
	v_mfma_f32_16x16x32_f16 v[46:49], v[152:155], v[210:213], v[46:49]
	v_mfma_f32_16x16x32_f16 v[42:45], v[182:185], v[210:213], v[42:45]
	v_mfma_f32_16x16x32_f16 v[30:33], v[152:155], v[218:221], v[30:33]
	v_mfma_f32_16x16x32_f16 v[26:29], v[182:185], v[218:221], v[26:29]
	v_mfma_f32_16x16x32_f16 v[14:17], v[152:155], v[226:229], v[14:17]
	v_mfma_f32_16x16x32_f16 v[10:13], v[182:185], v[226:229], v[10:13]
	v_mfma_f32_16x16x32_f16 v[62:65], v[178:181], v[206:209], v[62:65]
	v_mfma_f32_16x16x32_f16 v[58:61], v[186:189], v[206:209], v[58:61]
	v_mfma_f32_16x16x32_f16 v[46:49], v[178:181], v[214:217], v[46:49]
	v_mfma_f32_16x16x32_f16 v[42:45], v[186:189], v[214:217], v[42:45]
	v_mfma_f32_16x16x32_f16 v[30:33], v[178:181], v[222:225], v[30:33]
	v_mfma_f32_16x16x32_f16 v[26:29], v[186:189], v[222:225], v[26:29]
	v_mfma_f32_16x16x32_f16 v[14:17], v[178:181], v[230:233], v[14:17]
	v_mfma_f32_16x16x32_f16 v[10:13], v[186:189], v[230:233], v[10:13]
	s_setprio 0
	s_barrier
	s_add_u32 s56, s12, 0x40000
	s_addc_u32 s57, s13, 0
	s_mov_b32 m0, s39
	v_lshl_add_u64 v[152:153], s[56:57], 0, v[132:133]
	global_load_lds_dwordx4 v[152:153], off
	v_lshl_add_u64 v[152:153], s[56:57], 0, v[130:131]
	s_mov_b32 m0, s40
	s_nop 0
	global_load_lds_dwordx4 v[152:153], off
	s_waitcnt vmcnt(6)
	s_barrier
; #define G8_STAGE(bufoff, gbase) do { _Pragma("unroll") for (int _i = 0; _i < 2; ++_i) \
;     __builtin_amdgcn_global_load_lds((const unsigned*)((const char*)(gbase) + voffA[_i]), (LAS unsigned*)(lds + (bufoff) + ldsw + _i * 8192), 16, 0, 0); } while (0)
; #define G8_LDA(dst, b, h) do { _Pragma("unroll") for (int m = 0; m < 4; ++m) _Pragma("unroll") for (int k = 0; k < 2; ++k) dst[m][k] = *(const LAS h16x8*)(lds + G8_SA(b, h) + aoff + m * 2048 + k * 1024); } while (0)
; #define G8_LDB(dst, b, h) do { _Pragma("unroll") for (int n = 0; n < 2; ++n) _Pragma("unroll") for (int k = 0; k < 2; ++k) dst[n][k] = *(const LAS h16x8*)(lds + G8_SB(b, h) + boff + n * 2048 + k * 1024); } while (0)
; #define G8_MMA(ai, bj, At, Bt_) do { __builtin_amdgcn_s_setprio(1); _Pragma("unroll") for (int m = 0; m < 4; ++m) _Pragma("unroll") for (int n = 0; n < 2; ++n) _Pragma("unroll") for (int k = 0; k < 2; ++k) \
;     acc[ai][bj][m][n] = __builtin_amdgcn_mfma_f32_16x16x32_f16(Bt_[n][k], At[m][k], acc[ai][bj][m][n], 0, 0, 0); __builtin_amdgcn_s_setprio(0); } while (0)
; #define G8_WAIT_V(n) asm volatile("s_waitcnt vmcnt(" #n ")" ::: "memory")
; #define G8_WAIT_L(n) asm volatile("s_waitcnt lgkmcnt(" #n ")" ::: "memory")
; #define G8_BAR __builtin_amdgcn_s_barrier()
; #define G8_SCHED __builtin_amdgcn_sched_barrier(0)
; template <class Epi>
; __device__ __forceinline__ void gemm_phase(LAS unsigned char* lds, const h16* A, const h16* Bt, int K, const Order& S, const Epi& E) {
;     ...
;       G8_WAIT_V(6); G8_BAR; G8_MMA(1, 1, At, B1); G8_BAR;
;       G8_LDB(B0, 1, 0); G8_SCHED; G8_LDA(At, 1, 0); G8_STAGE(G8_SA(0, 1), a2 + hstep);
;       G8_WAIT_L(8); G8_BAR; G8_WAIT_L(0); G8_MMA(0, 0, At, B0); G8_BAR; G8_SCHED;
;       G8_LDB(B1, 1, 1); G8_STAGE(G8_SB(1, 0), b3);
;       G8_BAR; G8_WAIT_L(0); G8_MMA(0, 1, At, B1); G8_BAR;
	s_setprio 1
	v_mfma_f32_16x16x32_f16 v[54:57], v[234:237], v[202:205], v[54:57]
	v_mfma_f32_16x16x32_f16 v[50:53], v[242:245], v[202:205], v[50:53]
	v_mfma_f32_16x16x32_f16 v[38:41], v[234:237], v[210:213], v[38:41]
	v_mfma_f32_16x16x32_f16 v[34:37], v[242:245], v[210:213], v[34:37]
	v_mfma_f32_16x16x32_f16 v[22:25], v[234:237], v[218:221], v[22:25]
	v_mfma_f32_16x16x32_f16 v[18:21], v[242:245], v[218:221], v[18:21]
	v_mfma_f32_16x16x32_f16 v[6:9], v[234:237], v[226:229], v[6:9]
	v_mfma_f32_16x16x32_f16 v[2:5], v[242:245], v[226:229], v[2:5]
	v_mfma_f32_16x16x32_f16 v[54:57], v[238:241], v[206:209], v[54:57]
	v_mfma_f32_16x16x32_f16 v[50:53], v[246:249], v[206:209], v[50:53]
	v_mfma_f32_16x16x32_f16 v[38:41], v[238:241], v[214:217], v[38:41]
	v_mfma_f32_16x16x32_f16 v[34:37], v[246:249], v[214:217], v[34:37]
	v_mfma_f32_16x16x32_f16 v[22:25], v[238:241], v[222:225], v[22:25]
	v_mfma_f32_16x16x32_f16 v[18:21], v[246:249], v[222:225], v[18:21]
	v_mfma_f32_16x16x32_f16 v[6:9], v[238:241], v[230:233], v[6:9]
	v_mfma_f32_16x16x32_f16 v[2:5], v[246:249], v[230:233], v[2:5]
	s_setprio 0
	s_barrier
	ds_read_b128 v[152:155], v169
	ds_read_b128 v[178:181], v170
	ds_read_b128 v[182:185], v171
	ds_read_b128 v[186:189], v172
	s_add_u32 s14, s14, 0x40000
	s_addc_u32 s15, s15, 0
	s_mov_b32 m0, s41
	v_lshl_add_u64 v[234:235], s[14:15], 0, v[132:133]
	ds_read_b128 v[202:205], v159 offset:32768
	ds_read_b128 v[206:209], v159 offset:33792
	ds_read_b128 v[210:213], v159 offset:34816
	ds_read_b128 v[214:217], v159 offset:35840
	ds_read_b128 v[218:221], v159 offset:36864
	ds_read_b128 v[222:225], v159 offset:37888
	ds_read_b128 v[226:229], v159 offset:38912
	ds_read_b128 v[230:233], v159 offset:39936
	global_load_lds_dwordx4 v[234:235], off
	v_lshl_add_u64 v[234:235], s[14:15], 0, v[130:131]
	s_mov_b32 m0, s42
	s_nop 0
	global_load_lds_dwordx4 v[234:235], off
	s_waitcnt lgkmcnt(8)
	s_barrier
	s_waitcnt lgkmcnt(0)
	s_setprio 1
	s_waitcnt lgkmcnt(0)
	v_mfma_f32_16x16x32_f16 v[126:129], v[152:155], v[202:205], v[126:129]
	v_mfma_f32_16x16x32_f16 v[122:125], v[182:185], v[202:205], v[122:125]
	v_mfma_f32_16x16x32_f16 v[110:113], v[152:155], v[210:213], v[110:113]
	v_mfma_f32_16x16x32_f16 v[106:109], v[182:185], v[210:213], v[106:109]
	v_mfma_f32_16x16x32_f16 v[94:97], v[152:155], v[218:221], v[94:97]
	v_mfma_f32_16x16x32_f16 v[90:93], v[182:185], v[218:221], v[90:93]
	v_mfma_f32_16x16x32_f16 v[78:81], v[152:155], v[226:229], v[78:81]
	v_mfma_f32_16x16x32_f16 v[74:77], v[182:185], v[226:229], v[74:77]
	v_mfma_f32_16x16x32_f16 v[126:129], v[178:181], v[206:209], v[126:129]
	v_mfma_f32_16x16x32_f16 v[122:125], v[186:189], v[206:209], v[122:125]
	v_mfma_f32_16x16x32_f16 v[110:113], v[178:181], v[214:217], v[110:113]
	v_mfma_f32_16x16x32_f16 v[106:109], v[186:189], v[214:217], v[106:109]
	v_mfma_f32_16x16x32_f16 v[94:97], v[178:181], v[222:225], v[94:97]
	v_mfma_f32_16x16x32_f16 v[90:93], v[186:189], v[222:225], v[90:93]
	v_mfma_f32_16x16x32_f16 v[78:81], v[178:181], v[230:233], v[78:81]
	v_mfma_f32_16x16x32_f16 v[74:77], v[186:189], v[230:233], v[74:77]
	s_setprio 0
	s_barrier
	s_mov_b32 m0, s44
	v_lshl_add_u64 v[140:141], v[140:141], 0, s[94:95]
	ds_read_b128 v[234:237], v173
	ds_read_b128 v[238:241], v174
	ds_read_b128 v[242:245], v175
	ds_read_b128 v[246:249], v176
	global_load_lds_dwordx4 v[140:141], off
	v_lshl_add_u64 v[140:141], v[156:157], 0, s[94:95]
	s_mov_b32 m0, s45
	s_nop 0
	global_load_lds_dwordx4 v[140:141], off
	s_barrier
	s_waitcnt lgkmcnt(0)
	s_setprio 1
	s_waitcnt lgkmcnt(0)
	v_mfma_f32_16x16x32_f16 v[118:121], v[234:237], v[202:205], v[118:121]
	v_mfma_f32_16x16x32_f16 v[114:117], v[242:245], v[202:205], v[114:117]
	v_mfma_f32_16x16x32_f16 v[102:105], v[234:237], v[210:213], v[102:105]
	v_mfma_f32_16x16x32_f16 v[98:101], v[242:245], v[210:213], v[98:101]
	v_mfma_f32_16x16x32_f16 v[86:89], v[234:237], v[218:221], v[86:89]
	v_mfma_f32_16x16x32_f16 v[82:85], v[242:245], v[218:221], v[82:85]
	v_mfma_f32_16x16x32_f16 v[70:73], v[234:237], v[226:229], v[70:73]
	v_mfma_f32_16x16x32_f16 v[66:69], v[242:245], v[226:229], v[66:69]
	v_mfma_f32_16x16x32_f16 v[118:121], v[238:241], v[206:209], v[118:121]
	v_mfma_f32_16x16x32_f16 v[114:117], v[246:249], v[206:209], v[114:117]
	v_mfma_f32_16x16x32_f16 v[102:105], v[238:241], v[214:217], v[102:105]
	v_mfma_f32_16x16x32_f16 v[98:101], v[246:249], v[214:217], v[98:101]
	v_mfma_f32_16x16x32_f16 v[86:89], v[238:241], v[222:225], v[86:89]
	v_mfma_f32_16x16x32_f16 v[82:85], v[246:249], v[222:225], v[82:85]
	v_mfma_f32_16x16x32_f16 v[70:73], v[238:241], v[230:233], v[70:73]
	v_mfma_f32_16x16x32_f16 v[66:69], v[246:249], v[230:233], v[66:69]
	s_setprio 0
	s_mov_b32 m0, s46
	v_lshl_add_u64 v[140:141], v[250:251], 0, s[94:95]
	s_barrier
; #define G8_STAGE(bufoff, gbase) do { _Pragma("unroll") for (int _i = 0; _i < 2; ++_i) \
;     __builtin_amdgcn_global_load_lds((const unsigned*)((const char*)(gbase) + voffA[_i]), (LAS unsigned*)(lds + (bufoff) + ldsw + _i * 8192), 16, 0, 0); } while (0)
; #define G8_LDA(dst, b, h) do { _Pragma("unroll") for (int m = 0; m < 4; ++m) _Pragma("unroll") for (int k = 0; k < 2; ++k) dst[m][k] = *(const LAS h16x8*)(lds + G8_SA(b, h) + aoff + m * 2048 + k * 1024); } while (0)
; #define G8_MMA(ai, bj, At, Bt_) do { __builtin_amdgcn_s_setprio(1); _Pragma("unroll") for (int m = 0; m < 4; ++m) _Pragma("unroll") for (int n = 0; n < 2; ++n) _Pragma("unroll") for (int k = 0; k < 2; ++k) \
;     acc[ai][bj][m][n] = __builtin_amdgcn_mfma_f32_16x16x32_f16(Bt_[n][k], At[m][k], acc[ai][bj][m][n], 0, 0, 0); __builtin_amdgcn_s_setprio(0); } while (0)
; #define G8_WAIT_V(n) asm volatile("s_waitcnt vmcnt(" #n ")" ::: "memory")
; #define G8_WAIT_L(n) asm volatile("s_waitcnt lgkmcnt(" #n ")" ::: "memory")
; #define G8_BAR __builtin_amdgcn_s_barrier()
; #define G8_SCHED __builtin_amdgcn_sched_barrier(0)
; template <class Epi>
; __device__ __forceinline__ void gemm_phase(LAS unsigned char* lds, const h16* A, const h16* Bt, int K, const Order& S, const Epi& E) {
;     ...
;       G8_LDA(At, 1, 1); G8_STAGE(G8_SA(1, 0), a3);
;       G8_BAR; G8_WAIT_L(0); G8_MMA(1, 0, At, B0); G8_BAR; G8_SCHED;
;       G8_STAGE(G8_SB(1, 1), b3 + hstep);
;       G8_WAIT_V(6); G8_BAR; G8_MMA(1, 1, At, B1); G8_BAR;
;     }
;     E(acc, cur, ui, wr, wc, fr, fq);
;   __device__ __forceinline__ void operator()(const f32x4 (&acc)[2][2][4][2], const g8::Unit& u, int ui, int wr, int wc, int fr, int fq) const {
;     const int hs = u.pn * 4 + wc;
;     int gi = -1;
;     if (hs < 4) gi = 0; else if (hs < 6) gi = 1; else if (hs >= 16 && hs < 20) gi = 2; else if (hs == 22) gi = 4; else if (hs == 24) gi = 5;
	ds_read_b128 v[202:205], v159 offset:49152
	ds_read_b128 v[206:209], v159 offset:50176
	ds_read_b128 v[210:213], v159 offset:51200
	ds_read_b128 v[214:217], v159 offset:52224
	ds_read_b128 v[218:221], v159 offset:53248
	ds_read_b128 v[222:225], v159 offset:54272
	ds_read_b128 v[226:229], v159 offset:55296
	ds_read_b128 v[230:233], v159 offset:56320
	global_load_lds_dwordx4 v[140:141], off
	v_lshl_add_u64 v[140:141], v[252:253], 0, s[94:95]
	s_mov_b32 m0, s47
	s_nop 0
	global_load_lds_dwordx4 v[140:141], off
	s_barrier
	s_waitcnt lgkmcnt(0)
	s_setprio 1
	s_waitcnt lgkmcnt(0)
	v_mfma_f32_16x16x32_f16 v[62:65], v[152:155], v[202:205], v[62:65]
	v_mfma_f32_16x16x32_f16 v[58:61], v[182:185], v[202:205], v[58:61]
	v_mfma_f32_16x16x32_f16 v[46:49], v[152:155], v[210:213], v[46:49]
	v_mfma_f32_16x16x32_f16 v[42:45], v[182:185], v[210:213], v[42:45]
	v_mfma_f32_16x16x32_f16 v[30:33], v[152:155], v[218:221], v[30:33]
	v_mfma_f32_16x16x32_f16 v[26:29], v[182:185], v[218:221], v[26:29]
	v_mfma_f32_16x16x32_f16 v[14:17], v[152:155], v[226:229], v[14:17]
	v_mfma_f32_16x16x32_f16 v[10:13], v[182:185], v[226:229], v[10:13]
	v_mfma_f32_16x16x32_f16 v[62:65], v[178:181], v[206:209], v[62:65]
	v_mfma_f32_16x16x32_f16 v[58:61], v[186:189], v[206:209], v[58:61]
	v_mfma_f32_16x16x32_f16 v[46:49], v[178:181], v[214:217], v[46:49]
	v_mfma_f32_16x16x32_f16 v[42:45], v[186:189], v[214:217], v[42:45]
	v_mfma_f32_16x16x32_f16 v[30:33], v[178:181], v[222:225], v[30:33]
	v_mfma_f32_16x16x32_f16 v[26:29], v[186:189], v[222:225], v[26:29]
	v_mfma_f32_16x16x32_f16 v[14:17], v[178:181], v[230:233], v[14:17]
	v_mfma_f32_16x16x32_f16 v[10:13], v[186:189], v[230:233], v[10:13]
	s_setprio 0
	s_barrier
	s_add_u32 s12, s12, 0x40080
	s_addc_u32 s13, s13, 0
	s_mov_b32 m0, s48
	v_lshl_add_u64 v[140:141], s[12:13], 0, v[132:133]
	global_load_lds_dwordx4 v[140:141], off
	v_lshl_add_u64 v[140:141], s[12:13], 0, v[130:131]
	s_mov_b32 m0, s49
	s_nop 0
	global_load_lds_dwordx4 v[140:141], off
	s_waitcnt vmcnt(6)
	s_barrier
	s_setprio 1
	v_mfma_f32_16x16x32_f16 v[54:57], v[234:237], v[202:205], v[54:57]
	v_mfma_f32_16x16x32_f16 v[50:53], v[242:245], v[202:205], v[50:53]
	v_mfma_f32_16x16x32_f16 v[38:41], v[234:237], v[210:213], v[38:41]
	v_mfma_f32_16x16x32_f16 v[34:37], v[242:245], v[210:213], v[34:37]
	v_mfma_f32_16x16x32_f16 v[22:25], v[234:237], v[218:221], v[22:25]
	v_mfma_f32_16x16x32_f16 v[18:21], v[242:245], v[218:221], v[18:21]
	v_mfma_f32_16x16x32_f16 v[6:9], v[234:237], v[226:229], v[6:9]
	v_mfma_f32_16x16x32_f16 v[2:5], v[242:245], v[226:229], v[2:5]
	v_mfma_f32_16x16x32_f16 v[54:57], v[238:241], v[206:209], v[54:57]
	v_mfma_f32_16x16x32_f16 v[50:53], v[246:249], v[206:209], v[50:53]
	v_mfma_f32_16x16x32_f16 v[38:41], v[238:241], v[214:217], v[38:41]
	v_mfma_f32_16x16x32_f16 v[34:37], v[246:249], v[214:217], v[34:37]
	v_mfma_f32_16x16x32_f16 v[22:25], v[238:241], v[222:225], v[22:25]
	v_mfma_f32_16x16x32_f16 v[18:21], v[246:249], v[222:225], v[18:21]
	v_mfma_f32_16x16x32_f16 v[6:9], v[238:241], v[230:233], v[6:9]
	v_mfma_f32_16x16x32_f16 v[2:5], v[246:249], v[230:233], v[2:5]
	s_setprio 0
	s_add_i32 s54, s54, 2
	s_add_u32 s10, s10, 0x100
	s_addc_u32 s11, s11, 0
	s_add_u32 s27, s27, 0x100
	s_addc_u32 s53, s53, 0
	s_cmp_gt_u32 s54, 13
	s_barrier
	s_cbranch_scc0 .LBB0_195
	s_lshl_b32 s10, s24, 2
	s_or_b32 s19, s10, s43
	s_cmp_lt_i32 s19, 4
	s_cbranch_scc1 .LBB0_203
	s_cmp_lt_u32 s19, 6
	s_cbranch_scc1 .LBB0_204
	s_cmp_eq_u32 s24, 4
	s_cbranch_scc1 .LBB0_205
	s_cmp_lt_i32 s19, 24
	s_cbranch_scc1 .LBB0_206
	s_cmp_eq_u32 s19, 24
	s_mov_b64 s[10:11], -1
	s_cbranch_scc0 .LBB0_202
	s_mov_b64 s[10:11], 0

; #define G8_STAGE(bufoff, gbase) do { _Pragma("unroll") for (int _i = 0; _i < 2; ++_i) \
;     __builtin_amdgcn_global_load_lds((const unsigned*)((const char*)(gbase) + voffA[_i]), (LAS unsigned*)(lds + (bufoff) + ldsw + _i * 8192), 16, 0, 0); } while (0)
; #define G8_LDA(dst, b, h) do { _Pragma("unroll") for (int m = 0; m < 4; ++m) _Pragma("unroll") for (int k = 0; k < 2; ++k) dst[m][k] = *(const LAS h16x8*)(lds + G8_SA(b, h) + aoff + m * 2048 + k * 1024); } while (0)
; #define G8_LDB(dst, b, h) do { _Pragma("unroll") for (int n = 0; n < 2; ++n) _Pragma("unroll") for (int k = 0; k < 2; ++k) dst[n][k] = *(const LAS h16x8*)(lds + G8_SB(b, h) + boff + n * 2048 + k * 1024); } while (0)
; #define G8_MMA(ai, bj, At, Bt_) do { __builtin_amdgcn_s_setprio(1); _Pragma("unroll") for (int m = 0; m < 4; ++m) _Pragma("unroll") for (int n = 0; n < 2; ++n) _Pragma("unroll") for (int k = 0; k < 2; ++k) \
;     acc[ai][bj][m][n] = __builtin_amdgcn_mfma_f32_16x16x32_f16(Bt_[n][k], At[m][k], acc[ai][bj][m][n], 0, 0, 0); __builtin_amdgcn_s_setprio(0); } while (0)
; #define G8_WAIT_L(n) asm volatile("s_waitcnt lgkmcnt(" #n ")" ::: "memory")
; #define G8_BAR __builtin_amdgcn_s_barrier()
; #define G8_SCHED __builtin_amdgcn_sched_barrier(0)
; template <class Epi>
; __device__ __forceinline__ void gemm_phase(LAS unsigned char* lds, const h16* A, const h16* Bt, int K, const Order& S, const Epi& E) {
;     ...
;       const char* a1 = cA + (size_t)(t + 1) * kstep;
;       const char* a2 = last ? nA : cA + (size_t)(t + 2) * kstep;
;       const char* b2 = last ? nB : cB + (size_t)(t + 2) * kstep;
;       const char* a3 = a2 + kstep;
;       const char* b3 = b2 + kstep;
;       if (Epi::MID_T >= 0 && t == Epi::MID_T) E.mid(acc, ui, wr, fr);
;       G8_LDB(B0, 0, 0); G8_SCHED; G8_LDA(At, 0, 0); G8_STAGE(G8_SA(1, 1), a1 + hstep);
;       G8_WAIT_L(8); G8_BAR; G8_WAIT_L(0); G8_MMA(0, 0, At, B0); G8_BAR; G8_SCHED;
;       G8_LDB(B1, 0, 1); G8_STAGE(G8_SB(0, 0), b2);
;       G8_BAR; G8_WAIT_L(0); G8_MMA(0, 1, At, B1); G8_BAR;
;       G8_LDA(At, 0, 1); G8_STAGE(G8_SA(0, 0), a2);
;       G8_BAR; G8_WAIT_L(0); G8_MMA(1, 0, At, B0); G8_BAR; G8_SCHED;
.LBB0_2284:
	v_or_b32_e32 v34, 0x10000, v171
	v_add_u32_e32 v46, 0x10400, v171
	v_add_u32_e32 v50, 0x10800, v171
	v_add_u32_e32 v160, 0x10c00, v171
	ds_read_b128 v[34:37], v34
	ds_read_b128 v[46:49], v46
	ds_read_b128 v[50:53], v50
	ds_read_b128 v[160:163], v160
	s_add_u32 s26, s24, 0xfffe0080
	s_addc_u32 s27, s25, -1
	s_cmp_eq_u32 s55, 4
	s_cselect_b32 s29, s3, s27
	s_cselect_b32 s28, s17, s26
	s_cselect_b32 s27, s15, s54
	s_cselect_b32 s26, s23, s53
	v_lshl_add_u64 v[168:169], s[24:25], 0, v[156:157]
	s_add_i32 m0, s37, 0xc000
	ds_read_b128 v[164:167], v170
	ds_read_b128 v[174:177], v170 offset:1024
	ds_read_b128 v[178:181], v170 offset:2048
	ds_read_b128 v[182:185], v170 offset:3072
	ds_read_b128 v[186:189], v170 offset:4096
	ds_read_b128 v[202:205], v170 offset:5120
	ds_read_b128 v[206:209], v170 offset:6144
	ds_read_b128 v[210:213], v170 offset:7168
	global_load_lds_dwordx4 v[168:169], off
	v_lshl_add_u64 v[168:169], s[24:25], 0, v[158:159]
	s_add_i32 m0, s37, 0xe000
	s_nop 0
	global_load_lds_dwordx4 v[168:169], off
	s_waitcnt lgkmcnt(8)
	s_barrier
	s_waitcnt lgkmcnt(0)
	s_setprio 1
	s_waitcnt lgkmcnt(0)
	v_mfma_f32_16x16x32_f16 v[62:65], v[34:37], v[164:167], v[62:65]
	v_mfma_f32_16x16x32_f16 v[138:141], v[50:53], v[164:167], v[138:141]
	v_mfma_f32_16x16x32_f16 v[122:125], v[34:37], v[178:181], v[122:125]
	v_mfma_f32_16x16x32_f16 v[126:129], v[50:53], v[178:181], v[126:129]
	v_mfma_f32_16x16x32_f16 v[106:109], v[34:37], v[186:189], v[106:109]
	v_mfma_f32_16x16x32_f16 v[110:113], v[50:53], v[186:189], v[110:113]
	v_mfma_f32_16x16x32_f16 v[90:93], v[34:37], v[206:209], v[90:93]
	v_mfma_f32_16x16x32_f16 v[94:97], v[50:53], v[206:209], v[94:97]
	v_mfma_f32_16x16x32_f16 v[62:65], v[46:49], v[174:177], v[62:65]
	v_mfma_f32_16x16x32_f16 v[138:141], v[160:163], v[174:177], v[138:141]
	v_mfma_f32_16x16x32_f16 v[122:125], v[46:49], v[182:185], v[122:125]
	v_mfma_f32_16x16x32_f16 v[126:129], v[160:163], v[182:185], v[126:129]
	v_mfma_f32_16x16x32_f16 v[106:109], v[46:49], v[202:205], v[106:109]
	v_mfma_f32_16x16x32_f16 v[110:113], v[160:163], v[202:205], v[110:113]
	v_mfma_f32_16x16x32_f16 v[90:93], v[46:49], v[210:213], v[90:93]
	v_mfma_f32_16x16x32_f16 v[94:97], v[160:163], v[210:213], v[94:97]
	s_setprio 0
	s_barrier
	v_or_b32_e32 v168, 0x14000, v171
	v_add_u32_e32 v169, 0x14400, v171
	ds_read_b128 v[214:217], v168
	ds_read_b128 v[218:221], v169
	v_add_u32_e32 v168, 0x14800, v171
	v_add_u32_e32 v169, 0x14c00, v171
	s_mov_b32 m0, s38
	ds_read_b128 v[222:225], v168
	ds_read_b128 v[226:229], v169
	v_lshl_add_u64 v[168:169], s[26:27], 0, v[0:1]
	global_load_lds_dwordx4 v[168:169], off
	v_lshl_add_u64 v[230:231], s[26:27], 0, v[152:153]
	s_mov_b32 m0, s39
	s_nop 0
	global_load_lds_dwordx4 v[230:231], off
	s_barrier
	s_waitcnt lgkmcnt(0)
	s_setprio 1
	s_waitcnt lgkmcnt(0)
	v_mfma_f32_16x16x32_f16 v[130:133], v[214:217], v[164:167], v[130:133]
	v_mfma_f32_16x16x32_f16 v[134:137], v[222:225], v[164:167], v[134:137]
	v_mfma_f32_16x16x32_f16 v[114:117], v[214:217], v[178:181], v[114:117]
	v_mfma_f32_16x16x32_f16 v[118:121], v[222:225], v[178:181], v[118:121]
	v_mfma_f32_16x16x32_f16 v[98:101], v[214:217], v[186:189], v[98:101]
	v_mfma_f32_16x16x32_f16 v[102:105], v[222:225], v[186:189], v[102:105]
	v_mfma_f32_16x16x32_f16 v[82:85], v[214:217], v[206:209], v[82:85]
	v_mfma_f32_16x16x32_f16 v[86:89], v[222:225], v[206:209], v[86:89]
	v_mfma_f32_16x16x32_f16 v[130:133], v[218:221], v[174:177], v[130:133]
	v_mfma_f32_16x16x32_f16 v[134:137], v[226:229], v[174:177], v[134:137]
	v_mfma_f32_16x16x32_f16 v[114:117], v[218:221], v[182:185], v[114:117]
	v_mfma_f32_16x16x32_f16 v[118:121], v[226:229], v[182:185], v[118:121]
	v_mfma_f32_16x16x32_f16 v[98:101], v[218:221], v[202:205], v[98:101]
	v_mfma_f32_16x16x32_f16 v[102:105], v[226:229], v[202:205], v[102:105]
	v_mfma_f32_16x16x32_f16 v[82:85], v[218:221], v[210:213], v[82:85]
	v_mfma_f32_16x16x32_f16 v[86:89], v[226:229], v[210:213], v[86:89]
	s_setprio 0
	s_mov_b32 m0, s37
	v_lshl_add_u64 v[232:233], s[28:29], 0, v[0:1]
	s_barrier
	ds_read_b128 v[164:167], v170 offset:16384
	ds_read_b128 v[174:177], v170 offset:17408
	ds_read_b128 v[178:181], v170 offset:18432
	ds_read_b128 v[182:185], v170 offset:19456
	ds_read_b128 v[186:189], v170 offset:20480
	ds_read_b128 v[202:205], v170 offset:21504
	ds_read_b128 v[206:209], v170 offset:22528
	ds_read_b128 v[210:213], v170 offset:23552
	global_load_lds_dwordx4 v[232:233], off
	v_lshl_add_u64 v[234:235], s[28:29], 0, v[152:153]
	s_mov_b32 m0, s40
	s_nop 0
	global_load_lds_dwordx4 v[234:235], off
	s_barrier
	s_waitcnt lgkmcnt(0)
	s_setprio 1
	s_waitcnt lgkmcnt(0)
	v_mfma_f32_16x16x32_f16 v[74:77], v[34:37], v[164:167], v[74:77]
	v_mfma_f32_16x16x32_f16 v[78:81], v[50:53], v[164:167], v[78:81]
	v_mfma_f32_16x16x32_f16 v[54:57], v[34:37], v[178:181], v[54:57]
	v_mfma_f32_16x16x32_f16 v[58:61], v[50:53], v[178:181], v[58:61]
	v_mfma_f32_16x16x32_f16 v[26:29], v[34:37], v[186:189], v[26:29]
	v_mfma_f32_16x16x32_f16 v[30:33], v[50:53], v[186:189], v[30:33]
	v_mfma_f32_16x16x32_f16 v[10:13], v[34:37], v[206:209], v[10:13]
	v_mfma_f32_16x16x32_f16 v[14:17], v[50:53], v[206:209], v[14:17]
	v_mfma_f32_16x16x32_f16 v[74:77], v[46:49], v[174:177], v[74:77]
	v_mfma_f32_16x16x32_f16 v[78:81], v[160:163], v[174:177], v[78:81]
	v_mfma_f32_16x16x32_f16 v[54:57], v[46:49], v[182:185], v[54:57]
	v_mfma_f32_16x16x32_f16 v[58:61], v[160:163], v[182:185], v[58:61]
	v_mfma_f32_16x16x32_f16 v[26:29], v[46:49], v[202:205], v[26:29]
	v_mfma_f32_16x16x32_f16 v[30:33], v[160:163], v[202:205], v[30:33]
	v_mfma_f32_16x16x32_f16 v[10:13], v[46:49], v[210:213], v[10:13]
	v_mfma_f32_16x16x32_f16 v[14:17], v[160:163], v[210:213], v[14:17]
	s_setprio 0
	s_barrier
; #define G8_STAGE(bufoff, gbase) do { _Pragma("unroll") for (int _i = 0; _i < 2; ++_i) \
;     __builtin_amdgcn_global_load_lds((const unsigned*)((const char*)(gbase) + voffA[_i]), (LAS unsigned*)(lds + (bufoff) + ldsw + _i * 8192), 16, 0, 0); } while (0)
; #define G8_LDA(dst, b, h) do { _Pragma("unroll") for (int m = 0; m < 4; ++m) _Pragma("unroll") for (int k = 0; k < 2; ++k) dst[m][k] = *(const LAS h16x8*)(lds + G8_SA(b, h) + aoff + m * 2048 + k * 1024); } while (0)
; #define G8_LDB(dst, b, h) do { _Pragma("unroll") for (int n = 0; n < 2; ++n) _Pragma("unroll") for (int k = 0; k < 2; ++k) dst[n][k] = *(const LAS h16x8*)(lds + G8_SB(b, h) + boff + n * 2048 + k * 1024); } while (0)
; #define G8_MMA(ai, bj, At, Bt_) do { __builtin_amdgcn_s_setprio(1); _Pragma("unroll") for (int m = 0; m < 4; ++m) _Pragma("unroll") for (int n = 0; n < 2; ++n) _Pragma("unroll") for (int k = 0; k < 2; ++k) \
;     acc[ai][bj][m][n] = __builtin_amdgcn_mfma_f32_16x16x32_f16(Bt_[n][k], At[m][k], acc[ai][bj][m][n], 0, 0, 0); __builtin_amdgcn_s_setprio(0); } while (0)
; #define G8_WAIT_V(n) asm volatile("s_waitcnt vmcnt(" #n ")" ::: "memory")
; #define G8_WAIT_L(n) asm volatile("s_waitcnt lgkmcnt(" #n ")" ::: "memory")
; #define G8_BAR __builtin_amdgcn_s_barrier()
; #define G8_SCHED __builtin_amdgcn_sched_barrier(0)
; template <class Epi>
; __device__ __forceinline__ void gemm_phase(LAS unsigned char* lds, const h16* A, const h16* Bt, int K, const Order& S, const Epi& E) {
;     ...
;       G8_STAGE(G8_SB(0, 1), b2 + hstep);
;       G8_WAIT_V(6); G8_BAR; G8_MMA(1, 1, At, B1); G8_BAR;
;       G8_LDB(B0, 1, 0); G8_SCHED; G8_LDA(At, 1, 0); G8_STAGE(G8_SA(0, 1), a2 + hstep);
;       G8_WAIT_L(8); G8_BAR; G8_WAIT_L(0); G8_MMA(0, 0, At, B0); G8_BAR; G8_SCHED;
;       G8_LDB(B1, 1, 1); G8_STAGE(G8_SB(1, 0), b3);
;       G8_BAR; G8_WAIT_L(0); G8_MMA(0, 1, At, B1); G8_BAR;
;       G8_LDA(At, 1, 1); G8_STAGE(G8_SA(1, 0), a3);
	s_add_u32 s56, s26, 0x20000
	s_addc_u32 s57, s27, 0
	s_mov_b32 m0, s41
	v_lshl_add_u64 v[34:35], s[56:57], 0, v[0:1]
	global_load_lds_dwordx4 v[34:35], off
	v_lshl_add_u64 v[34:35], s[56:57], 0, v[152:153]
	s_mov_b32 m0, s42
	s_nop 0
	global_load_lds_dwordx4 v[34:35], off
	s_waitcnt vmcnt(6)
	s_barrier
	s_setprio 1
	v_mfma_f32_16x16x32_f16 v[38:41], v[214:217], v[178:181], v[38:41]
	v_mfma_f32_16x16x32_f16 v[42:45], v[222:225], v[178:181], v[42:45]
	v_mfma_f32_16x16x32_f16 v[18:21], v[214:217], v[186:189], v[18:21]
	v_mfma_f32_16x16x32_f16 v[22:25], v[222:225], v[186:189], v[22:25]
	v_mfma_f32_16x16x32_f16 v[2:5], v[214:217], v[206:209], v[2:5]
	v_mfma_f32_16x16x32_f16 v[6:9], v[222:225], v[206:209], v[6:9]
	v_mfma_f32_16x16x32_f16 v[34:37], v[214:217], v[164:167], v[66:69]
	v_mfma_f32_16x16x32_f16 v[46:49], v[222:225], v[164:167], v[70:73]
	v_mfma_f32_16x16x32_f16 v[38:41], v[218:221], v[182:185], v[38:41]
	v_mfma_f32_16x16x32_f16 v[42:45], v[226:229], v[182:185], v[42:45]
	v_mfma_f32_16x16x32_f16 v[18:21], v[218:221], v[202:205], v[18:21]
	v_mfma_f32_16x16x32_f16 v[22:25], v[226:229], v[202:205], v[22:25]
	v_mfma_f32_16x16x32_f16 v[2:5], v[218:221], v[210:213], v[2:5]
	v_mfma_f32_16x16x32_f16 v[6:9], v[226:229], v[210:213], v[6:9]
	v_mfma_f32_16x16x32_f16 v[34:37], v[218:221], v[174:177], v[34:37]
	v_mfma_f32_16x16x32_f16 v[46:49], v[226:229], v[174:177], v[46:49]
	s_setprio 0
	v_or_b32_e32 v50, 0x18000, v171
	v_add_u32_e32 v66, 0x18400, v171
	v_add_u32_e32 v70, 0x18800, v171
	v_add_u32_e32 v160, 0x18c00, v171
	s_barrier
	ds_read_b128 v[50:53], v50
	ds_read_b128 v[66:69], v66
	ds_read_b128 v[70:73], v70
	ds_read_b128 v[160:163], v160
	s_add_u32 s28, s28, 0x20000
	s_addc_u32 s29, s29, 0
	s_mov_b32 m0, s43
	v_lshl_add_u64 v[214:215], s[28:29], 0, v[0:1]
	ds_read_b128 v[164:167], v170 offset:32768
	ds_read_b128 v[174:177], v170 offset:33792
	ds_read_b128 v[178:181], v170 offset:34816
	ds_read_b128 v[182:185], v170 offset:35840
	ds_read_b128 v[186:189], v170 offset:36864
	ds_read_b128 v[202:205], v170 offset:37888
	ds_read_b128 v[206:209], v170 offset:38912
	ds_read_b128 v[210:213], v170 offset:39936
	global_load_lds_dwordx4 v[214:215], off
	v_lshl_add_u64 v[214:215], s[28:29], 0, v[152:153]
	s_mov_b32 m0, s44
	s_nop 0
	global_load_lds_dwordx4 v[214:215], off
	s_waitcnt lgkmcnt(8)
	s_barrier
	s_waitcnt lgkmcnt(0)
	s_setprio 1
	s_waitcnt lgkmcnt(0)
	v_mfma_f32_16x16x32_f16 v[62:65], v[50:53], v[164:167], v[62:65]
	v_mfma_f32_16x16x32_f16 v[138:141], v[70:73], v[164:167], v[138:141]
	v_mfma_f32_16x16x32_f16 v[122:125], v[50:53], v[178:181], v[122:125]
	v_mfma_f32_16x16x32_f16 v[126:129], v[70:73], v[178:181], v[126:129]
	v_mfma_f32_16x16x32_f16 v[106:109], v[50:53], v[186:189], v[106:109]
	v_mfma_f32_16x16x32_f16 v[110:113], v[70:73], v[186:189], v[110:113]
	v_mfma_f32_16x16x32_f16 v[90:93], v[50:53], v[206:209], v[90:93]
	v_mfma_f32_16x16x32_f16 v[94:97], v[70:73], v[206:209], v[94:97]
	v_mfma_f32_16x16x32_f16 v[62:65], v[66:69], v[174:177], v[62:65]
	v_mfma_f32_16x16x32_f16 v[138:141], v[160:163], v[174:177], v[138:141]
	v_mfma_f32_16x16x32_f16 v[122:125], v[66:69], v[182:185], v[122:125]
	v_mfma_f32_16x16x32_f16 v[126:129], v[160:163], v[182:185], v[126:129]
	v_mfma_f32_16x16x32_f16 v[106:109], v[66:69], v[202:205], v[106:109]
	v_mfma_f32_16x16x32_f16 v[110:113], v[160:163], v[202:205], v[110:113]
	v_mfma_f32_16x16x32_f16 v[90:93], v[66:69], v[210:213], v[90:93]
	v_mfma_f32_16x16x32_f16 v[94:97], v[160:163], v[210:213], v[94:97]
	s_setprio 0
	s_barrier
	v_or_b32_e32 v173, 0x1c000, v171
	s_mov_b32 m0, s46
	v_add_u32_e32 v195, 0x1c400, v171
	ds_read_b128 v[214:217], v173
	ds_read_b128 v[218:221], v195
	v_add_u32_e32 v173, 0x1c800, v171
	v_lshl_add_u64 v[168:169], v[168:169], 0, s[94:95]
	v_add_u32_e32 v195, 0x1cc00, v171
	ds_read_b128 v[222:225], v173
	ds_read_b128 v[226:229], v195
	global_load_lds_dwordx4 v[168:169], off
	v_lshl_add_u64 v[168:169], v[230:231], 0, s[94:95]
	s_mov_b32 m0, s47
	s_nop 0
	global_load_lds_dwordx4 v[168:169], off
	s_barrier
	s_waitcnt lgkmcnt(0)
	s_setprio 1
	s_waitcnt lgkmcnt(0)
	v_mfma_f32_16x16x32_f16 v[130:133], v[214:217], v[164:167], v[130:133]
	v_mfma_f32_16x16x32_f16 v[134:137], v[222:225], v[164:167], v[134:137]
	v_mfma_f32_16x16x32_f16 v[114:117], v[214:217], v[178:181], v[114:117]
	v_mfma_f32_16x16x32_f16 v[118:121], v[222:225], v[178:181], v[118:121]
	v_mfma_f32_16x16x32_f16 v[98:101], v[214:217], v[186:189], v[98:101]
	v_mfma_f32_16x16x32_f16 v[102:105], v[222:225], v[186:189], v[102:105]
	v_mfma_f32_16x16x32_f16 v[82:85], v[214:217], v[206:209], v[82:85]
	v_mfma_f32_16x16x32_f16 v[86:89], v[222:225], v[206:209], v[86:89]
	v_mfma_f32_16x16x32_f16 v[130:133], v[218:221], v[174:177], v[130:133]
	v_mfma_f32_16x16x32_f16 v[134:137], v[226:229], v[174:177], v[134:137]
	v_mfma_f32_16x16x32_f16 v[114:117], v[218:221], v[182:185], v[114:117]
	v_mfma_f32_16x16x32_f16 v[118:121], v[226:229], v[182:185], v[118:121]
	v_mfma_f32_16x16x32_f16 v[98:101], v[218:221], v[202:205], v[98:101]
	v_mfma_f32_16x16x32_f16 v[102:105], v[226:229], v[202:205], v[102:105]
	v_mfma_f32_16x16x32_f16 v[82:85], v[218:221], v[210:213], v[82:85]
	v_mfma_f32_16x16x32_f16 v[86:89], v[226:229], v[210:213], v[86:89]
	s_setprio 0
	s_mov_b32 m0, s48
	v_lshl_add_u64 v[168:169], v[232:233], 0, s[94:95]
	s_barrier
	ds_read_b128 v[164:167], v170 offset:49152
	ds_read_b128 v[174:177], v170 offset:50176
	ds_read_b128 v[178:181], v170 offset:51200
	ds_read_b128 v[182:185], v170 offset:52224
	ds_read_b128 v[186:189], v170 offset:53248
	ds_read_b128 v[202:205], v170 offset:54272
	ds_read_b128 v[206:209], v170 offset:55296
	ds_read_b128 v[210:213], v170 offset:56320
	global_load_lds_dwordx4 v[168:169], off
	v_lshl_add_u64 v[168:169], v[234:235], 0, s[94:95]
	s_mov_b32 m0, s49
	s_nop 0
	global_load_lds_dwordx4 v[168:169], off
	s_barrier
; #define G8_STAGE(bufoff, gbase) do { _Pragma("unroll") for (int _i = 0; _i < 2; ++_i) \
;     __builtin_amdgcn_global_load_lds((const unsigned*)((const char*)(gbase) + voffA[_i]), (LAS unsigned*)(lds + (bufoff) + ldsw + _i * 8192), 16, 0, 0); } while (0)
; #define G8_MMA(ai, bj, At, Bt_) do { __builtin_amdgcn_s_setprio(1); _Pragma("unroll") for (int m = 0; m < 4; ++m) _Pragma("unroll") for (int n = 0; n < 2; ++n) _Pragma("unroll") for (int k = 0; k < 2; ++k) \
;     acc[ai][bj][m][n] = __builtin_amdgcn_mfma_f32_16x16x32_f16(Bt_[n][k], At[m][k], acc[ai][bj][m][n], 0, 0, 0); __builtin_amdgcn_s_setprio(0); } while (0)
; #define G8_WAIT_V(n) asm volatile("s_waitcnt vmcnt(" #n ")" ::: "memory")
; #define G8_WAIT_L(n) asm volatile("s_waitcnt lgkmcnt(" #n ")" ::: "memory")
; #define G8_BAR __builtin_amdgcn_s_barrier()
; #define G8_SCHED __builtin_amdgcn_sched_barrier(0)
; template <class Epi>
; __device__ __forceinline__ void gemm_phase(LAS unsigned char* lds, const h16* A, const h16* Bt, int K, const Order& S, const Epi& E) {
;     ...
;       G8_BAR; G8_WAIT_L(0); G8_MMA(1, 0, At, B0); G8_BAR; G8_SCHED;
;       G8_STAGE(G8_SB(1, 1), b3 + hstep);
;       G8_WAIT_V(6); G8_BAR; G8_MMA(1, 1, At, B1); G8_BAR;
;     }
	s_waitcnt lgkmcnt(0)
	s_setprio 1
	s_waitcnt lgkmcnt(0)
	v_mfma_f32_16x16x32_f16 v[74:77], v[50:53], v[164:167], v[74:77]
	v_mfma_f32_16x16x32_f16 v[78:81], v[70:73], v[164:167], v[78:81]
	v_mfma_f32_16x16x32_f16 v[54:57], v[50:53], v[178:181], v[54:57]
	v_mfma_f32_16x16x32_f16 v[58:61], v[70:73], v[178:181], v[58:61]
	v_mfma_f32_16x16x32_f16 v[26:29], v[50:53], v[186:189], v[26:29]
	v_mfma_f32_16x16x32_f16 v[30:33], v[70:73], v[186:189], v[30:33]
	v_mfma_f32_16x16x32_f16 v[10:13], v[50:53], v[206:209], v[10:13]
	v_mfma_f32_16x16x32_f16 v[14:17], v[70:73], v[206:209], v[14:17]
	v_mfma_f32_16x16x32_f16 v[74:77], v[66:69], v[174:177], v[74:77]
	v_mfma_f32_16x16x32_f16 v[78:81], v[160:163], v[174:177], v[78:81]
	v_mfma_f32_16x16x32_f16 v[54:57], v[66:69], v[182:185], v[54:57]
	v_mfma_f32_16x16x32_f16 v[58:61], v[160:163], v[182:185], v[58:61]
	v_mfma_f32_16x16x32_f16 v[26:29], v[66:69], v[202:205], v[26:29]
	v_mfma_f32_16x16x32_f16 v[30:33], v[160:163], v[202:205], v[30:33]
	v_mfma_f32_16x16x32_f16 v[10:13], v[66:69], v[210:213], v[10:13]
	v_mfma_f32_16x16x32_f16 v[14:17], v[160:163], v[210:213], v[14:17]
	s_setprio 0
	s_barrier
	s_add_u32 s26, s26, 0x20080
	s_addc_u32 s27, s27, 0
	s_mov_b32 m0, s50
	v_lshl_add_u64 v[50:51], s[26:27], 0, v[0:1]
	global_load_lds_dwordx4 v[50:51], off
	v_lshl_add_u64 v[50:51], s[26:27], 0, v[152:153]
	s_mov_b32 m0, s51
	s_nop 0
	global_load_lds_dwordx4 v[50:51], off
	s_waitcnt vmcnt(6)
	s_barrier
	s_setprio 1
	v_mfma_f32_16x16x32_f16 v[34:37], v[214:217], v[164:167], v[34:37]
	v_mfma_f32_16x16x32_f16 v[66:69], v[218:221], v[174:177], v[34:37]
	v_mfma_f32_16x16x32_f16 v[34:37], v[222:225], v[164:167], v[46:49]
	v_mfma_f32_16x16x32_f16 v[70:73], v[226:229], v[174:177], v[34:37]
	v_mfma_f32_16x16x32_f16 v[34:37], v[214:217], v[178:181], v[38:41]
	v_mfma_f32_16x16x32_f16 v[38:41], v[218:221], v[182:185], v[34:37]
	v_mfma_f32_16x16x32_f16 v[34:37], v[222:225], v[178:181], v[42:45]
	v_mfma_f32_16x16x32_f16 v[18:21], v[214:217], v[186:189], v[18:21]
	v_mfma_f32_16x16x32_f16 v[22:25], v[222:225], v[186:189], v[22:25]
	v_mfma_f32_16x16x32_f16 v[2:5], v[214:217], v[206:209], v[2:5]
	v_mfma_f32_16x16x32_f16 v[6:9], v[222:225], v[206:209], v[6:9]
	v_mfma_f32_16x16x32_f16 v[42:45], v[226:229], v[182:185], v[34:37]
	v_mfma_f32_16x16x32_f16 v[18:21], v[218:221], v[202:205], v[18:21]
	v_mfma_f32_16x16x32_f16 v[22:25], v[226:229], v[202:205], v[22:25]
	v_mfma_f32_16x16x32_f16 v[2:5], v[218:221], v[210:213], v[2:5]
	v_mfma_f32_16x16x32_f16 v[6:9], v[226:229], v[210:213], v[6:9]
	s_setprio 0
	s_add_i32 s55, s55, 2
	s_add_u32 s24, s24, 0x100
	s_addc_u32 s25, s25, 0
	s_add_u32 s53, s53, 0x100
	s_addc_u32 s54, s54, 0
	s_cmp_gt_u32 s55, 5
	s_barrier
	s_cbranch_scc0 .LBB0_2284
; __device__ __forceinline__ float xor16(float v) { return __int_as_float(__builtin_amdgcn_ds_swizzle(__float_as_int(v), 0x401F)); }
; __device__ __forceinline__ float sigmoidf(float x) { return 1.f / (1.f + __expf(-x)); }
;   __device__ __forceinline__ void operator()(const f32x4 (&acc)[2][2][4][2], const g8::Unit& u, int ui, int wr, int wc, int fr, int fq) const {
;     const int ocb = 128 * u.pn + 16 * wc + 4 * fq;
;     float4 ba[2], bb[2];
; #pragma unroll
;     for (int bj = 0; bj < 2; ++bj) { ba[bj] = *(const float4*)(gb + ocb + 64 * bj); bb[bj] = *(const float4*)(gb + 512 + ocb + 64 * bj); }
; #pragma unroll
;     for (int ai = 0; ai < 2; ++ai)
; #pragma unroll
;       for (int m = 0; m < 4; ++m) {
;         const size_t row = (size_t)u.pm * 256 + 128 * ai + 64 * wr + 16 * m + fr;
;         float ss = 0.f;
; #pragma unroll
;         for (int bj = 0; bj < 2; ++bj) {
;           const f32x4 a = acc[ai][bj][m][0], b = acc[ai][bj][m][1];
;           float o0 = (a[0] + ba[bj].x) * sigmoidf(b[0] + bb[bj].x);
;           float o1 = (a[1] + ba[bj].y) * sigmoidf(b[1] + bb[bj].y);
;           float o2 = (a[2] + ba[bj].z) * sigmoidf(b[2] + bb[bj].z);
;           float o3 = (a[3] + ba[bj].w) * sigmoidf(b[3] + bb[bj].w);
;           *(h16x4*)(OB + row * 1024 + ocb + 64 * bj) = pack4(o0, o1, o2, o3);
;           ss += o0 * o0 + o1 * o1 + o2 * o2 + o3 * o3;
;         }
;         ss += xor16(ss);
;         ss += __shfl_xor(ss, 32);
;         if (fq == 0) ssqb[row * 16 + u.pn * 4 + wc] = ss;
	v_lshl_or_b32 v160, s2, 7, v172
	v_ashrrev_i32_e32 v161, 31, v160
	v_lshl_add_u64 v[166:167], v[160:161], 2, s[12:13]
	global_load_dwordx4 v[46:49], v[166:167], off offset:2048
	global_load_dwordx4 v[34:37], v[166:167], off offset:2304
	v_and_b32_e32 v51, 64, v199
	v_xor_b32_e32 v50, 32, v199
	v_add_u32_e32 v51, 64, v51
	v_cmp_lt_i32_e32 vcc, v50, v51
	s_ashr_i32 s23, s22, 31
	s_lshl_b64 s[22:23], s[22:23], 8
	v_cndmask_b32_e32 v50, v199, v50, vcc
	v_lshlrev_b32_e32 v173, 2, v50
	v_lshl_add_u64 v[162:163], s[22:23], 0, v[154:155]
	s_lshl_b32 s22, s2, 2
	v_lshlrev_b64 v[164:165], 11, v[162:163]
	s_ashr_i32 s23, s22, 31
	s_waitcnt vmcnt(0)
	v_add_f32_e32 v50, v138, v46
	v_mul_f32_e32 v50, 0xbfb8aa3b, v50
	v_exp_f32_e32 v138, v50
	global_load_dwordx4 v[50:53], v[166:167], off
	v_add_f32_e32 v139, v139, v47
	v_mul_f32_e32 v139, 0xbfb8aa3b, v139
	v_exp_f32_e32 v139, v139
	v_add_f32_e32 v140, v140, v48
	v_add_f32_e32 v141, v141, v49
	v_mul_f32_e32 v140, 0xbfb8aa3b, v140
	v_pk_add_f32 v[138:139], v[138:139], 1.0 op_sel_hi:[1,0]
	v_mul_f32_e32 v141, 0xbfb8aa3b, v141
	v_div_scale_f32 v168, s[2:3], v139, v139, 1.0
	v_rcp_f32_e32 v169, v168
	v_exp_f32_e32 v140, v140
	v_exp_f32_e32 v141, v141
	v_add_f32_e32 v135, v135, v35
	v_fma_f32 v174, -v168, v169, 1.0
	v_fmac_f32_e32 v169, v174, v169
	v_div_scale_f32 v174, vcc, 1.0, v139, 1.0
	v_mul_f32_e32 v175, v174, v169
	v_fma_f32 v176, -v168, v175, v174
	v_fmac_f32_e32 v175, v176, v169
	v_fma_f32 v168, -v168, v175, v174
	v_div_fmas_f32 v168, v168, v169, v175
	v_div_fixup_f32 v139, v168, v139, 1.0
	v_div_scale_f32 v168, s[2:3], v138, v138, 1.0
	v_rcp_f32_e32 v169, v168
	v_mul_f32_e32 v135, 0xbfb8aa3b, v135
	v_exp_f32_e32 v135, v135
	v_add_f32_e32 v136, v136, v36
	v_fma_f32 v174, -v168, v169, 1.0
	v_fmac_f32_e32 v169, v174, v169
	v_div_scale_f32 v174, vcc, 1.0, v138, 1.0
	v_mul_f32_e32 v175, v174, v169
	v_fma_f32 v176, -v168, v175, v174
	v_fmac_f32_e32 v175, v176, v169
	v_fma_f32 v168, -v168, v175, v174
	v_div_fmas_f32 v168, v168, v169, v175
	v_div_fixup_f32 v138, v168, v138, 1.0
	v_add_f32_e32 v137, v137, v37
	v_mul_f32_e32 v136, 0xbfb8aa3b, v136
	v_mul_f32_e32 v137, 0xbfb8aa3b, v137
	v_exp_f32_e32 v136, v136
	v_exp_f32_e32 v137, v137
	s_waitcnt vmcnt(0)
	v_pk_add_f32 v[62:63], v[62:63], v[50:51]
	s_nop 0
	v_pk_mul_f32 v[62:63], v[62:63], v[138:139]
	v_pk_add_f32 v[138:139], v[140:141], 1.0 op_sel_hi:[1,0]
	v_cvt_pk_f16_f32 v168, v62, v63
	v_div_scale_f32 v140, s[2:3], v139, v139, 1.0
	v_rcp_f32_e32 v141, v140
	v_pk_add_f32 v[64:65], v[64:65], v[52:53]
	v_pk_add_f32 v[136:137], v[136:137], 1.0 op_sel_hi:[1,0]
	v_fma_f32 v169, -v140, v141, 1.0
	v_fmac_f32_e32 v141, v169, v141
	v_div_scale_f32 v169, vcc, 1.0, v139, 1.0
	v_mul_f32_e32 v174, v169, v141
	v_fma_f32 v175, -v140, v174, v169
	v_fmac_f32_e32 v174, v175, v141
	v_fma_f32 v140, -v140, v174, v169
	v_div_fmas_f32 v140, v140, v141, v174
	v_div_fixup_f32 v139, v140, v139, 1.0
	v_div_scale_f32 v140, s[2:3], v138, v138, 1.0
	v_rcp_f32_e32 v141, v140
	s_nop 0
	v_fma_f32 v169, -v140, v141, 1.0
	v_fmac_f32_e32 v141, v169, v141
	v_div_scale_f32 v169, vcc, 1.0, v138, 1.0
	v_mul_f32_e32 v174, v169, v141
	v_fma_f32 v175, -v140, v174, v169
	v_fmac_f32_e32 v174, v175, v141
	v_fma_f32 v140, -v140, v174, v169
	v_div_fmas_f32 v140, v140, v141, v174
	v_div_fixup_f32 v138, v140, v138, 1.0
	v_pk_mul_f32 v[140:141], v[62:63], v[62:63]
	v_add_f32_e32 v62, v134, v34
	v_pk_mul_f32 v[64:65], v[64:65], v[138:139]
	v_lshl_add_u64 v[138:139], s[0:1], 0, v[164:165]
	v_mul_f32_e32 v62, 0xbfb8aa3b, v62
	v_cvt_pk_f16_f32 v169, v64, v65
	v_lshl_add_u64 v[164:165], v[160:161], 1, v[138:139]
	v_pk_mul_f32 v[138:139], v[64:65], v[64:65]
	v_exp_f32_e32 v134, v62
	global_load_dwordx4 v[62:65], v[166:167], off offset:256
	v_pk_add_f32 v[134:135], v[134:135], 1.0 op_sel_hi:[1,0]
	s_nop 0
	v_div_scale_f32 v166, s[2:3], v135, v135, 1.0
	v_rcp_f32_e32 v167, v166
	global_store_dwordx2 v[164:165], v[168:169], off
	v_fma_f32 v168, -v166, v167, 1.0
	v_fmac_f32_e32 v167, v168, v167
	v_div_scale_f32 v168, vcc, 1.0, v135, 1.0
	v_mul_f32_e32 v169, v168, v167
	v_fma_f32 v174, -v166, v169, v168
	v_fmac_f32_e32 v169, v174, v167
	v_fma_f32 v166, -v166, v169, v168
	v_div_fmas_f32 v166, v166, v167, v169
	v_div_fixup_f32 v135, v166, v135, 1.0
	v_div_scale_f32 v166, s[2:3], v134, v134, 1.0
	v_rcp_f32_e32 v167, v166
	s_waitcnt vmcnt(0)
	v_pk_add_f32 v[130:131], v[130:131], v[62:63]
	v_fma_f32 v168, -v166, v167, 1.0
	v_fmac_f32_e32 v167, v168, v167
	v_div_scale_f32 v168, vcc, 1.0, v134, 1.0
	v_mul_f32_e32 v169, v168, v167
	v_fma_f32 v174, -v166, v169, v168
	v_fmac_f32_e32 v169, v174, v167
	v_fma_f32 v166, -v166, v169, v168
	v_div_fmas_f32 v166, v166, v167, v169
	v_div_fixup_f32 v134, v166, v134, 1.0
	v_pk_mul_f32 v[130:131], v[130:131], v[134:135]
	v_div_scale_f32 v135, s[2:3], v137, v137, 1.0
	v_rcp_f32_e32 v166, v135
	v_pk_add_f32 v[132:133], v[132:133], v[64:65]
	v_cvt_pk_f16_f32 v134, v130, v131
	v_pk_mul_f32 v[130:131], v[130:131], v[130:131]
	v_fma_f32 v167, -v135, v166, 1.0
	v_fmac_f32_e32 v166, v167, v166
	v_div_scale_f32 v167, vcc, 1.0, v137, 1.0
	v_mul_f32_e32 v168, v167, v166
	v_fma_f32 v169, -v135, v168, v167
	v_fmac_f32_e32 v168, v169, v166
	v_fma_f32 v135, -v135, v168, v167
	v_div_fmas_f32 v135, v135, v166, v168
	v_div_fixup_f32 v137, v135, v137, 1.0
	v_div_scale_f32 v135, s[2:3], v136, v136, 1.0
	v_rcp_f32_e32 v166, v135
	v_add_f32_e32 v130, v130, v131
	v_add_f32_e32 v131, v140, v141
	v_add_f32_e32 v131, v138, v131
	v_fma_f32 v167, -v135, v166, 1.0
	v_fmac_f32_e32 v166, v167, v166
	v_div_scale_f32 v167, vcc, 1.0, v136, 1.0
	v_mul_f32_e32 v168, v167, v166
	v_fma_f32 v169, -v135, v168, v167
	v_fmac_f32_e32 v168, v169, v166
	v_fma_f32 v135, -v135, v168, v167
	v_div_fmas_f32 v135, v135, v166, v168
	v_div_fixup_f32 v136, v135, v136, 1.0
	v_pk_mul_f32 v[132:133], v[132:133], v[136:137]
	v_add_f32_e32 v131, v139, v131
	v_cvt_pk_f16_f32 v135, v132, v133
	v_pk_mul_f32 v[132:133], v[132:133], v[132:133]
	global_store_dwordx2 v[164:165], v[134:135], off offset:128
	v_add_f32_e32 v130, v132, v130
	v_add_f32_e32 v130, v133, v130
	v_add_f32_e32 v130, v131, v130
	ds_swizzle_b32 v131, v130 offset:swizzle(SWAP,16)
	s_waitcnt lgkmcnt(0)
	v_add_f32_e32 v130, v130, v131
	ds_bpermute_b32 v131, v173, v130
	s_and_saveexec_b64 s[24:25], s[6:7]
	s_cbranch_execz .LBB0_2287
	s_waitcnt lgkmcnt(0)
	v_add_f32_e32 v132, v130, v131
	v_lshlrev_b64 v[130:131], 6, v[162:163]
	v_lshl_add_u64 v[130:131], s[10:11], 0, v[130:131]
	v_lshl_add_u64 v[130:131], s[22:23], 2, v[130:131]
	s_lshl_b32 s92, s45, 2
	v_lshl_add_u64 v[130:131], v[130:131], 0, s[92:93]
	global_store_dword v[130:131], v132, off

; #define G8_STAGE(bufoff, gbase) do { _Pragma("unroll") for (int _i = 0; _i < 2; ++_i) \
;     __builtin_amdgcn_global_load_lds((const unsigned*)((const char*)(gbase) + voffA[_i]), (LAS unsigned*)(lds + (bufoff) + ldsw + _i * 8192), 16, 0, 0); } while (0)
; #define G8_LDA(dst, b, h) do { _Pragma("unroll") for (int m = 0; m < 4; ++m) _Pragma("unroll") for (int k = 0; k < 2; ++k) dst[m][k] = *(const LAS h16x8*)(lds + G8_SA(b, h) + aoff + m * 2048 + k * 1024); } while (0)
; #define G8_LDB(dst, b, h) do { _Pragma("unroll") for (int n = 0; n < 2; ++n) _Pragma("unroll") for (int k = 0; k < 2; ++k) dst[n][k] = *(const LAS h16x8*)(lds + G8_SB(b, h) + boff + n * 2048 + k * 1024); } while (0)
; #define G8_MMA(ai, bj, At, Bt_) do { __builtin_amdgcn_s_setprio(1); _Pragma("unroll") for (int m = 0; m < 4; ++m) _Pragma("unroll") for (int n = 0; n < 2; ++n) _Pragma("unroll") for (int k = 0; k < 2; ++k) \
;     acc[ai][bj][m][n] = __builtin_amdgcn_mfma_f32_16x16x32_f16(Bt_[n][k], At[m][k], acc[ai][bj][m][n], 0, 0, 0); __builtin_amdgcn_s_setprio(0); } while (0)
; #define G8_WAIT_L(n) asm volatile("s_waitcnt lgkmcnt(" #n ")" ::: "memory")
; #define G8_BAR __builtin_amdgcn_s_barrier()
; #define G8_SCHED __builtin_amdgcn_sched_barrier(0)
; template <class Epi>
; __device__ __forceinline__ void gemm_phase(LAS unsigned char* lds, const h16* A, const h16* Bt, int K, const Order& S, const Epi& E) {
;     ...
;       const char* a1 = cA + (size_t)(t + 1) * kstep;
;       const char* a2 = last ? nA : cA + (size_t)(t + 2) * kstep;
;       const char* b2 = last ? nB : cB + (size_t)(t + 2) * kstep;
;       const char* a3 = a2 + kstep;
;       const char* b3 = b2 + kstep;
;       if (Epi::MID_T >= 0 && t == Epi::MID_T) E.mid(acc, ui, wr, fr);
;       G8_LDB(B0, 0, 0); G8_SCHED; G8_LDA(At, 0, 0); G8_STAGE(G8_SA(1, 1), a1 + hstep);
;       G8_WAIT_L(8); G8_BAR; G8_WAIT_L(0); G8_MMA(0, 0, At, B0); G8_BAR; G8_SCHED;
;       G8_LDB(B1, 0, 1); G8_STAGE(G8_SB(0, 0), b2);
;       G8_BAR; G8_WAIT_L(0); G8_MMA(0, 1, At, B1); G8_BAR;
;       G8_LDA(At, 0, 1); G8_STAGE(G8_SA(0, 0), a2);
;       G8_BAR; G8_WAIT_L(0); G8_MMA(1, 0, At, B0); G8_BAR; G8_SCHED;
.LBB0_2378:
	s_add_u32 s26, s20, s24
	v_or_b32_e32 v0, 0x10000, v158
	s_addc_u32 s27, s21, s25
	v_add_u32_e32 v2, 0x10400, v158
	ds_read_b128 v[162:165], v0
	ds_read_b128 v[166:169], v2
	v_add_u32_e32 v0, 0x10800, v158
	s_add_u32 s26, s26, 0x100
	v_add_u32_e32 v2, 0x10c00, v158
	ds_read_b128 v[170:173], v0
	ds_read_b128 v[174:177], v2
	s_addc_u32 s27, s27, 0
	s_add_u32 s56, s53, s24
	s_addc_u32 s57, s54, s25
	s_cmpk_eq_i32 s24, 0x700
	s_cselect_b32 s29, s3, s27
	s_cselect_b32 s28, s15, s26
	s_cselect_b32 s27, s13, s57
	s_cselect_b32 s26, s23, s56
	v_lshl_add_u64 v[2:3], v[154:155], 0, s[24:25]
	s_add_i32 m0, s37, 0xc000
	ds_read_b128 v[178:181], v139
	ds_read_b128 v[182:185], v139 offset:1024
	ds_read_b128 v[186:189], v139 offset:2048
	ds_read_b128 v[202:205], v139 offset:3072
	ds_read_b128 v[206:209], v139 offset:4096
	ds_read_b128 v[210:213], v139 offset:5120
	ds_read_b128 v[214:217], v139 offset:6144
	ds_read_b128 v[218:221], v139 offset:7168
	global_load_lds_dwordx4 v[2:3], off
	v_lshl_add_u64 v[2:3], v[156:157], 0, s[24:25]
	s_add_i32 m0, s37, 0xe000
	s_nop 0
	global_load_lds_dwordx4 v[2:3], off
	s_waitcnt lgkmcnt(8)
	s_barrier
	s_waitcnt lgkmcnt(0)
	s_setprio 1
	s_waitcnt lgkmcnt(0)
	v_mfma_f32_16x16x32_f16 v[128:131], v[162:165], v[178:181], v[128:131]
	v_mfma_f32_16x16x32_f16 v[124:127], v[170:173], v[178:181], v[124:127]
	v_mfma_f32_16x16x32_f16 v[112:115], v[162:165], v[186:189], v[112:115]
	v_mfma_f32_16x16x32_f16 v[108:111], v[170:173], v[186:189], v[108:111]
	v_mfma_f32_16x16x32_f16 v[96:99], v[162:165], v[206:209], v[96:99]
	v_mfma_f32_16x16x32_f16 v[92:95], v[170:173], v[206:209], v[92:95]
	v_mfma_f32_16x16x32_f16 v[80:83], v[162:165], v[214:217], v[80:83]
	v_mfma_f32_16x16x32_f16 v[76:79], v[170:173], v[214:217], v[76:79]
	v_mfma_f32_16x16x32_f16 v[128:131], v[166:169], v[182:185], v[128:131]
	v_mfma_f32_16x16x32_f16 v[124:127], v[174:177], v[182:185], v[124:127]
	v_mfma_f32_16x16x32_f16 v[112:115], v[166:169], v[202:205], v[112:115]
	v_mfma_f32_16x16x32_f16 v[108:111], v[174:177], v[202:205], v[108:111]
	v_mfma_f32_16x16x32_f16 v[96:99], v[166:169], v[210:213], v[96:99]
	v_mfma_f32_16x16x32_f16 v[92:95], v[174:177], v[210:213], v[92:95]
	v_mfma_f32_16x16x32_f16 v[80:83], v[166:169], v[218:221], v[80:83]
	v_mfma_f32_16x16x32_f16 v[76:79], v[174:177], v[218:221], v[76:79]
	s_setprio 0
	s_barrier
	v_or_b32_e32 v0, 0x14000, v158
	s_mov_b32 m0, s38
	v_add_u32_e32 v2, 0x14400, v158
	ds_read_b128 v[222:225], v0
	ds_read_b128 v[226:229], v2
	v_add_u32_e32 v0, 0x14800, v158
	v_lshl_add_u64 v[238:239], s[26:27], 0, v[134:135]
	v_add_u32_e32 v2, 0x14c00, v158
	ds_read_b128 v[230:233], v0
	ds_read_b128 v[234:237], v2
	global_load_lds_dwordx4 v[238:239], off
	v_lshl_add_u64 v[240:241], s[26:27], 0, v[132:133]
	s_mov_b32 m0, s39
	s_nop 0
	global_load_lds_dwordx4 v[240:241], off
	s_barrier
	s_waitcnt lgkmcnt(0)
	s_setprio 1
	s_waitcnt lgkmcnt(0)
	v_mfma_f32_16x16x32_f16 v[120:123], v[222:225], v[178:181], v[120:123]
	v_mfma_f32_16x16x32_f16 v[116:119], v[230:233], v[178:181], v[116:119]
	v_mfma_f32_16x16x32_f16 v[104:107], v[222:225], v[186:189], v[104:107]
	v_mfma_f32_16x16x32_f16 v[100:103], v[230:233], v[186:189], v[100:103]
	v_mfma_f32_16x16x32_f16 v[88:91], v[222:225], v[206:209], v[88:91]
	v_mfma_f32_16x16x32_f16 v[84:87], v[230:233], v[206:209], v[84:87]
	v_mfma_f32_16x16x32_f16 v[72:75], v[222:225], v[214:217], v[72:75]
	v_mfma_f32_16x16x32_f16 v[68:71], v[230:233], v[214:217], v[68:71]
	v_mfma_f32_16x16x32_f16 v[120:123], v[226:229], v[182:185], v[120:123]
	v_mfma_f32_16x16x32_f16 v[116:119], v[234:237], v[182:185], v[116:119]
	v_mfma_f32_16x16x32_f16 v[104:107], v[226:229], v[202:205], v[104:107]
	v_mfma_f32_16x16x32_f16 v[100:103], v[234:237], v[202:205], v[100:103]
	v_mfma_f32_16x16x32_f16 v[88:91], v[226:229], v[210:213], v[88:91]
	v_mfma_f32_16x16x32_f16 v[84:87], v[234:237], v[210:213], v[84:87]
	v_mfma_f32_16x16x32_f16 v[72:75], v[226:229], v[218:221], v[72:75]
	v_mfma_f32_16x16x32_f16 v[68:71], v[234:237], v[218:221], v[68:71]
	s_setprio 0
	s_mov_b32 m0, s37
	v_lshl_add_u64 v[242:243], s[28:29], 0, v[134:135]
	s_barrier
	ds_read_b128 v[178:181], v139 offset:16384
	ds_read_b128 v[182:185], v139 offset:17408
	ds_read_b128 v[186:189], v139 offset:18432
	ds_read_b128 v[202:205], v139 offset:19456
	ds_read_b128 v[206:209], v139 offset:20480
	ds_read_b128 v[210:213], v139 offset:21504
	ds_read_b128 v[214:217], v139 offset:22528
	ds_read_b128 v[218:221], v139 offset:23552
	global_load_lds_dwordx4 v[242:243], off
	v_lshl_add_u64 v[244:245], s[28:29], 0, v[132:133]
	s_mov_b32 m0, s40
	s_nop 0
	global_load_lds_dwordx4 v[244:245], off
	s_barrier
	s_waitcnt lgkmcnt(0)
	s_setprio 1
	s_waitcnt lgkmcnt(0)
	v_mfma_f32_16x16x32_f16 v[64:67], v[162:165], v[178:181], v[64:67]
	v_mfma_f32_16x16x32_f16 v[60:63], v[170:173], v[178:181], v[60:63]
	v_mfma_f32_16x16x32_f16 v[48:51], v[162:165], v[186:189], v[48:51]
	v_mfma_f32_16x16x32_f16 v[44:47], v[170:173], v[186:189], v[44:47]
	v_mfma_f32_16x16x32_f16 v[32:35], v[162:165], v[206:209], v[32:35]
	v_mfma_f32_16x16x32_f16 v[28:31], v[170:173], v[206:209], v[28:31]
	v_mfma_f32_16x16x32_f16 v[16:19], v[162:165], v[214:217], v[16:19]
	v_mfma_f32_16x16x32_f16 v[12:15], v[170:173], v[214:217], v[12:15]
	v_mfma_f32_16x16x32_f16 v[64:67], v[166:169], v[182:185], v[64:67]
	v_mfma_f32_16x16x32_f16 v[60:63], v[174:177], v[182:185], v[60:63]
	v_mfma_f32_16x16x32_f16 v[48:51], v[166:169], v[202:205], v[48:51]
	v_mfma_f32_16x16x32_f16 v[44:47], v[174:177], v[202:205], v[44:47]
	v_mfma_f32_16x16x32_f16 v[32:35], v[166:169], v[210:213], v[32:35]
	v_mfma_f32_16x16x32_f16 v[28:31], v[174:177], v[210:213], v[28:31]
	v_mfma_f32_16x16x32_f16 v[16:19], v[166:169], v[218:221], v[16:19]
	v_mfma_f32_16x16x32_f16 v[12:15], v[174:177], v[218:221], v[12:15]
	s_setprio 0
	s_barrier
; #define G8_STAGE(bufoff, gbase) do { _Pragma("unroll") for (int _i = 0; _i < 2; ++_i) \
;     __builtin_amdgcn_global_load_lds((const unsigned*)((const char*)(gbase) + voffA[_i]), (LAS unsigned*)(lds + (bufoff) + ldsw + _i * 8192), 16, 0, 0); } while (0)
; #define G8_LDA(dst, b, h) do { _Pragma("unroll") for (int m = 0; m < 4; ++m) _Pragma("unroll") for (int k = 0; k < 2; ++k) dst[m][k] = *(const LAS h16x8*)(lds + G8_SA(b, h) + aoff + m * 2048 + k * 1024); } while (0)
; #define G8_LDB(dst, b, h) do { _Pragma("unroll") for (int n = 0; n < 2; ++n) _Pragma("unroll") for (int k = 0; k < 2; ++k) dst[n][k] = *(const LAS h16x8*)(lds + G8_SB(b, h) + boff + n * 2048 + k * 1024); } while (0)
; #define G8_MMA(ai, bj, At, Bt_) do { __builtin_amdgcn_s_setprio(1); _Pragma("unroll") for (int m = 0; m < 4; ++m) _Pragma("unroll") for (int n = 0; n < 2; ++n) _Pragma("unroll") for (int k = 0; k < 2; ++k) \
;     acc[ai][bj][m][n] = __builtin_amdgcn_mfma_f32_16x16x32_f16(Bt_[n][k], At[m][k], acc[ai][bj][m][n], 0, 0, 0); __builtin_amdgcn_s_setprio(0); } while (0)
; #define G8_WAIT_V(n) asm volatile("s_waitcnt vmcnt(" #n ")" ::: "memory")
; #define G8_WAIT_L(n) asm volatile("s_waitcnt lgkmcnt(" #n ")" ::: "memory")
; #define G8_BAR __builtin_amdgcn_s_barrier()
; #define G8_SCHED __builtin_amdgcn_sched_barrier(0)
; template <class Epi>
; __device__ __forceinline__ void gemm_phase(LAS unsigned char* lds, const h16* A, const h16* Bt, int K, const Order& S, const Epi& E) {
;     ...
;       G8_STAGE(G8_SB(0, 1), b2 + hstep);
;       G8_WAIT_V(6); G8_BAR; G8_MMA(1, 1, At, B1); G8_BAR;
;       G8_LDB(B0, 1, 0); G8_SCHED; G8_LDA(At, 1, 0); G8_STAGE(G8_SA(0, 1), a2 + hstep);
;       G8_WAIT_L(8); G8_BAR; G8_WAIT_L(0); G8_MMA(0, 0, At, B0); G8_BAR; G8_SCHED;
;       G8_LDB(B1, 1, 1); G8_STAGE(G8_SB(1, 0), b3);
	s_add_u32 s56, s26, 0x40000
	s_addc_u32 s57, s27, 0
	s_mov_b32 m0, s41
	v_lshl_add_u64 v[2:3], s[56:57], 0, v[134:135]
	global_load_lds_dwordx4 v[2:3], off
	v_lshl_add_u64 v[2:3], s[56:57], 0, v[132:133]
	s_mov_b32 m0, s42
	s_nop 0
	global_load_lds_dwordx4 v[2:3], off
	s_waitcnt vmcnt(6)
	s_barrier
	s_setprio 1
	v_mfma_f32_16x16x32_f16 v[56:59], v[222:225], v[178:181], v[56:59]
	v_mfma_f32_16x16x32_f16 v[52:55], v[230:233], v[178:181], v[52:55]
	v_mfma_f32_16x16x32_f16 v[40:43], v[222:225], v[186:189], v[40:43]
	v_mfma_f32_16x16x32_f16 v[36:39], v[230:233], v[186:189], v[36:39]
	v_mfma_f32_16x16x32_f16 v[24:27], v[222:225], v[206:209], v[24:27]
	v_mfma_f32_16x16x32_f16 v[20:23], v[230:233], v[206:209], v[20:23]
	v_mfma_f32_16x16x32_f16 v[8:11], v[222:225], v[214:217], v[8:11]
	v_mfma_f32_16x16x32_f16 v[2:5], v[230:233], v[214:217], v[4:7]
	v_mfma_f32_16x16x32_f16 v[56:59], v[226:229], v[182:185], v[56:59]
	v_mfma_f32_16x16x32_f16 v[52:55], v[234:237], v[182:185], v[52:55]
	v_mfma_f32_16x16x32_f16 v[40:43], v[226:229], v[202:205], v[40:43]
	v_mfma_f32_16x16x32_f16 v[36:39], v[234:237], v[202:205], v[36:39]
	v_mfma_f32_16x16x32_f16 v[24:27], v[226:229], v[210:213], v[24:27]
	v_mfma_f32_16x16x32_f16 v[20:23], v[234:237], v[210:213], v[20:23]
	v_mfma_f32_16x16x32_f16 v[8:11], v[226:229], v[218:221], v[8:11]
	v_mfma_f32_16x16x32_f16 v[2:5], v[234:237], v[218:221], v[2:5]
	s_setprio 0
	v_or_b32_e32 v0, 0x18000, v158
	s_barrier
	v_add_u32_e32 v6, 0x18400, v158
	ds_read_b128 v[162:165], v0
	ds_read_b128 v[166:169], v6
	v_add_u32_e32 v0, 0x18800, v158
	v_add_u32_e32 v6, 0x18c00, v158
	ds_read_b128 v[170:173], v0
	ds_read_b128 v[174:177], v6
	s_add_u32 s28, s28, 0x40000
	s_addc_u32 s29, s29, 0
	s_mov_b32 m0, s43
	v_lshl_add_u64 v[6:7], s[28:29], 0, v[134:135]
	ds_read_b128 v[178:181], v139 offset:32768
	ds_read_b128 v[182:185], v139 offset:33792
	ds_read_b128 v[186:189], v139 offset:34816
	ds_read_b128 v[202:205], v139 offset:35840
	ds_read_b128 v[206:209], v139 offset:36864
	ds_read_b128 v[210:213], v139 offset:37888
	ds_read_b128 v[214:217], v139 offset:38912
	ds_read_b128 v[218:221], v139 offset:39936
	global_load_lds_dwordx4 v[6:7], off
	v_lshl_add_u64 v[6:7], s[28:29], 0, v[132:133]
	s_mov_b32 m0, s44
	s_nop 0
	global_load_lds_dwordx4 v[6:7], off
	s_waitcnt lgkmcnt(8)
	s_barrier
	s_waitcnt lgkmcnt(0)
	s_setprio 1
	s_waitcnt lgkmcnt(0)
	v_mfma_f32_16x16x32_f16 v[128:131], v[162:165], v[178:181], v[128:131]
	v_mfma_f32_16x16x32_f16 v[124:127], v[170:173], v[178:181], v[124:127]
	v_mfma_f32_16x16x32_f16 v[112:115], v[162:165], v[186:189], v[112:115]
	v_mfma_f32_16x16x32_f16 v[108:111], v[170:173], v[186:189], v[108:111]
	v_mfma_f32_16x16x32_f16 v[96:99], v[162:165], v[206:209], v[96:99]
	v_mfma_f32_16x16x32_f16 v[92:95], v[170:173], v[206:209], v[92:95]
	v_mfma_f32_16x16x32_f16 v[80:83], v[162:165], v[214:217], v[80:83]
	v_mfma_f32_16x16x32_f16 v[76:79], v[170:173], v[214:217], v[76:79]
	v_mfma_f32_16x16x32_f16 v[128:131], v[166:169], v[182:185], v[128:131]
	v_mfma_f32_16x16x32_f16 v[124:127], v[174:177], v[182:185], v[124:127]
	v_mfma_f32_16x16x32_f16 v[112:115], v[166:169], v[202:205], v[112:115]
	v_mfma_f32_16x16x32_f16 v[108:111], v[174:177], v[202:205], v[108:111]
	v_mfma_f32_16x16x32_f16 v[96:99], v[166:169], v[210:213], v[96:99]
	v_mfma_f32_16x16x32_f16 v[92:95], v[174:177], v[210:213], v[92:95]
	v_mfma_f32_16x16x32_f16 v[80:83], v[166:169], v[218:221], v[80:83]
	v_mfma_f32_16x16x32_f16 v[76:79], v[174:177], v[218:221], v[76:79]
	s_setprio 0
	s_barrier
	v_or_b32_e32 v0, 0x1c000, v158
	v_add_u32_e32 v6, 0x1c400, v158
	ds_read_b128 v[222:225], v0
	ds_read_b128 v[226:229], v6
	v_add_u32_e32 v0, 0x1c800, v158
	v_add_u32_e32 v6, 0x1cc00, v158
	s_mov_b32 m0, s46
	ds_read_b128 v[230:233], v0
	ds_read_b128 v[234:237], v6
	v_lshl_add_u64 v[6:7], v[238:239], 0, s[94:95]
	global_load_lds_dwordx4 v[6:7], off
	v_lshl_add_u64 v[6:7], v[240:241], 0, s[94:95]
	s_mov_b32 m0, s47
	s_nop 0
	global_load_lds_dwordx4 v[6:7], off
	s_barrier
; #define G8_STAGE(bufoff, gbase) do { _Pragma("unroll") for (int _i = 0; _i < 2; ++_i) \
;     __builtin_amdgcn_global_load_lds((const unsigned*)((const char*)(gbase) + voffA[_i]), (LAS unsigned*)(lds + (bufoff) + ldsw + _i * 8192), 16, 0, 0); } while (0)
; #define G8_LDA(dst, b, h) do { _Pragma("unroll") for (int m = 0; m < 4; ++m) _Pragma("unroll") for (int k = 0; k < 2; ++k) dst[m][k] = *(const LAS h16x8*)(lds + G8_SA(b, h) + aoff + m * 2048 + k * 1024); } while (0)
; #define G8_MMA(ai, bj, At, Bt_) do { __builtin_amdgcn_s_setprio(1); _Pragma("unroll") for (int m = 0; m < 4; ++m) _Pragma("unroll") for (int n = 0; n < 2; ++n) _Pragma("unroll") for (int k = 0; k < 2; ++k) \
;     acc[ai][bj][m][n] = __builtin_amdgcn_mfma_f32_16x16x32_f16(Bt_[n][k], At[m][k], acc[ai][bj][m][n], 0, 0, 0); __builtin_amdgcn_s_setprio(0); } while (0)
; #define G8_WAIT_V(n) asm volatile("s_waitcnt vmcnt(" #n ")" ::: "memory")
; #define G8_WAIT_L(n) asm volatile("s_waitcnt lgkmcnt(" #n ")" ::: "memory")
; #define G8_BAR __builtin_amdgcn_s_barrier()
; #define G8_SCHED __builtin_amdgcn_sched_barrier(0)
; template <class Epi>
; __device__ __forceinline__ void gemm_phase(LAS unsigned char* lds, const h16* A, const h16* Bt, int K, const Order& S, const Epi& E) {
;     ...
;       G8_BAR; G8_WAIT_L(0); G8_MMA(0, 1, At, B1); G8_BAR;
;       G8_LDA(At, 1, 1); G8_STAGE(G8_SA(1, 0), a3);
;       G8_BAR; G8_WAIT_L(0); G8_MMA(1, 0, At, B0); G8_BAR; G8_SCHED;
;       G8_STAGE(G8_SB(1, 1), b3 + hstep);
;       G8_WAIT_V(6); G8_BAR; G8_MMA(1, 1, At, B1); G8_BAR;
;     }
	s_waitcnt lgkmcnt(0)
	s_setprio 1
	s_waitcnt lgkmcnt(0)
	v_mfma_f32_16x16x32_f16 v[120:123], v[222:225], v[178:181], v[120:123]
	v_mfma_f32_16x16x32_f16 v[116:119], v[230:233], v[178:181], v[116:119]
	v_mfma_f32_16x16x32_f16 v[104:107], v[222:225], v[186:189], v[104:107]
	v_mfma_f32_16x16x32_f16 v[100:103], v[230:233], v[186:189], v[100:103]
	v_mfma_f32_16x16x32_f16 v[88:91], v[222:225], v[206:209], v[88:91]
	v_mfma_f32_16x16x32_f16 v[84:87], v[230:233], v[206:209], v[84:87]
	v_mfma_f32_16x16x32_f16 v[72:75], v[222:225], v[214:217], v[72:75]
	v_mfma_f32_16x16x32_f16 v[68:71], v[230:233], v[214:217], v[68:71]
	v_mfma_f32_16x16x32_f16 v[120:123], v[226:229], v[182:185], v[120:123]
	v_mfma_f32_16x16x32_f16 v[116:119], v[234:237], v[182:185], v[116:119]
	v_mfma_f32_16x16x32_f16 v[104:107], v[226:229], v[202:205], v[104:107]
	v_mfma_f32_16x16x32_f16 v[100:103], v[234:237], v[202:205], v[100:103]
	v_mfma_f32_16x16x32_f16 v[88:91], v[226:229], v[210:213], v[88:91]
	v_mfma_f32_16x16x32_f16 v[84:87], v[234:237], v[210:213], v[84:87]
	v_mfma_f32_16x16x32_f16 v[72:75], v[226:229], v[218:221], v[72:75]
	v_mfma_f32_16x16x32_f16 v[68:71], v[234:237], v[218:221], v[68:71]
	s_setprio 0
	s_mov_b32 m0, s48
	v_lshl_add_u64 v[6:7], v[242:243], 0, s[94:95]
	s_barrier
	ds_read_b128 v[178:181], v139 offset:49152
	ds_read_b128 v[182:185], v139 offset:50176
	ds_read_b128 v[186:189], v139 offset:51200
	ds_read_b128 v[202:205], v139 offset:52224
	ds_read_b128 v[206:209], v139 offset:53248
	ds_read_b128 v[210:213], v139 offset:54272
	ds_read_b128 v[214:217], v139 offset:55296
	ds_read_b128 v[218:221], v139 offset:56320
	global_load_lds_dwordx4 v[6:7], off
	v_lshl_add_u64 v[6:7], v[244:245], 0, s[94:95]
	s_mov_b32 m0, s49
	s_nop 0
	global_load_lds_dwordx4 v[6:7], off
	s_barrier
	s_waitcnt lgkmcnt(0)
	s_setprio 1
	s_waitcnt lgkmcnt(0)
	v_mfma_f32_16x16x32_f16 v[64:67], v[162:165], v[178:181], v[64:67]
	v_mfma_f32_16x16x32_f16 v[60:63], v[170:173], v[178:181], v[60:63]
	v_mfma_f32_16x16x32_f16 v[48:51], v[162:165], v[186:189], v[48:51]
	v_mfma_f32_16x16x32_f16 v[44:47], v[170:173], v[186:189], v[44:47]
	v_mfma_f32_16x16x32_f16 v[32:35], v[162:165], v[206:209], v[32:35]
	v_mfma_f32_16x16x32_f16 v[28:31], v[170:173], v[206:209], v[28:31]
	v_mfma_f32_16x16x32_f16 v[16:19], v[162:165], v[214:217], v[16:19]
	v_mfma_f32_16x16x32_f16 v[12:15], v[170:173], v[214:217], v[12:15]
	v_mfma_f32_16x16x32_f16 v[64:67], v[166:169], v[182:185], v[64:67]
	v_mfma_f32_16x16x32_f16 v[60:63], v[174:177], v[182:185], v[60:63]
	v_mfma_f32_16x16x32_f16 v[48:51], v[166:169], v[202:205], v[48:51]
	v_mfma_f32_16x16x32_f16 v[44:47], v[174:177], v[202:205], v[44:47]
	v_mfma_f32_16x16x32_f16 v[32:35], v[166:169], v[210:213], v[32:35]
	v_mfma_f32_16x16x32_f16 v[28:31], v[174:177], v[210:213], v[28:31]
	v_mfma_f32_16x16x32_f16 v[16:19], v[166:169], v[218:221], v[16:19]
	v_mfma_f32_16x16x32_f16 v[12:15], v[174:177], v[218:221], v[12:15]
	s_setprio 0
	s_barrier
	s_add_u32 s26, s26, 0x40080
	s_addc_u32 s27, s27, 0
	s_mov_b32 m0, s50
	v_lshl_add_u64 v[6:7], s[26:27], 0, v[134:135]
	global_load_lds_dwordx4 v[6:7], off
	v_lshl_add_u64 v[6:7], s[26:27], 0, v[132:133]
	s_mov_b32 m0, s51
	s_nop 0
	global_load_lds_dwordx4 v[6:7], off
	s_waitcnt vmcnt(6)
	s_barrier
	s_setprio 1
	v_mfma_f32_16x16x32_f16 v[56:59], v[222:225], v[178:181], v[56:59]
	v_mfma_f32_16x16x32_f16 v[52:55], v[230:233], v[178:181], v[52:55]
	v_mfma_f32_16x16x32_f16 v[40:43], v[222:225], v[186:189], v[40:43]
	v_mfma_f32_16x16x32_f16 v[36:39], v[230:233], v[186:189], v[36:39]
	v_mfma_f32_16x16x32_f16 v[24:27], v[222:225], v[206:209], v[24:27]
	v_mfma_f32_16x16x32_f16 v[20:23], v[230:233], v[206:209], v[20:23]
	v_mfma_f32_16x16x32_f16 v[6:9], v[222:225], v[214:217], v[8:11]
	v_mfma_f32_16x16x32_f16 v[2:5], v[230:233], v[214:217], v[2:5]
	v_mfma_f32_16x16x32_f16 v[56:59], v[226:229], v[182:185], v[56:59]
	v_mfma_f32_16x16x32_f16 v[52:55], v[234:237], v[182:185], v[52:55]
	v_mfma_f32_16x16x32_f16 v[40:43], v[226:229], v[202:205], v[40:43]
	v_mfma_f32_16x16x32_f16 v[36:39], v[234:237], v[202:205], v[36:39]
	v_mfma_f32_16x16x32_f16 v[24:27], v[226:229], v[210:213], v[24:27]
	v_mfma_f32_16x16x32_f16 v[20:23], v[234:237], v[210:213], v[20:23]
	v_mfma_f32_16x16x32_f16 v[8:11], v[226:229], v[218:221], v[6:9]
	v_mfma_f32_16x16x32_f16 v[4:7], v[234:237], v[218:221], v[2:5]
	s_setprio 0
	s_add_i32 s55, s55, 2
	s_add_u32 s24, s24, 0x100
	s_addc_u32 s25, s25, 0
	s_cmp_gt_u32 s55, 13
	s_barrier
	s_cbranch_scc1 .LBB0_2381

; #define G8_STAGE(bufoff, gbase) do { _Pragma("unroll") for (int _i = 0; _i < 2; ++_i) \
;     __builtin_amdgcn_global_load_lds((const unsigned*)((const char*)(gbase) + voffA[_i]), (LAS unsigned*)(lds + (bufoff) + ldsw + _i * 8192), 16, 0, 0); } while (0)
; #define G8_LDA(dst, b, h) do { _Pragma("unroll") for (int m = 0; m < 4; ++m) _Pragma("unroll") for (int k = 0; k < 2; ++k) dst[m][k] = *(const LAS h16x8*)(lds + G8_SA(b, h) + aoff + m * 2048 + k * 1024); } while (0)
; #define G8_LDB(dst, b, h) do { _Pragma("unroll") for (int n = 0; n < 2; ++n) _Pragma("unroll") for (int k = 0; k < 2; ++k) dst[n][k] = *(const LAS h16x8*)(lds + G8_SB(b, h) + boff + n * 2048 + k * 1024); } while (0)
; #define G8_MMA(ai, bj, At, Bt_) do { __builtin_amdgcn_s_setprio(1); _Pragma("unroll") for (int m = 0; m < 4; ++m) _Pragma("unroll") for (int n = 0; n < 2; ++n) _Pragma("unroll") for (int k = 0; k < 2; ++k) \
;     acc[ai][bj][m][n] = __builtin_amdgcn_mfma_f32_16x16x32_f16(Bt_[n][k], At[m][k], acc[ai][bj][m][n], 0, 0, 0); __builtin_amdgcn_s_setprio(0); } while (0)
; #define G8_WAIT_L(n) asm volatile("s_waitcnt lgkmcnt(" #n ")" ::: "memory")
; #define G8_BAR __builtin_amdgcn_s_barrier()
; #define G8_SCHED __builtin_amdgcn_sched_barrier(0)
; template <class Epi>
; __device__ __forceinline__ void gemm_phase(LAS unsigned char* lds, const h16* A, const h16* Bt, int K, const Order& S, const Epi& E) {
;     ...
;       const char* a1 = cA + (size_t)(t + 1) * kstep;
;       const char* a2 = last ? nA : cA + (size_t)(t + 2) * kstep;
;       const char* b2 = last ? nB : cB + (size_t)(t + 2) * kstep;
;       const char* a3 = a2 + kstep;
;       const char* b3 = b2 + kstep;
;       if (Epi::MID_T >= 0 && t == Epi::MID_T) E.mid(acc, ui, wr, fr);
;       G8_LDB(B0, 0, 0); G8_SCHED; G8_LDA(At, 0, 0); G8_STAGE(G8_SA(1, 1), a1 + hstep);
;       G8_WAIT_L(8); G8_BAR; G8_WAIT_L(0); G8_MMA(0, 0, At, B0); G8_BAR; G8_SCHED;
;       G8_LDB(B1, 0, 1); G8_STAGE(G8_SB(0, 0), b2);
;       G8_BAR; G8_WAIT_L(0); G8_MMA(0, 1, At, B1); G8_BAR;
;       G8_LDA(At, 0, 1); G8_STAGE(G8_SA(0, 0), a2);
;       G8_BAR; G8_WAIT_L(0); G8_MMA(1, 0, At, B0); G8_BAR; G8_SCHED;
.LBB0_2473:
	v_or_b32_e32 v159, 0x10000, v140
	v_add_u32_e32 v164, 0x10400, v140
	ds_read_b128 v[160:163], v159
	ds_read_b128 v[164:167], v164
	v_add_u32_e32 v159, 0x10800, v140
	v_add_u32_e32 v172, 0x10c00, v140
	ds_read_b128 v[168:171], v159
	ds_read_b128 v[172:175], v172
	s_add_u32 s20, s18, 0xfffc0080
	s_addc_u32 s21, s19, -1
	s_cmp_eq_u32 s51, 12
	s_cselect_b32 s23, s13, s21
	s_cselect_b32 s22, s47, s20
	s_cselect_b32 s21, s11, s50
	s_cselect_b32 s20, s48, s49
	v_lshl_add_u64 v[188:189], s[18:19], 0, v[134:135]
	s_add_i32 m0, s27, 0xc000
	ds_read_b128 v[176:179], v139
	ds_read_b128 v[180:183], v139 offset:1024
	ds_read_b128 v[184:187], v139 offset:2048
	ds_read_b128 v[202:205], v139 offset:3072
	ds_read_b128 v[206:209], v139 offset:4096
	ds_read_b128 v[210:213], v139 offset:5120
	ds_read_b128 v[214:217], v139 offset:6144
	ds_read_b128 v[218:221], v139 offset:7168
	global_load_lds_dwordx4 v[188:189], off
	v_lshl_add_u64 v[188:189], s[18:19], 0, v[136:137]
	s_add_i32 m0, s27, 0xe000
	s_nop 0
	global_load_lds_dwordx4 v[188:189], off
	s_waitcnt lgkmcnt(8)
	s_barrier
	s_waitcnt lgkmcnt(0)
	s_setprio 1
	s_waitcnt lgkmcnt(0)
	v_mfma_f32_16x16x32_f16 v[126:129], v[160:163], v[176:179], v[126:129]
	v_mfma_f32_16x16x32_f16 v[122:125], v[168:171], v[176:179], v[122:125]
	v_mfma_f32_16x16x32_f16 v[110:113], v[160:163], v[184:187], v[110:113]
	v_mfma_f32_16x16x32_f16 v[106:109], v[168:171], v[184:187], v[106:109]
	v_mfma_f32_16x16x32_f16 v[94:97], v[160:163], v[206:209], v[94:97]
	v_mfma_f32_16x16x32_f16 v[90:93], v[168:171], v[206:209], v[90:93]
	v_mfma_f32_16x16x32_f16 v[78:81], v[160:163], v[214:217], v[78:81]
	v_mfma_f32_16x16x32_f16 v[74:77], v[168:171], v[214:217], v[74:77]
	v_mfma_f32_16x16x32_f16 v[126:129], v[164:167], v[180:183], v[126:129]
	v_mfma_f32_16x16x32_f16 v[122:125], v[172:175], v[180:183], v[122:125]
	v_mfma_f32_16x16x32_f16 v[110:113], v[164:167], v[202:205], v[110:113]
	v_mfma_f32_16x16x32_f16 v[106:109], v[172:175], v[202:205], v[106:109]
	v_mfma_f32_16x16x32_f16 v[94:97], v[164:167], v[210:213], v[94:97]
	v_mfma_f32_16x16x32_f16 v[90:93], v[172:175], v[210:213], v[90:93]
	v_mfma_f32_16x16x32_f16 v[78:81], v[164:167], v[218:221], v[78:81]
	v_mfma_f32_16x16x32_f16 v[74:77], v[172:175], v[218:221], v[74:77]
	s_setprio 0
	s_barrier
	v_or_b32_e32 v159, 0x14000, v140
	v_add_u32_e32 v188, 0x14400, v140
	ds_read_b128 v[222:225], v159
	ds_read_b128 v[226:229], v188
	v_add_u32_e32 v159, 0x14800, v140
	v_add_u32_e32 v188, 0x14c00, v140
	s_mov_b32 m0, s28
	ds_read_b128 v[230:233], v159
	ds_read_b128 v[234:237], v188
	v_lshl_add_u64 v[188:189], s[20:21], 0, v[132:133]
	global_load_lds_dwordx4 v[188:189], off
	v_lshl_add_u64 v[238:239], s[20:21], 0, v[130:131]
	s_mov_b32 m0, s29
	s_nop 0
	global_load_lds_dwordx4 v[238:239], off
	s_barrier
	s_waitcnt lgkmcnt(0)
	s_setprio 1
	s_waitcnt lgkmcnt(0)
	v_mfma_f32_16x16x32_f16 v[118:121], v[222:225], v[176:179], v[118:121]
	v_mfma_f32_16x16x32_f16 v[114:117], v[230:233], v[176:179], v[114:117]
	v_mfma_f32_16x16x32_f16 v[102:105], v[222:225], v[184:187], v[102:105]
	v_mfma_f32_16x16x32_f16 v[98:101], v[230:233], v[184:187], v[98:101]
	v_mfma_f32_16x16x32_f16 v[86:89], v[222:225], v[206:209], v[86:89]
	v_mfma_f32_16x16x32_f16 v[82:85], v[230:233], v[206:209], v[82:85]
	v_mfma_f32_16x16x32_f16 v[70:73], v[222:225], v[214:217], v[70:73]
	v_mfma_f32_16x16x32_f16 v[66:69], v[230:233], v[214:217], v[66:69]
	v_mfma_f32_16x16x32_f16 v[118:121], v[226:229], v[180:183], v[118:121]
	v_mfma_f32_16x16x32_f16 v[114:117], v[234:237], v[180:183], v[114:117]
	v_mfma_f32_16x16x32_f16 v[102:105], v[226:229], v[202:205], v[102:105]
	v_mfma_f32_16x16x32_f16 v[98:101], v[234:237], v[202:205], v[98:101]
	v_mfma_f32_16x16x32_f16 v[86:89], v[226:229], v[210:213], v[86:89]
	v_mfma_f32_16x16x32_f16 v[82:85], v[234:237], v[210:213], v[82:85]
	v_mfma_f32_16x16x32_f16 v[70:73], v[226:229], v[218:221], v[70:73]
	v_mfma_f32_16x16x32_f16 v[66:69], v[234:237], v[218:221], v[66:69]
	s_setprio 0
	s_mov_b32 m0, s27
	v_lshl_add_u64 v[240:241], s[22:23], 0, v[132:133]
	s_barrier
	ds_read_b128 v[176:179], v139 offset:16384
	ds_read_b128 v[180:183], v139 offset:17408
	ds_read_b128 v[184:187], v139 offset:18432
	ds_read_b128 v[202:205], v139 offset:19456
	ds_read_b128 v[206:209], v139 offset:20480
	ds_read_b128 v[210:213], v139 offset:21504
	ds_read_b128 v[214:217], v139 offset:22528
	ds_read_b128 v[218:221], v139 offset:23552
	global_load_lds_dwordx4 v[240:241], off
	v_lshl_add_u64 v[242:243], s[22:23], 0, v[130:131]
	s_mov_b32 m0, s30
	s_nop 0
	global_load_lds_dwordx4 v[242:243], off
	s_barrier
	s_waitcnt lgkmcnt(0)
	s_setprio 1
	s_waitcnt lgkmcnt(0)
	v_mfma_f32_16x16x32_f16 v[62:65], v[160:163], v[176:179], v[62:65]
	v_mfma_f32_16x16x32_f16 v[58:61], v[168:171], v[176:179], v[58:61]
	v_mfma_f32_16x16x32_f16 v[46:49], v[160:163], v[184:187], v[46:49]
	v_mfma_f32_16x16x32_f16 v[42:45], v[168:171], v[184:187], v[42:45]
	v_mfma_f32_16x16x32_f16 v[30:33], v[160:163], v[206:209], v[30:33]
	v_mfma_f32_16x16x32_f16 v[26:29], v[168:171], v[206:209], v[26:29]
	v_mfma_f32_16x16x32_f16 v[14:17], v[160:163], v[214:217], v[14:17]
	v_mfma_f32_16x16x32_f16 v[10:13], v[168:171], v[214:217], v[10:13]
	v_mfma_f32_16x16x32_f16 v[62:65], v[164:167], v[180:183], v[62:65]
	v_mfma_f32_16x16x32_f16 v[58:61], v[172:175], v[180:183], v[58:61]
	v_mfma_f32_16x16x32_f16 v[46:49], v[164:167], v[202:205], v[46:49]
	v_mfma_f32_16x16x32_f16 v[42:45], v[172:175], v[202:205], v[42:45]
	v_mfma_f32_16x16x32_f16 v[30:33], v[164:167], v[210:213], v[30:33]
	v_mfma_f32_16x16x32_f16 v[26:29], v[172:175], v[210:213], v[26:29]
	v_mfma_f32_16x16x32_f16 v[14:17], v[164:167], v[218:221], v[14:17]
	v_mfma_f32_16x16x32_f16 v[10:13], v[172:175], v[218:221], v[10:13]
	s_setprio 0
	s_barrier
; #define G8_STAGE(bufoff, gbase) do { _Pragma("unroll") for (int _i = 0; _i < 2; ++_i) \
;     __builtin_amdgcn_global_load_lds((const unsigned*)((const char*)(gbase) + voffA[_i]), (LAS unsigned*)(lds + (bufoff) + ldsw + _i * 8192), 16, 0, 0); } while (0)
; #define G8_LDA(dst, b, h) do { _Pragma("unroll") for (int m = 0; m < 4; ++m) _Pragma("unroll") for (int k = 0; k < 2; ++k) dst[m][k] = *(const LAS h16x8*)(lds + G8_SA(b, h) + aoff + m * 2048 + k * 1024); } while (0)
; #define G8_LDB(dst, b, h) do { _Pragma("unroll") for (int n = 0; n < 2; ++n) _Pragma("unroll") for (int k = 0; k < 2; ++k) dst[n][k] = *(const LAS h16x8*)(lds + G8_SB(b, h) + boff + n * 2048 + k * 1024); } while (0)
; #define G8_MMA(ai, bj, At, Bt_) do { __builtin_amdgcn_s_setprio(1); _Pragma("unroll") for (int m = 0; m < 4; ++m) _Pragma("unroll") for (int n = 0; n < 2; ++n) _Pragma("unroll") for (int k = 0; k < 2; ++k) \
;     acc[ai][bj][m][n] = __builtin_amdgcn_mfma_f32_16x16x32_f16(Bt_[n][k], At[m][k], acc[ai][bj][m][n], 0, 0, 0); __builtin_amdgcn_s_setprio(0); } while (0)
; #define G8_WAIT_V(n) asm volatile("s_waitcnt vmcnt(" #n ")" ::: "memory")
; #define G8_WAIT_L(n) asm volatile("s_waitcnt lgkmcnt(" #n ")" ::: "memory")
; #define G8_BAR __builtin_amdgcn_s_barrier()
; #define G8_SCHED __builtin_amdgcn_sched_barrier(0)
; template <class Epi>
; __device__ __forceinline__ void gemm_phase(LAS unsigned char* lds, const h16* A, const h16* Bt, int K, const Order& S, const Epi& E) {
;     ...
;       G8_STAGE(G8_SB(0, 1), b2 + hstep);
;       G8_WAIT_V(6); G8_BAR; G8_MMA(1, 1, At, B1); G8_BAR;
;       G8_LDB(B0, 1, 0); G8_SCHED; G8_LDA(At, 1, 0); G8_STAGE(G8_SA(0, 1), a2 + hstep);
;       G8_WAIT_L(8); G8_BAR; G8_WAIT_L(0); G8_MMA(0, 0, At, B0); G8_BAR; G8_SCHED;
;       G8_LDB(B1, 1, 1); G8_STAGE(G8_SB(1, 0), b3);
;       G8_BAR; G8_WAIT_L(0); G8_MMA(0, 1, At, B1); G8_BAR;
;       G8_LDA(At, 1, 1); G8_STAGE(G8_SA(1, 0), a3);
	s_add_u32 s52, s20, 0x40000
	s_addc_u32 s53, s21, 0
	s_mov_b32 m0, s31
	v_lshl_add_u64 v[160:161], s[52:53], 0, v[132:133]
	global_load_lds_dwordx4 v[160:161], off
	v_lshl_add_u64 v[160:161], s[52:53], 0, v[130:131]
	s_mov_b32 m0, s34
	s_nop 0
	global_load_lds_dwordx4 v[160:161], off
	s_waitcnt vmcnt(6)
	s_barrier
	s_setprio 1
	v_mfma_f32_16x16x32_f16 v[54:57], v[222:225], v[176:179], v[54:57]
	v_mfma_f32_16x16x32_f16 v[50:53], v[230:233], v[176:179], v[50:53]
	v_mfma_f32_16x16x32_f16 v[38:41], v[222:225], v[184:187], v[38:41]
	v_mfma_f32_16x16x32_f16 v[34:37], v[230:233], v[184:187], v[34:37]
	v_mfma_f32_16x16x32_f16 v[22:25], v[222:225], v[206:209], v[22:25]
	v_mfma_f32_16x16x32_f16 v[18:21], v[230:233], v[206:209], v[18:21]
	v_mfma_f32_16x16x32_f16 v[6:9], v[222:225], v[214:217], v[6:9]
	v_mfma_f32_16x16x32_f16 v[2:5], v[230:233], v[214:217], v[2:5]
	v_mfma_f32_16x16x32_f16 v[54:57], v[226:229], v[180:183], v[54:57]
	v_mfma_f32_16x16x32_f16 v[50:53], v[234:237], v[180:183], v[50:53]
	v_mfma_f32_16x16x32_f16 v[38:41], v[226:229], v[202:205], v[38:41]
	v_mfma_f32_16x16x32_f16 v[34:37], v[234:237], v[202:205], v[34:37]
	v_mfma_f32_16x16x32_f16 v[22:25], v[226:229], v[210:213], v[22:25]
	v_mfma_f32_16x16x32_f16 v[18:21], v[234:237], v[210:213], v[18:21]
	v_mfma_f32_16x16x32_f16 v[6:9], v[226:229], v[218:221], v[6:9]
	v_mfma_f32_16x16x32_f16 v[2:5], v[234:237], v[218:221], v[2:5]
	s_setprio 0
	v_or_b32_e32 v159, 0x18000, v140
	v_add_u32_e32 v164, 0x18400, v140
	s_barrier
	ds_read_b128 v[160:163], v159
	ds_read_b128 v[164:167], v164
	v_add_u32_e32 v159, 0x18800, v140
	v_add_u32_e32 v172, 0x18c00, v140
	ds_read_b128 v[168:171], v159
	ds_read_b128 v[172:175], v172
	s_add_u32 s22, s22, 0x40000
	s_addc_u32 s23, s23, 0
	s_mov_b32 m0, s35
	v_lshl_add_u64 v[222:223], s[22:23], 0, v[132:133]
	ds_read_b128 v[176:179], v139 offset:32768
	ds_read_b128 v[180:183], v139 offset:33792
	ds_read_b128 v[184:187], v139 offset:34816
	ds_read_b128 v[202:205], v139 offset:35840
	ds_read_b128 v[206:209], v139 offset:36864
	ds_read_b128 v[210:213], v139 offset:37888
	ds_read_b128 v[214:217], v139 offset:38912
	ds_read_b128 v[218:221], v139 offset:39936
	global_load_lds_dwordx4 v[222:223], off
	v_lshl_add_u64 v[222:223], s[22:23], 0, v[130:131]
	s_mov_b32 m0, s36
	s_nop 0
	global_load_lds_dwordx4 v[222:223], off
	s_waitcnt lgkmcnt(8)
	s_barrier
	s_waitcnt lgkmcnt(0)
	s_setprio 1
	s_waitcnt lgkmcnt(0)
	v_mfma_f32_16x16x32_f16 v[126:129], v[160:163], v[176:179], v[126:129]
	v_mfma_f32_16x16x32_f16 v[122:125], v[168:171], v[176:179], v[122:125]
	v_mfma_f32_16x16x32_f16 v[110:113], v[160:163], v[184:187], v[110:113]
	v_mfma_f32_16x16x32_f16 v[106:109], v[168:171], v[184:187], v[106:109]
	v_mfma_f32_16x16x32_f16 v[94:97], v[160:163], v[206:209], v[94:97]
	v_mfma_f32_16x16x32_f16 v[90:93], v[168:171], v[206:209], v[90:93]
	v_mfma_f32_16x16x32_f16 v[78:81], v[160:163], v[214:217], v[78:81]
	v_mfma_f32_16x16x32_f16 v[74:77], v[168:171], v[214:217], v[74:77]
	v_mfma_f32_16x16x32_f16 v[126:129], v[164:167], v[180:183], v[126:129]
	v_mfma_f32_16x16x32_f16 v[122:125], v[172:175], v[180:183], v[122:125]
	v_mfma_f32_16x16x32_f16 v[110:113], v[164:167], v[202:205], v[110:113]
	v_mfma_f32_16x16x32_f16 v[106:109], v[172:175], v[202:205], v[106:109]
	v_mfma_f32_16x16x32_f16 v[94:97], v[164:167], v[210:213], v[94:97]
	v_mfma_f32_16x16x32_f16 v[90:93], v[172:175], v[210:213], v[90:93]
	v_mfma_f32_16x16x32_f16 v[78:81], v[164:167], v[218:221], v[78:81]
	v_mfma_f32_16x16x32_f16 v[74:77], v[172:175], v[218:221], v[74:77]
	s_setprio 0
	s_barrier
	v_or_b32_e32 v159, 0x1c000, v140
	s_mov_b32 m0, s37
	v_add_u32_e32 v195, 0x1c400, v140
	ds_read_b128 v[222:225], v159
	ds_read_b128 v[226:229], v195
	v_add_u32_e32 v159, 0x1c800, v140
	v_lshl_add_u64 v[188:189], v[188:189], 0, s[94:95]
	v_add_u32_e32 v195, 0x1cc00, v140
	ds_read_b128 v[230:233], v159
	ds_read_b128 v[234:237], v195
	global_load_lds_dwordx4 v[188:189], off
	v_lshl_add_u64 v[188:189], v[238:239], 0, s[94:95]
	s_mov_b32 m0, s38
	s_nop 0
	global_load_lds_dwordx4 v[188:189], off
	s_barrier
	s_waitcnt lgkmcnt(0)
	s_setprio 1
	s_waitcnt lgkmcnt(0)
	v_mfma_f32_16x16x32_f16 v[118:121], v[222:225], v[176:179], v[118:121]
	v_mfma_f32_16x16x32_f16 v[114:117], v[230:233], v[176:179], v[114:117]
	v_mfma_f32_16x16x32_f16 v[102:105], v[222:225], v[184:187], v[102:105]
	v_mfma_f32_16x16x32_f16 v[98:101], v[230:233], v[184:187], v[98:101]
	v_mfma_f32_16x16x32_f16 v[86:89], v[222:225], v[206:209], v[86:89]
	v_mfma_f32_16x16x32_f16 v[82:85], v[230:233], v[206:209], v[82:85]
	v_mfma_f32_16x16x32_f16 v[70:73], v[222:225], v[214:217], v[70:73]
	v_mfma_f32_16x16x32_f16 v[66:69], v[230:233], v[214:217], v[66:69]
	v_mfma_f32_16x16x32_f16 v[118:121], v[226:229], v[180:183], v[118:121]
	v_mfma_f32_16x16x32_f16 v[114:117], v[234:237], v[180:183], v[114:117]
	v_mfma_f32_16x16x32_f16 v[102:105], v[226:229], v[202:205], v[102:105]
	v_mfma_f32_16x16x32_f16 v[98:101], v[234:237], v[202:205], v[98:101]
	v_mfma_f32_16x16x32_f16 v[86:89], v[226:229], v[210:213], v[86:89]
	v_mfma_f32_16x16x32_f16 v[82:85], v[234:237], v[210:213], v[82:85]
	v_mfma_f32_16x16x32_f16 v[70:73], v[226:229], v[218:221], v[70:73]
	v_mfma_f32_16x16x32_f16 v[66:69], v[234:237], v[218:221], v[66:69]
	s_setprio 0
	s_mov_b32 m0, s39
	v_lshl_add_u64 v[188:189], v[240:241], 0, s[94:95]
	s_barrier
	ds_read_b128 v[176:179], v139 offset:49152
	ds_read_b128 v[180:183], v139 offset:50176
	ds_read_b128 v[184:187], v139 offset:51200
	ds_read_b128 v[202:205], v139 offset:52224
	ds_read_b128 v[206:209], v139 offset:53248
	ds_read_b128 v[210:213], v139 offset:54272
	ds_read_b128 v[214:217], v139 offset:55296
	ds_read_b128 v[218:221], v139 offset:56320
	global_load_lds_dwordx4 v[188:189], off
	v_lshl_add_u64 v[188:189], v[242:243], 0, s[94:95]
	s_mov_b32 m0, s40
	s_nop 0
	global_load_lds_dwordx4 v[188:189], off
	s_barrier
; #define G8_STAGE(bufoff, gbase) do { _Pragma("unroll") for (int _i = 0; _i < 2; ++_i) \
;     __builtin_amdgcn_global_load_lds((const unsigned*)((const char*)(gbase) + voffA[_i]), (LAS unsigned*)(lds + (bufoff) + ldsw + _i * 8192), 16, 0, 0); } while (0)
; #define G8_MMA(ai, bj, At, Bt_) do { __builtin_amdgcn_s_setprio(1); _Pragma("unroll") for (int m = 0; m < 4; ++m) _Pragma("unroll") for (int n = 0; n < 2; ++n) _Pragma("unroll") for (int k = 0; k < 2; ++k) \
;     acc[ai][bj][m][n] = __builtin_amdgcn_mfma_f32_16x16x32_f16(Bt_[n][k], At[m][k], acc[ai][bj][m][n], 0, 0, 0); __builtin_amdgcn_s_setprio(0); } while (0)
; #define G8_WAIT_V(n) asm volatile("s_waitcnt vmcnt(" #n ")" ::: "memory")
; #define G8_WAIT_L(n) asm volatile("s_waitcnt lgkmcnt(" #n ")" ::: "memory")
; #define G8_BAR __builtin_amdgcn_s_barrier()
; #define G8_SCHED __builtin_amdgcn_sched_barrier(0)
; template <class Epi>
; __device__ __forceinline__ void gemm_phase(LAS unsigned char* lds, const h16* A, const h16* Bt, int K, const Order& S, const Epi& E) {
;     ...
;       G8_BAR; G8_WAIT_L(0); G8_MMA(1, 0, At, B0); G8_BAR; G8_SCHED;
;       G8_STAGE(G8_SB(1, 1), b3 + hstep);
;       G8_WAIT_V(6); G8_BAR; G8_MMA(1, 1, At, B1); G8_BAR;
;     }
;   __device__ __forceinline__ void operator()(const f32x4 (&acc)[2][2][4][2], const g8::Unit& u, int ui, int wr, int wc, int fr, int fq) const {
;     ...
;     for (int ai = 0; ai < 2; ++ai)
; #pragma unroll
;       for (int m = 0; m < 4; ++m) {
;         const int rl = 128 * ai + 64 * wr + 16 * m + fr;
;         const float r = rsl[ui * 256 + rl];
;         h16* rowp = hid + (size_t)(u.pm * 256 + rl) * DFF + 256 * u.pn + 32 * wc + 8 * fq;
; #pragma unroll
;         for (int bj = 0; bj < 2; ++bj) {
;           f32x4 v[2];
; #pragma unroll
;           for (int n = 0; n < 2; ++n) {
;             v[n] = acc[ai][bj][m][n] * r;
; #pragma unroll
;             for (int j = 0; j < 4; ++j) { const float t = fmaxf(v[n][j], 0.f); v[n][j] = t * t; }
;           }
;           __builtin_nontemporal_store(pack8(v[0], v[1]), (h16x8*)(rowp + 128 * bj));
	s_waitcnt lgkmcnt(0)
	s_setprio 1
	s_waitcnt lgkmcnt(0)
	v_mfma_f32_16x16x32_f16 v[62:65], v[160:163], v[176:179], v[62:65]
	v_mfma_f32_16x16x32_f16 v[58:61], v[168:171], v[176:179], v[58:61]
	v_mfma_f32_16x16x32_f16 v[46:49], v[160:163], v[184:187], v[46:49]
	v_mfma_f32_16x16x32_f16 v[42:45], v[168:171], v[184:187], v[42:45]
	v_mfma_f32_16x16x32_f16 v[30:33], v[160:163], v[206:209], v[30:33]
	v_mfma_f32_16x16x32_f16 v[26:29], v[168:171], v[206:209], v[26:29]
	v_mfma_f32_16x16x32_f16 v[14:17], v[160:163], v[214:217], v[14:17]
	v_mfma_f32_16x16x32_f16 v[10:13], v[168:171], v[214:217], v[10:13]
	v_mfma_f32_16x16x32_f16 v[62:65], v[164:167], v[180:183], v[62:65]
	v_mfma_f32_16x16x32_f16 v[58:61], v[172:175], v[180:183], v[58:61]
	v_mfma_f32_16x16x32_f16 v[46:49], v[164:167], v[202:205], v[46:49]
	v_mfma_f32_16x16x32_f16 v[42:45], v[172:175], v[202:205], v[42:45]
	v_mfma_f32_16x16x32_f16 v[30:33], v[164:167], v[210:213], v[30:33]
	v_mfma_f32_16x16x32_f16 v[26:29], v[172:175], v[210:213], v[26:29]
	v_mfma_f32_16x16x32_f16 v[14:17], v[164:167], v[218:221], v[14:17]
	v_mfma_f32_16x16x32_f16 v[10:13], v[172:175], v[218:221], v[10:13]
	s_setprio 0
	s_barrier
	s_add_u32 s20, s20, 0x40080
	s_addc_u32 s21, s21, 0
	s_mov_b32 m0, s41
	v_lshl_add_u64 v[160:161], s[20:21], 0, v[132:133]
	global_load_lds_dwordx4 v[160:161], off
	v_lshl_add_u64 v[160:161], s[20:21], 0, v[130:131]
	s_mov_b32 m0, s42
	s_nop 0
	global_load_lds_dwordx4 v[160:161], off
	s_waitcnt vmcnt(6)
	s_barrier
	s_setprio 1
	v_mfma_f32_16x16x32_f16 v[54:57], v[222:225], v[176:179], v[54:57]
	v_mfma_f32_16x16x32_f16 v[50:53], v[230:233], v[176:179], v[50:53]
	v_mfma_f32_16x16x32_f16 v[38:41], v[222:225], v[184:187], v[38:41]
	v_mfma_f32_16x16x32_f16 v[34:37], v[230:233], v[184:187], v[34:37]
	v_mfma_f32_16x16x32_f16 v[22:25], v[222:225], v[206:209], v[22:25]
	v_mfma_f32_16x16x32_f16 v[18:21], v[230:233], v[206:209], v[18:21]
	v_mfma_f32_16x16x32_f16 v[6:9], v[222:225], v[214:217], v[6:9]
	v_mfma_f32_16x16x32_f16 v[2:5], v[230:233], v[214:217], v[2:5]
	v_mfma_f32_16x16x32_f16 v[54:57], v[226:229], v[180:183], v[54:57]
	v_mfma_f32_16x16x32_f16 v[50:53], v[234:237], v[180:183], v[50:53]
	v_mfma_f32_16x16x32_f16 v[38:41], v[226:229], v[202:205], v[38:41]
	v_mfma_f32_16x16x32_f16 v[34:37], v[234:237], v[202:205], v[34:37]
	v_mfma_f32_16x16x32_f16 v[22:25], v[226:229], v[210:213], v[22:25]
	v_mfma_f32_16x16x32_f16 v[18:21], v[234:237], v[210:213], v[18:21]
	v_mfma_f32_16x16x32_f16 v[6:9], v[226:229], v[218:221], v[6:9]
	v_mfma_f32_16x16x32_f16 v[2:5], v[234:237], v[218:221], v[2:5]
	s_setprio 0
	s_add_i32 s51, s51, 2
	s_add_u32 s18, s18, 0x100
	s_addc_u32 s19, s19, 0
	s_add_u32 s49, s49, 0x100
	s_addc_u32 s50, s50, 0
	s_cmp_gt_u32 s51, 13
	s_barrier
	s_cbranch_scc0 .LBB0_2473
	v_lshl_add_u32 v159, s44, 10, v158
	s_waitcnt vmcnt(0)
	ds_read2_b32 v[160:161], v159 offset1:16
	s_lshl_b32 s11, s46, 8
	v_add_u32_e32 v162, s11, v138
	s_lshl_b32 s18, s45, 8
	v_ashrrev_i32_e32 v163, 31, v162
	s_waitcnt lgkmcnt(0)
	v_pk_mul_f32 v[128:129], v[128:129], v[160:161] op_sel_hi:[1,0]
	v_pk_mul_f32 v[126:127], v[126:127], v[160:161] op_sel_hi:[1,0]
	v_pk_mul_f32 v[122:123], v[122:123], v[160:161] op_sel_hi:[1,0]
	v_max_f32_e32 v166, 0, v126
	v_max_f32_e32 v126, 0, v127
	v_max_f32_e32 v127, 0, v128
	v_max_f32_e32 v128, 0, v129
	v_pk_mul_f32 v[124:125], v[124:125], v[160:161] op_sel_hi:[1,0]
	v_max_f32_e32 v129, 0, v122
	v_max_f32_e32 v164, 0, v123
	v_pk_mul_f32 v[122:123], v[126:127], v[126:127]
	v_max_f32_e32 v165, 0, v124
	v_fma_mixlo_f16 v124, v166, v166, 0
	v_cvt_pk_f16_f32 v123, v122, v123
	s_ashr_i32 s19, s18, 31
	v_lshlrev_b64 v[162:163], 13, v[162:163]
	v_max_f32_e32 v167, 0, v125
	v_pack_b32_f16 v122, v124, v123
	v_pk_mul_f32 v[124:125], v[128:129], v[128:129]
	v_lshl_add_u64 v[162:163], s[0:1], 0, v[162:163]
	s_lshl_b64 s[18:19], s[18:19], 1
	v_cvt_pk_f16_f32 v126, v124, v125
	v_pk_mul_f32 v[124:125], v[164:165], v[164:165]
	v_lshl_add_u64 v[162:163], v[162:163], 0, s[18:19]
	v_cvt_pk_f16_f32 v125, v124, v125
	v_lshl_add_u64 v[162:163], v[162:163], 0, s[92:93]
	v_alignbit_b32 v124, v125, v126, 16
	v_lshrrev_b32_e32 v125, 16, v125
	v_lshl_add_u64 v[162:163], v[162:163], 0, v[0:1]
	v_alignbit_b32 v123, v126, v123, 16
	v_fma_mixhi_f16 v125, v167, v167, 0
	v_pk_mul_f32 v[120:121], v[120:121], v[160:161] op_sel_hi:[1,0]
	v_pk_mul_f32 v[118:119], v[118:119], v[160:161] op_sel_hi:[1,0]
	global_store_dwordx4 v[162:163], v[122:125], off nt
	v_pk_mul_f32 v[114:115], v[114:115], v[160:161] op_sel_hi:[1,0]
	v_pk_mul_f32 v[116:117], v[116:117], v[160:161] op_sel_hi:[1,0]
	v_max_f32_e32 v124, 0, v118
	v_max_f32_e32 v118, 0, v119
	v_max_f32_e32 v119, 0, v120
	v_max_f32_e32 v120, 0, v121
	v_max_f32_e32 v121, 0, v114
	v_max_f32_e32 v122, 0, v115
	v_pk_mul_f32 v[114:115], v[118:119], v[118:119]
	v_max_f32_e32 v123, 0, v116
	v_fma_mixlo_f16 v116, v124, v124, 0
	v_cvt_pk_f16_f32 v115, v114, v115
	v_max_f32_e32 v125, 0, v117
	v_pack_b32_f16 v114, v116, v115
	v_pk_mul_f32 v[116:117], v[120:121], v[120:121]
	s_and_b64 vcc, exec, s[6:7]
	v_cvt_pk_f16_f32 v118, v116, v117
	v_pk_mul_f32 v[116:117], v[122:123], v[122:123]
	v_alignbit_b32 v115, v118, v115, 16
	v_cvt_pk_f16_f32 v117, v116, v117
	v_alignbit_b32 v116, v117, v118, 16
	v_lshrrev_b32_e32 v117, 16, v117
	v_fma_mixhi_f16 v117, v125, v125, 0
	global_store_dwordx4 v[162:163], v[114:117], off offset:256 nt
	s_mov_b32 s45, s10
	s_mov_b32 s46, s12
	v_mov_b32_e32 v116, v161
	v_pk_mul_f32 v[110:111], v[110:111], v[116:117] op_sel_hi:[1,0]
	v_pk_mul_f32 v[112:113], v[112:113], v[116:117] op_sel_hi:[1,0]
	v_max_f32_e32 v117, 0, v110
	v_max_f32_e32 v110, 0, v111
	v_max_f32_e32 v111, 0, v112
;   __device__ __forceinline__ void operator()(const f32x4 (&acc)[2][2][4][2], const g8::Unit& u, int ui, int wr, int wc, int fr, int fq) const {
;     ...
;     for (int ai = 0; ai < 2; ++ai)
; #pragma unroll
;       for (int m = 0; m < 4; ++m) {
;         const int rl = 128 * ai + 64 * wr + 16 * m + fr;
;         const float r = rsl[ui * 256 + rl];
;         h16* rowp = hid + (size_t)(u.pm * 256 + rl) * DFF + 256 * u.pn + 32 * wc + 8 * fq;
; #pragma unroll
;         for (int bj = 0; bj < 2; ++bj) {
;           f32x4 v[2];
; #pragma unroll
;           for (int n = 0; n < 2; ++n) {
;             v[n] = acc[ai][bj][m][n] * r;
; #pragma unroll
;             for (int j = 0; j < 4; ++j) { const float t = fmaxf(v[n][j], 0.f); v[n][j] = t * t; }
;           }
;           __builtin_nontemporal_store(pack8(v[0], v[1]), (h16x8*)(rowp + 128 * bj));
	v_pk_mul_f32 v[106:107], v[106:107], v[116:117] op_sel_hi:[1,0]
	v_add_u32_e32 v114, s11, v141
	v_max_f32_e32 v112, 0, v113
	v_pk_mul_f32 v[108:109], v[108:109], v[116:117] op_sel_hi:[1,0]
	v_max_f32_e32 v113, 0, v106
	v_max_f32_e32 v118, 0, v107
	v_pk_mul_f32 v[106:107], v[110:111], v[110:111]
	v_ashrrev_i32_e32 v115, 31, v114
	v_max_f32_e32 v119, 0, v108
	v_fma_mixlo_f16 v108, v117, v117, 0
	v_cvt_pk_f16_f32 v107, v106, v107
	v_lshlrev_b64 v[114:115], 13, v[114:115]
	v_max_f32_e32 v120, 0, v109
	v_pack_b32_f16 v106, v108, v107
	v_pk_mul_f32 v[108:109], v[112:113], v[112:113]
	v_lshl_add_u64 v[114:115], s[0:1], 0, v[114:115]
	v_cvt_pk_f16_f32 v110, v108, v109
	v_pk_mul_f32 v[108:109], v[118:119], v[118:119]
	v_lshl_add_u64 v[114:115], v[114:115], 0, s[18:19]
	v_cvt_pk_f16_f32 v109, v108, v109
	v_lshl_add_u64 v[114:115], v[114:115], 0, s[92:93]
	v_alignbit_b32 v108, v109, v110, 16
	v_lshrrev_b32_e32 v109, 16, v109
	v_lshl_add_u64 v[114:115], v[114:115], 0, v[0:1]
	v_alignbit_b32 v107, v110, v107, 16
	v_fma_mixhi_f16 v109, v120, v120, 0
	v_pk_mul_f32 v[104:105], v[104:105], v[116:117] op_sel_hi:[1,0]
	v_pk_mul_f32 v[102:103], v[102:103], v[116:117] op_sel_hi:[1,0]
	global_store_dwordx4 v[114:115], v[106:109], off nt
	v_pk_mul_f32 v[98:99], v[98:99], v[116:117] op_sel_hi:[1,0]
	v_pk_mul_f32 v[100:101], v[100:101], v[116:117] op_sel_hi:[1,0]
	v_max_f32_e32 v108, 0, v102
	v_max_f32_e32 v102, 0, v103
	v_max_f32_e32 v103, 0, v104
	v_max_f32_e32 v104, 0, v105
	v_max_f32_e32 v105, 0, v98
	v_max_f32_e32 v106, 0, v99
	v_pk_mul_f32 v[98:99], v[102:103], v[102:103]
	v_max_f32_e32 v107, 0, v100
	v_fma_mixlo_f16 v100, v108, v108, 0
	v_cvt_pk_f16_f32 v99, v98, v99
	v_max_f32_e32 v109, 0, v101
	v_pack_b32_f16 v98, v100, v99
	v_pk_mul_f32 v[100:101], v[104:105], v[104:105]
	s_mov_b64 s[20:21], s[16:17]
	v_cvt_pk_f16_f32 v102, v100, v101
	v_pk_mul_f32 v[100:101], v[106:107], v[106:107]
	v_alignbit_b32 v99, v102, v99, 16
	v_cvt_pk_f16_f32 v101, v100, v101
	v_alignbit_b32 v100, v101, v102, 16
	v_lshrrev_b32_e32 v101, 16, v101
	v_fma_mixhi_f16 v101, v109, v109, 0
	global_store_dwordx4 v[114:115], v[98:101], off offset:256 nt
	ds_read2_b32 v[98:99], v159 offset0:32 offset1:48
	s_mov_b32 s44, s43
	v_add_u32_e32 v100, s11, v152
	v_ashrrev_i32_e32 v101, 31, v100
	v_lshlrev_b64 v[100:101], 13, v[100:101]
	s_waitcnt lgkmcnt(0)
	v_pk_mul_f32 v[96:97], v[96:97], v[98:99] op_sel_hi:[1,0]
	v_pk_mul_f32 v[94:95], v[94:95], v[98:99] op_sel_hi:[1,0]
	v_pk_mul_f32 v[90:91], v[90:91], v[98:99] op_sel_hi:[1,0]
	v_max_f32_e32 v104, 0, v94
	v_max_f32_e32 v94, 0, v95
	v_max_f32_e32 v95, 0, v96
	v_max_f32_e32 v96, 0, v97
	v_pk_mul_f32 v[92:93], v[92:93], v[98:99] op_sel_hi:[1,0]
	v_max_f32_e32 v97, 0, v90
	v_max_f32_e32 v102, 0, v91
	v_pk_mul_f32 v[90:91], v[94:95], v[94:95]
	v_max_f32_e32 v103, 0, v92
	v_fma_mixlo_f16 v92, v104, v104, 0
	v_cvt_pk_f16_f32 v91, v90, v91
	v_max_f32_e32 v105, 0, v93
	v_pack_b32_f16 v90, v92, v91
	v_pk_mul_f32 v[92:93], v[96:97], v[96:97]
	v_lshl_add_u64 v[100:101], s[0:1], 0, v[100:101]
	v_cvt_pk_f16_f32 v94, v92, v93
	v_pk_mul_f32 v[92:93], v[102:103], v[102:103]
	v_lshl_add_u64 v[100:101], v[100:101], 0, s[18:19]
	v_cvt_pk_f16_f32 v93, v92, v93
	v_lshl_add_u64 v[100:101], v[100:101], 0, s[92:93]
	v_alignbit_b32 v92, v93, v94, 16
	v_lshrrev_b32_e32 v93, 16, v93
	v_lshl_add_u64 v[100:101], v[100:101], 0, v[0:1]
	v_alignbit_b32 v91, v94, v91, 16
	v_fma_mixhi_f16 v93, v105, v105, 0
	v_pk_mul_f32 v[88:89], v[88:89], v[98:99] op_sel_hi:[1,0]
	v_pk_mul_f32 v[86:87], v[86:87], v[98:99] op_sel_hi:[1,0]
	global_store_dwordx4 v[100:101], v[90:93], off nt
	v_pk_mul_f32 v[82:83], v[82:83], v[98:99] op_sel_hi:[1,0]
	v_pk_mul_f32 v[84:85], v[84:85], v[98:99] op_sel_hi:[1,0]
	v_max_f32_e32 v92, 0, v86
	v_max_f32_e32 v86, 0, v87
	v_max_f32_e32 v87, 0, v88
	v_max_f32_e32 v88, 0, v89
	v_max_f32_e32 v89, 0, v82
	v_max_f32_e32 v90, 0, v83
	v_pk_mul_f32 v[82:83], v[86:87], v[86:87]
	v_max_f32_e32 v91, 0, v84
	v_fma_mixlo_f16 v84, v92, v92, 0
	v_cvt_pk_f16_f32 v83, v82, v83
	v_max_f32_e32 v93, 0, v85
	v_pack_b32_f16 v82, v84, v83
	v_pk_mul_f32 v[84:85], v[88:89], v[88:89]
	s_nop 0
	v_cvt_pk_f16_f32 v86, v84, v85
	v_pk_mul_f32 v[84:85], v[90:91], v[90:91]
	v_alignbit_b32 v83, v86, v83, 16
	v_cvt_pk_f16_f32 v85, v84, v85
	v_alignbit_b32 v84, v85, v86, 16
	v_lshrrev_b32_e32 v85, 16, v85
	v_fma_mixhi_f16 v85, v93, v93, 0
	global_store_dwordx4 v[100:101], v[82:85], off offset:256 nt
	s_nop 1
	v_mov_b32_e32 v84, v99
	v_pk_mul_f32 v[78:79], v[78:79], v[84:85] op_sel_hi:[1,0]
	v_pk_mul_f32 v[80:81], v[80:81], v[84:85] op_sel_hi:[1,0]
	v_max_f32_e32 v85, 0, v78
	v_max_f32_e32 v78, 0, v79
	v_max_f32_e32 v79, 0, v80
	v_pk_mul_f32 v[74:75], v[74:75], v[84:85] op_sel_hi:[1,0]
	v_add_u32_e32 v82, s11, v153
	v_max_f32_e32 v80, 0, v81
	v_pk_mul_f32 v[76:77], v[76:77], v[84:85] op_sel_hi:[1,0]
	v_max_f32_e32 v81, 0, v74
	v_max_f32_e32 v86, 0, v75
	v_pk_mul_f32 v[74:75], v[78:79], v[78:79]
	v_ashrrev_i32_e32 v83, 31, v82
	v_max_f32_e32 v87, 0, v76
	v_fma_mixlo_f16 v76, v85, v85, 0
	v_cvt_pk_f16_f32 v75, v74, v75
	v_lshlrev_b64 v[82:83], 13, v[82:83]
	v_max_f32_e32 v88, 0, v77
	v_pack_b32_f16 v74, v76, v75
	v_pk_mul_f32 v[76:77], v[80:81], v[80:81]
	v_lshl_add_u64 v[82:83], s[0:1], 0, v[82:83]
	v_cvt_pk_f16_f32 v78, v76, v77
	v_pk_mul_f32 v[76:77], v[86:87], v[86:87]
	v_lshl_add_u64 v[82:83], v[82:83], 0, s[18:19]
	v_cvt_pk_f16_f32 v77, v76, v77
	v_lshl_add_u64 v[82:83], v[82:83], 0, s[92:93]
	v_alignbit_b32 v76, v77, v78, 16
	v_lshrrev_b32_e32 v77, 16, v77
	v_lshl_add_u64 v[82:83], v[82:83], 0, v[0:1]
	v_alignbit_b32 v75, v78, v75, 16
	v_fma_mixhi_f16 v77, v88, v88, 0
	v_pk_mul_f32 v[72:73], v[72:73], v[84:85] op_sel_hi:[1,0]
	v_pk_mul_f32 v[70:71], v[70:71], v[84:85] op_sel_hi:[1,0]
	global_store_dwordx4 v[82:83], v[74:77], off nt
	v_pk_mul_f32 v[66:67], v[66:67], v[84:85] op_sel_hi:[1,0]
	v_pk_mul_f32 v[68:69], v[68:69], v[84:85] op_sel_hi:[1,0]
	v_max_f32_e32 v76, 0, v70
	v_max_f32_e32 v70, 0, v71
	v_max_f32_e32 v71, 0, v72
	v_max_f32_e32 v72, 0, v73
	v_max_f32_e32 v73, 0, v66
	v_max_f32_e32 v74, 0, v67
	v_pk_mul_f32 v[66:67], v[70:71], v[70:71]
	v_max_f32_e32 v75, 0, v68
	v_fma_mixlo_f16 v68, v76, v76, 0
	v_cvt_pk_f16_f32 v67, v66, v67
	v_max_f32_e32 v77, 0, v69
	v_pack_b32_f16 v66, v68, v67
	v_pk_mul_f32 v[68:69], v[72:73], v[72:73]
	s_nop 0
	v_cvt_pk_f16_f32 v70, v68, v69
	v_pk_mul_f32 v[68:69], v[74:75], v[74:75]
	v_alignbit_b32 v67, v70, v67, 16
	v_cvt_pk_f16_f32 v69, v68, v69
	v_alignbit_b32 v68, v69, v70, 16
	v_lshrrev_b32_e32 v69, 16, v69
	v_fma_mixhi_f16 v69, v77, v77, 0
	global_store_dwordx4 v[82:83], v[66:69], off offset:256 nt
	ds_read2_b32 v[66:67], v159 offset0:128 offset1:144
	s_waitcnt lgkmcnt(0)
;   __device__ __forceinline__ void operator()(const f32x4 (&acc)[2][2][4][2], const g8::Unit& u, int ui, int wr, int wc, int fr, int fq) const {
;     ...
;     for (int ai = 0; ai < 2; ++ai)
; #pragma unroll
;       for (int m = 0; m < 4; ++m) {
;         const int rl = 128 * ai + 64 * wr + 16 * m + fr;
;         const float r = rsl[ui * 256 + rl];
;         h16* rowp = hid + (size_t)(u.pm * 256 + rl) * DFF + 256 * u.pn + 32 * wc + 8 * fq;
; #pragma unroll
;         for (int bj = 0; bj < 2; ++bj) {
;           f32x4 v[2];
; #pragma unroll
;           for (int n = 0; n < 2; ++n) {
;             v[n] = acc[ai][bj][m][n] * r;
; #pragma unroll
;             for (int j = 0; j < 4; ++j) { const float t = fmaxf(v[n][j], 0.f); v[n][j] = t * t; }
;           }
;           __builtin_nontemporal_store(pack8(v[0], v[1]), (h16x8*)(rowp + 128 * bj));
	v_pk_mul_f32 v[64:65], v[64:65], v[66:67] op_sel_hi:[1,0]
	v_pk_mul_f32 v[62:63], v[62:63], v[66:67] op_sel_hi:[1,0]
	v_pk_mul_f32 v[58:59], v[58:59], v[66:67] op_sel_hi:[1,0]
	v_max_f32_e32 v72, 0, v62
	v_max_f32_e32 v62, 0, v63
	v_max_f32_e32 v63, 0, v64
	v_add_u32_e32 v68, s11, v154
	v_max_f32_e32 v64, 0, v65
	v_pk_mul_f32 v[60:61], v[60:61], v[66:67] op_sel_hi:[1,0]
	v_max_f32_e32 v65, 0, v58
	v_max_f32_e32 v70, 0, v59
	v_pk_mul_f32 v[58:59], v[62:63], v[62:63]
	v_ashrrev_i32_e32 v69, 31, v68
	v_max_f32_e32 v71, 0, v60
	v_fma_mixlo_f16 v60, v72, v72, 0
	v_cvt_pk_f16_f32 v59, v58, v59
	v_lshlrev_b64 v[68:69], 13, v[68:69]
	v_max_f32_e32 v73, 0, v61
	v_pack_b32_f16 v58, v60, v59
	v_pk_mul_f32 v[60:61], v[64:65], v[64:65]
	v_lshl_add_u64 v[68:69], s[0:1], 0, v[68:69]
	v_cvt_pk_f16_f32 v62, v60, v61
	v_pk_mul_f32 v[60:61], v[70:71], v[70:71]
	v_lshl_add_u64 v[68:69], v[68:69], 0, s[18:19]
	v_cvt_pk_f16_f32 v61, v60, v61
	v_lshl_add_u64 v[68:69], v[68:69], 0, s[92:93]
	v_alignbit_b32 v60, v61, v62, 16
	v_lshrrev_b32_e32 v61, 16, v61
	v_lshl_add_u64 v[68:69], v[68:69], 0, v[0:1]
	v_alignbit_b32 v59, v62, v59, 16
	v_fma_mixhi_f16 v61, v73, v73, 0
	v_pk_mul_f32 v[56:57], v[56:57], v[66:67] op_sel_hi:[1,0]
	v_pk_mul_f32 v[54:55], v[54:55], v[66:67] op_sel_hi:[1,0]
	global_store_dwordx4 v[68:69], v[58:61], off nt
	v_pk_mul_f32 v[50:51], v[50:51], v[66:67] op_sel_hi:[1,0]
	v_pk_mul_f32 v[52:53], v[52:53], v[66:67] op_sel_hi:[1,0]
	v_max_f32_e32 v60, 0, v54
	v_max_f32_e32 v54, 0, v55
	v_max_f32_e32 v55, 0, v56
	v_max_f32_e32 v56, 0, v57
	v_max_f32_e32 v57, 0, v50
	v_max_f32_e32 v58, 0, v51
	v_pk_mul_f32 v[50:51], v[54:55], v[54:55]
	v_max_f32_e32 v59, 0, v52
	v_fma_mixlo_f16 v52, v60, v60, 0
	v_cvt_pk_f16_f32 v51, v50, v51
	v_max_f32_e32 v61, 0, v53
	v_pack_b32_f16 v50, v52, v51
	v_pk_mul_f32 v[52:53], v[56:57], v[56:57]
	s_nop 0
	v_cvt_pk_f16_f32 v54, v52, v53
	v_pk_mul_f32 v[52:53], v[58:59], v[58:59]
	v_alignbit_b32 v51, v54, v51, 16
	v_cvt_pk_f16_f32 v53, v52, v53
	v_alignbit_b32 v52, v53, v54, 16
	v_lshrrev_b32_e32 v53, 16, v53
	v_fma_mixhi_f16 v53, v61, v61, 0
	global_store_dwordx4 v[68:69], v[50:53], off offset:256 nt
	s_nop 1
	v_mov_b32_e32 v52, v67
	v_pk_mul_f32 v[46:47], v[46:47], v[52:53] op_sel_hi:[1,0]
	v_pk_mul_f32 v[48:49], v[48:49], v[52:53] op_sel_hi:[1,0]
	v_max_f32_e32 v53, 0, v46
	v_max_f32_e32 v46, 0, v47
	v_max_f32_e32 v47, 0, v48
	v_pk_mul_f32 v[42:43], v[42:43], v[52:53] op_sel_hi:[1,0]
	v_add_u32_e32 v50, s11, v155
	v_max_f32_e32 v48, 0, v49
	v_pk_mul_f32 v[44:45], v[44:45], v[52:53] op_sel_hi:[1,0]
	v_max_f32_e32 v49, 0, v42
	v_max_f32_e32 v54, 0, v43
	v_pk_mul_f32 v[42:43], v[46:47], v[46:47]
	v_ashrrev_i32_e32 v51, 31, v50
	v_max_f32_e32 v55, 0, v44
	v_fma_mixlo_f16 v44, v53, v53, 0
	v_cvt_pk_f16_f32 v43, v42, v43
	v_lshlrev_b64 v[50:51], 13, v[50:51]
	v_max_f32_e32 v56, 0, v45
	v_pack_b32_f16 v42, v44, v43
	v_pk_mul_f32 v[44:45], v[48:49], v[48:49]
	v_lshl_add_u64 v[50:51], s[0:1], 0, v[50:51]
	v_cvt_pk_f16_f32 v46, v44, v45
	v_pk_mul_f32 v[44:45], v[54:55], v[54:55]
	v_lshl_add_u64 v[50:51], v[50:51], 0, s[18:19]
	v_cvt_pk_f16_f32 v45, v44, v45
	v_lshl_add_u64 v[50:51], v[50:51], 0, s[92:93]
	v_alignbit_b32 v44, v45, v46, 16
	v_lshrrev_b32_e32 v45, 16, v45
	v_lshl_add_u64 v[50:51], v[50:51], 0, v[0:1]
	v_alignbit_b32 v43, v46, v43, 16
	v_fma_mixhi_f16 v45, v56, v56, 0
	v_pk_mul_f32 v[40:41], v[40:41], v[52:53] op_sel_hi:[1,0]
	v_pk_mul_f32 v[38:39], v[38:39], v[52:53] op_sel_hi:[1,0]
	global_store_dwordx4 v[50:51], v[42:45], off nt
	v_pk_mul_f32 v[34:35], v[34:35], v[52:53] op_sel_hi:[1,0]
	v_pk_mul_f32 v[36:37], v[36:37], v[52:53] op_sel_hi:[1,0]
	v_max_f32_e32 v44, 0, v38
	v_max_f32_e32 v38, 0, v39
	v_max_f32_e32 v39, 0, v40
	v_max_f32_e32 v40, 0, v41
	v_max_f32_e32 v41, 0, v34
	v_max_f32_e32 v42, 0, v35
	v_pk_mul_f32 v[34:35], v[38:39], v[38:39]
	v_max_f32_e32 v43, 0, v36
	v_fma_mixlo_f16 v36, v44, v44, 0
	v_cvt_pk_f16_f32 v35, v34, v35
	v_max_f32_e32 v45, 0, v37
	v_pack_b32_f16 v34, v36, v35
	v_pk_mul_f32 v[36:37], v[40:41], v[40:41]
	s_nop 0
	v_cvt_pk_f16_f32 v38, v36, v37
	v_pk_mul_f32 v[36:37], v[42:43], v[42:43]
	v_alignbit_b32 v35, v38, v35, 16
	v_cvt_pk_f16_f32 v37, v36, v37
	v_alignbit_b32 v36, v37, v38, 16
	v_lshrrev_b32_e32 v37, 16, v37
	v_fma_mixhi_f16 v37, v45, v45, 0
	global_store_dwordx4 v[50:51], v[34:37], off offset:256 nt
	ds_read2_b32 v[34:35], v159 offset0:160 offset1:176
	s_waitcnt lgkmcnt(0)
; #define G8_WAIT_V(n) asm volatile("s_waitcnt vmcnt(" #n ")" ::: "memory")
; #define G8_BAR __builtin_amdgcn_s_barrier()
; template <class Epi>
; __device__ __forceinline__ void gemm_phase(LAS unsigned char* lds, const h16* A, const h16* Bt, int K, const Order& S, const Epi& E) {
;     ...
;     if (!has_next) break;
; #pragma unroll
;     for (int a = 0; a < 2; ++a)
; #pragma unroll
;       for (int b = 0; b < 2; ++b)
; #pragma unroll
;         for (int m = 0; m < 4; ++m)
; #pragma unroll
;           for (int n = 0; n < 2; ++n) acc[a][b][m][n] = (f32x4){0.f, 0.f, 0.f, 0.f};
;     cur = nxt; cA = nA; cB = nB; ++ui;
;   }
;   G8_WAIT_V(0);
;   if (wr == 0) G8_BAR;
;   __device__ __forceinline__ void operator()(const f32x4 (&acc)[2][2][4][2], const g8::Unit& u, int ui, int wr, int wc, int fr, int fq) const {
;     ...
;     for (int ai = 0; ai < 2; ++ai)
; #pragma unroll
;       for (int m = 0; m < 4; ++m) {
;         const int rl = 128 * ai + 64 * wr + 16 * m + fr;
;         const float r = rsl[ui * 256 + rl];
;         h16* rowp = hid + (size_t)(u.pm * 256 + rl) * DFF + 256 * u.pn + 32 * wc + 8 * fq;
; #pragma unroll
;         for (int bj = 0; bj < 2; ++bj) {
;           f32x4 v[2];
; #pragma unroll
;           for (int n = 0; n < 2; ++n) {
;             v[n] = acc[ai][bj][m][n] * r;
; #pragma unroll
;             for (int j = 0; j < 4; ++j) { const float t = fmaxf(v[n][j], 0.f); v[n][j] = t * t; }
;           }
;           __builtin_nontemporal_store(pack8(v[0], v[1]), (h16x8*)(rowp + 128 * bj));
	v_pk_mul_f32 v[32:33], v[32:33], v[34:35] op_sel_hi:[1,0]
	v_pk_mul_f32 v[30:31], v[30:31], v[34:35] op_sel_hi:[1,0]
	v_pk_mul_f32 v[26:27], v[26:27], v[34:35] op_sel_hi:[1,0]
	v_max_f32_e32 v40, 0, v30
	v_max_f32_e32 v30, 0, v31
	v_max_f32_e32 v31, 0, v32
	v_add_u32_e32 v36, s11, v156
	v_max_f32_e32 v32, 0, v33
	v_pk_mul_f32 v[28:29], v[28:29], v[34:35] op_sel_hi:[1,0]
	v_max_f32_e32 v33, 0, v26
	v_max_f32_e32 v38, 0, v27
	v_pk_mul_f32 v[26:27], v[30:31], v[30:31]
	v_ashrrev_i32_e32 v37, 31, v36
	v_max_f32_e32 v39, 0, v28
	v_fma_mixlo_f16 v28, v40, v40, 0
	v_cvt_pk_f16_f32 v27, v26, v27
	v_lshlrev_b64 v[36:37], 13, v[36:37]
	v_max_f32_e32 v41, 0, v29
	v_pack_b32_f16 v26, v28, v27
	v_pk_mul_f32 v[28:29], v[32:33], v[32:33]
	v_lshl_add_u64 v[36:37], s[0:1], 0, v[36:37]
	v_cvt_pk_f16_f32 v30, v28, v29
	v_pk_mul_f32 v[28:29], v[38:39], v[38:39]
	v_lshl_add_u64 v[36:37], v[36:37], 0, s[18:19]
	v_cvt_pk_f16_f32 v29, v28, v29
	v_lshl_add_u64 v[36:37], v[36:37], 0, s[92:93]
	v_alignbit_b32 v28, v29, v30, 16
	v_lshrrev_b32_e32 v29, 16, v29
	v_lshl_add_u64 v[36:37], v[36:37], 0, v[0:1]
	v_alignbit_b32 v27, v30, v27, 16
	v_fma_mixhi_f16 v29, v41, v41, 0
	v_pk_mul_f32 v[24:25], v[24:25], v[34:35] op_sel_hi:[1,0]
	v_pk_mul_f32 v[22:23], v[22:23], v[34:35] op_sel_hi:[1,0]
	global_store_dwordx4 v[36:37], v[26:29], off nt
	v_pk_mul_f32 v[18:19], v[18:19], v[34:35] op_sel_hi:[1,0]
	v_pk_mul_f32 v[20:21], v[20:21], v[34:35] op_sel_hi:[1,0]
	v_max_f32_e32 v28, 0, v22
	v_max_f32_e32 v22, 0, v23
	v_max_f32_e32 v23, 0, v24
	v_max_f32_e32 v24, 0, v25
	v_max_f32_e32 v25, 0, v18
	v_max_f32_e32 v26, 0, v19
	v_pk_mul_f32 v[18:19], v[22:23], v[22:23]
	v_max_f32_e32 v27, 0, v20
	v_fma_mixlo_f16 v20, v28, v28, 0
	v_cvt_pk_f16_f32 v19, v18, v19
	v_max_f32_e32 v29, 0, v21
	v_pack_b32_f16 v18, v20, v19
	v_pk_mul_f32 v[20:21], v[24:25], v[24:25]
	s_nop 0
	v_cvt_pk_f16_f32 v22, v20, v21
	v_pk_mul_f32 v[20:21], v[26:27], v[26:27]
	v_alignbit_b32 v19, v22, v19, 16
	v_cvt_pk_f16_f32 v21, v20, v21
	v_alignbit_b32 v20, v21, v22, 16
	v_lshrrev_b32_e32 v21, 16, v21
	v_fma_mixhi_f16 v21, v29, v29, 0
	global_store_dwordx4 v[36:37], v[18:21], off offset:256 nt
	s_nop 1
	v_mov_b32_e32 v20, v35
	v_pk_mul_f32 v[14:15], v[14:15], v[20:21] op_sel_hi:[1,0]
	v_pk_mul_f32 v[16:17], v[16:17], v[20:21] op_sel_hi:[1,0]
	v_max_f32_e32 v21, 0, v14
	v_max_f32_e32 v14, 0, v15
	v_max_f32_e32 v15, 0, v16
	v_pk_mul_f32 v[10:11], v[10:11], v[20:21] op_sel_hi:[1,0]
	v_add_u32_e32 v18, s11, v157
	v_max_f32_e32 v16, 0, v17
	v_pk_mul_f32 v[12:13], v[12:13], v[20:21] op_sel_hi:[1,0]
	v_max_f32_e32 v17, 0, v10
	v_max_f32_e32 v22, 0, v11
	v_pk_mul_f32 v[10:11], v[14:15], v[14:15]
	v_ashrrev_i32_e32 v19, 31, v18
	v_max_f32_e32 v23, 0, v12
	v_fma_mixlo_f16 v12, v21, v21, 0
	v_cvt_pk_f16_f32 v11, v10, v11
	v_lshlrev_b64 v[18:19], 13, v[18:19]
	v_max_f32_e32 v24, 0, v13
	v_pack_b32_f16 v10, v12, v11
	v_pk_mul_f32 v[12:13], v[16:17], v[16:17]
	v_lshl_add_u64 v[18:19], s[0:1], 0, v[18:19]
	v_cvt_pk_f16_f32 v14, v12, v13
	v_pk_mul_f32 v[12:13], v[22:23], v[22:23]
	v_lshl_add_u64 v[18:19], v[18:19], 0, s[18:19]
	v_cvt_pk_f16_f32 v13, v12, v13
	v_lshl_add_u64 v[18:19], v[18:19], 0, s[92:93]
	v_alignbit_b32 v12, v13, v14, 16
	v_lshrrev_b32_e32 v13, 16, v13
	v_lshl_add_u64 v[18:19], v[18:19], 0, v[0:1]
	v_alignbit_b32 v11, v14, v11, 16
	v_fma_mixhi_f16 v13, v24, v24, 0
	v_pk_mul_f32 v[8:9], v[8:9], v[20:21] op_sel_hi:[1,0]
	v_pk_mul_f32 v[6:7], v[6:7], v[20:21] op_sel_hi:[1,0]
	global_store_dwordx4 v[18:19], v[10:13], off nt
	v_pk_mul_f32 v[2:3], v[2:3], v[20:21] op_sel_hi:[1,0]
	v_pk_mul_f32 v[4:5], v[4:5], v[20:21] op_sel_hi:[1,0]
	v_max_f32_e32 v12, 0, v6
	v_max_f32_e32 v6, 0, v7
	v_max_f32_e32 v7, 0, v8
	v_max_f32_e32 v8, 0, v9
	v_max_f32_e32 v9, 0, v2
	v_max_f32_e32 v10, 0, v3
	v_pk_mul_f32 v[2:3], v[6:7], v[6:7]
	v_max_f32_e32 v11, 0, v4
	v_fma_mixlo_f16 v4, v12, v12, 0
	v_cvt_pk_f16_f32 v3, v2, v3
	v_max_f32_e32 v13, 0, v5
	v_pack_b32_f16 v2, v4, v3
	v_pk_mul_f32 v[4:5], v[8:9], v[8:9]
	s_mov_b64 s[18:19], s[14:15]
	v_cvt_pk_f16_f32 v6, v4, v5
	v_pk_mul_f32 v[4:5], v[10:11], v[10:11]
	v_alignbit_b32 v3, v6, v3, 16
	v_cvt_pk_f16_f32 v5, v4, v5
	v_alignbit_b32 v4, v5, v6, 16
	v_lshrrev_b32_e32 v5, 16, v5
	v_fma_mixhi_f16 v5, v13, v13, 0
	global_store_dwordx4 v[18:19], v[2:5], off offset:256 nt
	s_cbranch_vccz .LBB0_2466
	s_waitcnt vmcnt(0)
	s_cmpk_gt_u32 s2, 0xff
	s_cbranch_scc1 .LBB0_2477
	s_barrier

; #define G8_STAGE(bufoff, gbase) do { _Pragma("unroll") for (int _i = 0; _i < 2; ++_i) \
;     __builtin_amdgcn_global_load_lds((const unsigned*)((const char*)(gbase) + voffA[_i]), (LAS unsigned*)(lds + (bufoff) + ldsw + _i * 8192), 16, 0, 0); } while (0)
; #define G8_LDA(dst, b, h) do { _Pragma("unroll") for (int m = 0; m < 4; ++m) _Pragma("unroll") for (int k = 0; k < 2; ++k) dst[m][k] = *(const LAS h16x8*)(lds + G8_SA(b, h) + aoff + m * 2048 + k * 1024); } while (0)
; #define G8_LDB(dst, b, h) do { _Pragma("unroll") for (int n = 0; n < 2; ++n) _Pragma("unroll") for (int k = 0; k < 2; ++k) dst[n][k] = *(const LAS h16x8*)(lds + G8_SB(b, h) + boff + n * 2048 + k * 1024); } while (0)
; #define G8_MMA(ai, bj, At, Bt_) do { __builtin_amdgcn_s_setprio(1); _Pragma("unroll") for (int m = 0; m < 4; ++m) _Pragma("unroll") for (int n = 0; n < 2; ++n) _Pragma("unroll") for (int k = 0; k < 2; ++k) \
;     acc[ai][bj][m][n] = __builtin_amdgcn_mfma_f32_16x16x32_f16(Bt_[n][k], At[m][k], acc[ai][bj][m][n], 0, 0, 0); __builtin_amdgcn_s_setprio(0); } while (0)
; #define G8_WAIT_L(n) asm volatile("s_waitcnt lgkmcnt(" #n ")" ::: "memory")
; #define G8_BAR __builtin_amdgcn_s_barrier()
; #define G8_SCHED __builtin_amdgcn_sched_barrier(0)
; template <class Epi>
; __device__ __forceinline__ void gemm_phase(LAS unsigned char* lds, const h16* A, const h16* Bt, int K, const Order& S, const Epi& E) {
;     ...
;       const char* a1 = cA + (size_t)(t + 1) * kstep;
;       const char* a2 = last ? nA : cA + (size_t)(t + 2) * kstep;
;       const char* b2 = last ? nB : cB + (size_t)(t + 2) * kstep;
;       const char* a3 = a2 + kstep;
;       const char* b3 = b2 + kstep;
;       if (Epi::MID_T >= 0 && t == Epi::MID_T) E.mid(acc, ui, wr, fr);
;       G8_LDB(B0, 0, 0); G8_SCHED; G8_LDA(At, 0, 0); G8_STAGE(G8_SA(1, 1), a1 + hstep);
;       G8_WAIT_L(8); G8_BAR; G8_WAIT_L(0); G8_MMA(0, 0, At, B0); G8_BAR; G8_SCHED;
;       G8_LDB(B1, 0, 1); G8_STAGE(G8_SB(0, 0), b2);
;       G8_BAR; G8_WAIT_L(0); G8_MMA(0, 1, At, B1); G8_BAR;
;       G8_LDA(At, 0, 1); G8_STAGE(G8_SA(0, 0), a2);
;       G8_BAR; G8_WAIT_L(0); G8_MMA(1, 0, At, B0); G8_BAR; G8_SCHED;
.LBB0_2542:
	v_or_b32_e32 v140, 0x10000, v158
	v_add_u32_e32 v141, 0x10400, v158
	ds_read_b128 v[152:155], v140
	ds_read_b128 v[160:163], v141
	v_add_u32_e32 v140, 0x10800, v158
	v_add_u32_e32 v141, 0x10c00, v158
	ds_read_b128 v[164:167], v140
	ds_read_b128 v[168:171], v141
	s_add_u32 s24, s22, 0xfff00080
	s_addc_u32 s25, s23, -1
	s_cmp_eq_u32 s53, 60
	s_cselect_b32 s27, s3, s25
	s_cselect_b32 s26, s9, s24
	s_cselect_b32 s25, s15, s52
	s_cselect_b32 s24, s17, s51
	v_lshl_add_u64 v[140:141], s[22:23], 0, v[136:137]
	s_add_i32 m0, s35, 0xc000
	ds_read_b128 v[172:175], v135
	ds_read_b128 v[176:179], v135 offset:1024
	ds_read_b128 v[180:183], v135 offset:2048
	ds_read_b128 v[184:187], v135 offset:3072
	ds_read_b128 v[202:205], v135 offset:4096
	ds_read_b128 v[206:209], v135 offset:5120
	ds_read_b128 v[210:213], v135 offset:6144
	ds_read_b128 v[214:217], v135 offset:7168
	global_load_lds_dwordx4 v[140:141], off
	v_lshl_add_u64 v[140:141], s[22:23], 0, v[138:139]
	s_add_i32 m0, s35, 0xe000
	s_nop 0
	global_load_lds_dwordx4 v[140:141], off
	s_waitcnt lgkmcnt(8)
	s_barrier
	s_waitcnt lgkmcnt(0)
	s_setprio 1
	s_waitcnt lgkmcnt(0)
	v_mfma_f32_16x16x32_f16 v[126:129], v[152:155], v[172:175], v[126:129]
	v_mfma_f32_16x16x32_f16 v[122:125], v[164:167], v[172:175], v[122:125]
	v_mfma_f32_16x16x32_f16 v[110:113], v[152:155], v[180:183], v[110:113]
	v_mfma_f32_16x16x32_f16 v[106:109], v[164:167], v[180:183], v[106:109]
	v_mfma_f32_16x16x32_f16 v[94:97], v[152:155], v[202:205], v[94:97]
	v_mfma_f32_16x16x32_f16 v[90:93], v[164:167], v[202:205], v[90:93]
	v_mfma_f32_16x16x32_f16 v[78:81], v[152:155], v[210:213], v[78:81]
	v_mfma_f32_16x16x32_f16 v[74:77], v[164:167], v[210:213], v[74:77]
	v_mfma_f32_16x16x32_f16 v[126:129], v[160:163], v[176:179], v[126:129]
	v_mfma_f32_16x16x32_f16 v[122:125], v[168:171], v[176:179], v[122:125]
	v_mfma_f32_16x16x32_f16 v[110:113], v[160:163], v[184:187], v[110:113]
	v_mfma_f32_16x16x32_f16 v[106:109], v[168:171], v[184:187], v[106:109]
	v_mfma_f32_16x16x32_f16 v[94:97], v[160:163], v[206:209], v[94:97]
	v_mfma_f32_16x16x32_f16 v[90:93], v[168:171], v[206:209], v[90:93]
	v_mfma_f32_16x16x32_f16 v[78:81], v[160:163], v[214:217], v[78:81]
	v_mfma_f32_16x16x32_f16 v[74:77], v[168:171], v[214:217], v[74:77]
	s_setprio 0
	s_barrier
	v_or_b32_e32 v140, 0x14000, v158
	v_add_u32_e32 v141, 0x14400, v158
	ds_read_b128 v[218:221], v140
	ds_read_b128 v[222:225], v141
	v_add_u32_e32 v140, 0x14800, v158
	v_add_u32_e32 v141, 0x14c00, v158
	s_mov_b32 m0, s36
	ds_read_b128 v[226:229], v140
	ds_read_b128 v[230:233], v141
	v_lshl_add_u64 v[140:141], s[24:25], 0, v[0:1]
	global_load_lds_dwordx4 v[140:141], off
	v_lshl_add_u64 v[156:157], s[24:25], 0, v[130:131]
	s_mov_b32 m0, s37
	s_nop 0
	global_load_lds_dwordx4 v[156:157], off
	s_barrier
	s_waitcnt lgkmcnt(0)
	s_setprio 1
	s_waitcnt lgkmcnt(0)
	v_mfma_f32_16x16x32_f16 v[118:121], v[218:221], v[172:175], v[118:121]
	v_mfma_f32_16x16x32_f16 v[114:117], v[226:229], v[172:175], v[114:117]
	v_mfma_f32_16x16x32_f16 v[102:105], v[218:221], v[180:183], v[102:105]
	v_mfma_f32_16x16x32_f16 v[98:101], v[226:229], v[180:183], v[98:101]
	v_mfma_f32_16x16x32_f16 v[86:89], v[218:221], v[202:205], v[86:89]
	v_mfma_f32_16x16x32_f16 v[82:85], v[226:229], v[202:205], v[82:85]
	v_mfma_f32_16x16x32_f16 v[70:73], v[218:221], v[210:213], v[70:73]
	v_mfma_f32_16x16x32_f16 v[66:69], v[226:229], v[210:213], v[66:69]
	v_mfma_f32_16x16x32_f16 v[118:121], v[222:225], v[176:179], v[118:121]
	v_mfma_f32_16x16x32_f16 v[114:117], v[230:233], v[176:179], v[114:117]
	v_mfma_f32_16x16x32_f16 v[102:105], v[222:225], v[184:187], v[102:105]
	v_mfma_f32_16x16x32_f16 v[98:101], v[230:233], v[184:187], v[98:101]
	v_mfma_f32_16x16x32_f16 v[86:89], v[222:225], v[206:209], v[86:89]
	v_mfma_f32_16x16x32_f16 v[82:85], v[230:233], v[206:209], v[82:85]
	v_mfma_f32_16x16x32_f16 v[70:73], v[222:225], v[214:217], v[70:73]
	v_mfma_f32_16x16x32_f16 v[66:69], v[230:233], v[214:217], v[66:69]
	s_setprio 0
	s_mov_b32 m0, s35
	v_lshl_add_u64 v[188:189], s[26:27], 0, v[0:1]
	s_barrier
	ds_read_b128 v[172:175], v135 offset:16384
	ds_read_b128 v[176:179], v135 offset:17408
	ds_read_b128 v[180:183], v135 offset:18432
	ds_read_b128 v[184:187], v135 offset:19456
	ds_read_b128 v[202:205], v135 offset:20480
	ds_read_b128 v[206:209], v135 offset:21504
	ds_read_b128 v[210:213], v135 offset:22528
	ds_read_b128 v[214:217], v135 offset:23552
	global_load_lds_dwordx4 v[188:189], off
	v_lshl_add_u64 v[234:235], s[26:27], 0, v[130:131]
	s_mov_b32 m0, s38
	s_nop 0
	global_load_lds_dwordx4 v[234:235], off
	s_barrier
	s_waitcnt lgkmcnt(0)
	s_setprio 1
	s_waitcnt lgkmcnt(0)
	v_mfma_f32_16x16x32_f16 v[62:65], v[152:155], v[172:175], v[62:65]
	v_mfma_f32_16x16x32_f16 v[58:61], v[164:167], v[172:175], v[58:61]
	v_mfma_f32_16x16x32_f16 v[46:49], v[152:155], v[180:183], v[46:49]
	v_mfma_f32_16x16x32_f16 v[42:45], v[164:167], v[180:183], v[42:45]
	v_mfma_f32_16x16x32_f16 v[30:33], v[152:155], v[202:205], v[30:33]
	v_mfma_f32_16x16x32_f16 v[26:29], v[164:167], v[202:205], v[26:29]
	v_mfma_f32_16x16x32_f16 v[14:17], v[152:155], v[210:213], v[14:17]
	v_mfma_f32_16x16x32_f16 v[10:13], v[164:167], v[210:213], v[10:13]
	v_mfma_f32_16x16x32_f16 v[62:65], v[160:163], v[176:179], v[62:65]
	v_mfma_f32_16x16x32_f16 v[58:61], v[168:171], v[176:179], v[58:61]
	v_mfma_f32_16x16x32_f16 v[46:49], v[160:163], v[184:187], v[46:49]
	v_mfma_f32_16x16x32_f16 v[42:45], v[168:171], v[184:187], v[42:45]
	v_mfma_f32_16x16x32_f16 v[30:33], v[160:163], v[206:209], v[30:33]
	v_mfma_f32_16x16x32_f16 v[26:29], v[168:171], v[206:209], v[26:29]
	v_mfma_f32_16x16x32_f16 v[14:17], v[160:163], v[214:217], v[14:17]
	v_mfma_f32_16x16x32_f16 v[10:13], v[168:171], v[214:217], v[10:13]
	s_setprio 0
	s_barrier
; #define G8_STAGE(bufoff, gbase) do { _Pragma("unroll") for (int _i = 0; _i < 2; ++_i) \
;     __builtin_amdgcn_global_load_lds((const unsigned*)((const char*)(gbase) + voffA[_i]), (LAS unsigned*)(lds + (bufoff) + ldsw + _i * 8192), 16, 0, 0); } while (0)
; #define G8_LDA(dst, b, h) do { _Pragma("unroll") for (int m = 0; m < 4; ++m) _Pragma("unroll") for (int k = 0; k < 2; ++k) dst[m][k] = *(const LAS h16x8*)(lds + G8_SA(b, h) + aoff + m * 2048 + k * 1024); } while (0)
; #define G8_LDB(dst, b, h) do { _Pragma("unroll") for (int n = 0; n < 2; ++n) _Pragma("unroll") for (int k = 0; k < 2; ++k) dst[n][k] = *(const LAS h16x8*)(lds + G8_SB(b, h) + boff + n * 2048 + k * 1024); } while (0)
; #define G8_MMA(ai, bj, At, Bt_) do { __builtin_amdgcn_s_setprio(1); _Pragma("unroll") for (int m = 0; m < 4; ++m) _Pragma("unroll") for (int n = 0; n < 2; ++n) _Pragma("unroll") for (int k = 0; k < 2; ++k) \
;     acc[ai][bj][m][n] = __builtin_amdgcn_mfma_f32_16x16x32_f16(Bt_[n][k], At[m][k], acc[ai][bj][m][n], 0, 0, 0); __builtin_amdgcn_s_setprio(0); } while (0)
; #define G8_WAIT_V(n) asm volatile("s_waitcnt vmcnt(" #n ")" ::: "memory")
; #define G8_WAIT_L(n) asm volatile("s_waitcnt lgkmcnt(" #n ")" ::: "memory")
; #define G8_BAR __builtin_amdgcn_s_barrier()
; #define G8_SCHED __builtin_amdgcn_sched_barrier(0)
; template <class Epi>
; __device__ __forceinline__ void gemm_phase(LAS unsigned char* lds, const h16* A, const h16* Bt, int K, const Order& S, const Epi& E) {
;     ...
;       G8_STAGE(G8_SB(0, 1), b2 + hstep);
;       G8_WAIT_V(6); G8_BAR; G8_MMA(1, 1, At, B1); G8_BAR;
;       G8_LDB(B0, 1, 0); G8_SCHED; G8_LDA(At, 1, 0); G8_STAGE(G8_SA(0, 1), a2 + hstep);
;       G8_WAIT_L(8); G8_BAR; G8_WAIT_L(0); G8_MMA(0, 0, At, B0); G8_BAR; G8_SCHED;
;       G8_LDB(B1, 1, 1); G8_STAGE(G8_SB(1, 0), b3);
;       G8_BAR; G8_WAIT_L(0); G8_MMA(0, 1, At, B1); G8_BAR;
	s_add_u32 s54, s24, 0x100000
	s_addc_u32 s55, s25, 0
	s_mov_b32 m0, s39
	v_lshl_add_u64 v[152:153], s[54:55], 0, v[0:1]
	global_load_lds_dwordx4 v[152:153], off
	v_lshl_add_u64 v[152:153], s[54:55], 0, v[130:131]
	s_mov_b32 m0, s40
	s_nop 0
	global_load_lds_dwordx4 v[152:153], off
	s_waitcnt vmcnt(6)
	s_barrier
	s_setprio 1
	v_mfma_f32_16x16x32_f16 v[54:57], v[218:221], v[172:175], v[54:57]
	v_mfma_f32_16x16x32_f16 v[50:53], v[226:229], v[172:175], v[50:53]
	v_mfma_f32_16x16x32_f16 v[38:41], v[218:221], v[180:183], v[38:41]
	v_mfma_f32_16x16x32_f16 v[34:37], v[226:229], v[180:183], v[34:37]
	v_mfma_f32_16x16x32_f16 v[22:25], v[218:221], v[202:205], v[22:25]
	v_mfma_f32_16x16x32_f16 v[18:21], v[226:229], v[202:205], v[18:21]
	v_mfma_f32_16x16x32_f16 v[6:9], v[218:221], v[210:213], v[6:9]
	v_mfma_f32_16x16x32_f16 v[2:5], v[226:229], v[210:213], v[2:5]
	v_mfma_f32_16x16x32_f16 v[54:57], v[222:225], v[176:179], v[54:57]
	v_mfma_f32_16x16x32_f16 v[50:53], v[230:233], v[176:179], v[50:53]
	v_mfma_f32_16x16x32_f16 v[38:41], v[222:225], v[184:187], v[38:41]
	v_mfma_f32_16x16x32_f16 v[34:37], v[230:233], v[184:187], v[34:37]
	v_mfma_f32_16x16x32_f16 v[22:25], v[222:225], v[206:209], v[22:25]
	v_mfma_f32_16x16x32_f16 v[18:21], v[230:233], v[206:209], v[18:21]
	v_mfma_f32_16x16x32_f16 v[6:9], v[222:225], v[214:217], v[6:9]
	v_mfma_f32_16x16x32_f16 v[2:5], v[230:233], v[214:217], v[2:5]
	s_setprio 0
	v_or_b32_e32 v152, 0x18000, v158
	v_add_u32_e32 v159, 0x18400, v158
	s_barrier
	ds_read_b128 v[152:155], v152
	ds_read_b128 v[160:163], v159
	v_add_u32_e32 v159, 0x18800, v158
	v_add_u32_e32 v168, 0x18c00, v158
	ds_read_b128 v[164:167], v159
	ds_read_b128 v[168:171], v168
	s_add_u32 s26, s26, 0x100000
	s_addc_u32 s27, s27, 0
	s_mov_b32 m0, s41
	v_lshl_add_u64 v[218:219], s[26:27], 0, v[0:1]
	ds_read_b128 v[172:175], v135 offset:32768
	ds_read_b128 v[176:179], v135 offset:33792
	ds_read_b128 v[180:183], v135 offset:34816
	ds_read_b128 v[184:187], v135 offset:35840
	ds_read_b128 v[202:205], v135 offset:36864
	ds_read_b128 v[206:209], v135 offset:37888
	ds_read_b128 v[210:213], v135 offset:38912
	ds_read_b128 v[214:217], v135 offset:39936
	global_load_lds_dwordx4 v[218:219], off
	v_lshl_add_u64 v[218:219], s[26:27], 0, v[130:131]
	s_mov_b32 m0, s42
	s_nop 0
	global_load_lds_dwordx4 v[218:219], off
	s_waitcnt lgkmcnt(8)
	s_barrier
	s_waitcnt lgkmcnt(0)
	s_setprio 1
	s_waitcnt lgkmcnt(0)
	v_mfma_f32_16x16x32_f16 v[126:129], v[152:155], v[172:175], v[126:129]
	v_mfma_f32_16x16x32_f16 v[122:125], v[164:167], v[172:175], v[122:125]
	v_mfma_f32_16x16x32_f16 v[110:113], v[152:155], v[180:183], v[110:113]
	v_mfma_f32_16x16x32_f16 v[106:109], v[164:167], v[180:183], v[106:109]
	v_mfma_f32_16x16x32_f16 v[94:97], v[152:155], v[202:205], v[94:97]
	v_mfma_f32_16x16x32_f16 v[90:93], v[164:167], v[202:205], v[90:93]
	v_mfma_f32_16x16x32_f16 v[78:81], v[152:155], v[210:213], v[78:81]
	v_mfma_f32_16x16x32_f16 v[74:77], v[164:167], v[210:213], v[74:77]
	v_mfma_f32_16x16x32_f16 v[126:129], v[160:163], v[176:179], v[126:129]
	v_mfma_f32_16x16x32_f16 v[122:125], v[168:171], v[176:179], v[122:125]
	v_mfma_f32_16x16x32_f16 v[110:113], v[160:163], v[184:187], v[110:113]
	v_mfma_f32_16x16x32_f16 v[106:109], v[168:171], v[184:187], v[106:109]
	v_mfma_f32_16x16x32_f16 v[94:97], v[160:163], v[206:209], v[94:97]
	v_mfma_f32_16x16x32_f16 v[90:93], v[168:171], v[206:209], v[90:93]
	v_mfma_f32_16x16x32_f16 v[78:81], v[160:163], v[214:217], v[78:81]
	v_mfma_f32_16x16x32_f16 v[74:77], v[168:171], v[214:217], v[74:77]
	s_setprio 0
	s_barrier
	v_or_b32_e32 v159, 0x1c000, v158
	s_mov_b32 m0, s44
	v_add_u32_e32 v195, 0x1c400, v158
	ds_read_b128 v[218:221], v159
	ds_read_b128 v[222:225], v195
	v_add_u32_e32 v159, 0x1c800, v158
	v_lshl_add_u64 v[140:141], v[140:141], 0, s[94:95]
	v_add_u32_e32 v195, 0x1cc00, v158
	ds_read_b128 v[226:229], v159
	ds_read_b128 v[230:233], v195
	global_load_lds_dwordx4 v[140:141], off
	v_lshl_add_u64 v[140:141], v[156:157], 0, s[94:95]
	s_mov_b32 m0, s45
	s_nop 0
	global_load_lds_dwordx4 v[140:141], off
	s_barrier
	s_waitcnt lgkmcnt(0)
	s_setprio 1
	s_waitcnt lgkmcnt(0)
	v_mfma_f32_16x16x32_f16 v[118:121], v[218:221], v[172:175], v[118:121]
	v_mfma_f32_16x16x32_f16 v[114:117], v[226:229], v[172:175], v[114:117]
	v_mfma_f32_16x16x32_f16 v[102:105], v[218:221], v[180:183], v[102:105]
	v_mfma_f32_16x16x32_f16 v[98:101], v[226:229], v[180:183], v[98:101]
	v_mfma_f32_16x16x32_f16 v[86:89], v[218:221], v[202:205], v[86:89]
	v_mfma_f32_16x16x32_f16 v[82:85], v[226:229], v[202:205], v[82:85]
	v_mfma_f32_16x16x32_f16 v[70:73], v[218:221], v[210:213], v[70:73]
	v_mfma_f32_16x16x32_f16 v[66:69], v[226:229], v[210:213], v[66:69]
	v_mfma_f32_16x16x32_f16 v[118:121], v[222:225], v[176:179], v[118:121]
	v_mfma_f32_16x16x32_f16 v[114:117], v[230:233], v[176:179], v[114:117]
	v_mfma_f32_16x16x32_f16 v[102:105], v[222:225], v[184:187], v[102:105]
	v_mfma_f32_16x16x32_f16 v[98:101], v[230:233], v[184:187], v[98:101]
	v_mfma_f32_16x16x32_f16 v[86:89], v[222:225], v[206:209], v[86:89]
	v_mfma_f32_16x16x32_f16 v[82:85], v[230:233], v[206:209], v[82:85]
	v_mfma_f32_16x16x32_f16 v[70:73], v[222:225], v[214:217], v[70:73]
	v_mfma_f32_16x16x32_f16 v[66:69], v[230:233], v[214:217], v[66:69]
	s_setprio 0
	s_mov_b32 m0, s46
	v_lshl_add_u64 v[140:141], v[188:189], 0, s[94:95]
	s_barrier
; #define G8_STAGE(bufoff, gbase) do { _Pragma("unroll") for (int _i = 0; _i < 2; ++_i) \
;     __builtin_amdgcn_global_load_lds((const unsigned*)((const char*)(gbase) + voffA[_i]), (LAS unsigned*)(lds + (bufoff) + ldsw + _i * 8192), 16, 0, 0); } while (0)
; #define G8_LDA(dst, b, h) do { _Pragma("unroll") for (int m = 0; m < 4; ++m) _Pragma("unroll") for (int k = 0; k < 2; ++k) dst[m][k] = *(const LAS h16x8*)(lds + G8_SA(b, h) + aoff + m * 2048 + k * 1024); } while (0)
; #define G8_MMA(ai, bj, At, Bt_) do { __builtin_amdgcn_s_setprio(1); _Pragma("unroll") for (int m = 0; m < 4; ++m) _Pragma("unroll") for (int n = 0; n < 2; ++n) _Pragma("unroll") for (int k = 0; k < 2; ++k) \
;     acc[ai][bj][m][n] = __builtin_amdgcn_mfma_f32_16x16x32_f16(Bt_[n][k], At[m][k], acc[ai][bj][m][n], 0, 0, 0); __builtin_amdgcn_s_setprio(0); } while (0)
; #define G8_WAIT_V(n) asm volatile("s_waitcnt vmcnt(" #n ")" ::: "memory")
; template <class Epi>
; __device__ __forceinline__ void gemm_phase(LAS unsigned char* lds, const h16* A, const h16* Bt, int K, const Order& S, const Epi& E) {
;     ...
;       G8_LDA(At, 1, 1); G8_STAGE(G8_SA(1, 0), a3);
;       G8_BAR; G8_WAIT_L(0); G8_MMA(1, 0, At, B0); G8_BAR; G8_SCHED;
;       G8_STAGE(G8_SB(1, 1), b3 + hstep);
;       G8_WAIT_V(6); G8_BAR; G8_MMA(1, 1, At, B1); G8_BAR;
;     }
;   __device__ __forceinline__ void operator()(const f32x4 (&acc)[2][2][4][2], const g8::Unit& u, int ui, int wr, int wc, int fr, int fq) const {
; #pragma unroll
;     for (int ai = 0; ai < 2; ++ai)
; #pragma unroll
;       for (int m = 0; m < 4; ++m) {
;         const size_t row = (size_t)u.pm * 256 + 128 * ai + 64 * wr + 16 * m + fr;
;         const size_t base = row * DM + 256 * u.pn + 32 * wc + 8 * fq;
;         float ss = 0.f;
; #pragma unroll
;         for (int bj = 0; bj < 2; ++bj) {
;           const size_t idx = base + 128 * bj;
;           const h16x8 xv = *(const h16x8*)(xb + idx);
;           f32x4 x0 = acc[ai][bj][m][0], x1 = acc[ai][bj][m][1];
; #pragma unroll
;           for (int j = 0; j < 4; ++j) { x0[j] += (float)xv[j]; x1[j] += (float)xv[4 + j]; ss += x0[j] * x0[j] + x1[j] * x1[j]; }
;           if (final_out) {
;             __builtin_nontemporal_store(x0, (f32x4*)(xo + idx));
;             __builtin_nontemporal_store(x1, (f32x4*)(xo + idx + 4));
;           } else {
;             *(h16x8*)(xb + idx) = pack8(x0, x1);
	ds_read_b128 v[172:175], v135 offset:49152
	ds_read_b128 v[176:179], v135 offset:50176
	ds_read_b128 v[180:183], v135 offset:51200
	ds_read_b128 v[184:187], v135 offset:52224
	ds_read_b128 v[202:205], v135 offset:53248
	ds_read_b128 v[206:209], v135 offset:54272
	ds_read_b128 v[210:213], v135 offset:55296
	ds_read_b128 v[214:217], v135 offset:56320
	global_load_lds_dwordx4 v[140:141], off
	v_lshl_add_u64 v[140:141], v[234:235], 0, s[94:95]
	s_mov_b32 m0, s47
	s_nop 0
	global_load_lds_dwordx4 v[140:141], off
	s_barrier
	s_waitcnt lgkmcnt(0)
	s_setprio 1
	s_waitcnt lgkmcnt(0)
	v_mfma_f32_16x16x32_f16 v[62:65], v[152:155], v[172:175], v[62:65]
	v_mfma_f32_16x16x32_f16 v[58:61], v[164:167], v[172:175], v[58:61]
	v_mfma_f32_16x16x32_f16 v[46:49], v[152:155], v[180:183], v[46:49]
	v_mfma_f32_16x16x32_f16 v[42:45], v[164:167], v[180:183], v[42:45]
	v_mfma_f32_16x16x32_f16 v[30:33], v[152:155], v[202:205], v[30:33]
	v_mfma_f32_16x16x32_f16 v[26:29], v[164:167], v[202:205], v[26:29]
	v_mfma_f32_16x16x32_f16 v[14:17], v[152:155], v[210:213], v[14:17]
	v_mfma_f32_16x16x32_f16 v[10:13], v[164:167], v[210:213], v[10:13]
	v_mfma_f32_16x16x32_f16 v[62:65], v[160:163], v[176:179], v[62:65]
	v_mfma_f32_16x16x32_f16 v[58:61], v[168:171], v[176:179], v[58:61]
	v_mfma_f32_16x16x32_f16 v[46:49], v[160:163], v[184:187], v[46:49]
	v_mfma_f32_16x16x32_f16 v[42:45], v[168:171], v[184:187], v[42:45]
	v_mfma_f32_16x16x32_f16 v[30:33], v[160:163], v[206:209], v[30:33]
	v_mfma_f32_16x16x32_f16 v[26:29], v[168:171], v[206:209], v[26:29]
	v_mfma_f32_16x16x32_f16 v[14:17], v[160:163], v[214:217], v[14:17]
	v_mfma_f32_16x16x32_f16 v[10:13], v[168:171], v[214:217], v[10:13]
	s_setprio 0
	s_barrier
	s_add_u32 s24, s24, 0x100080
	s_addc_u32 s25, s25, 0
	s_mov_b32 m0, s48
	v_lshl_add_u64 v[140:141], s[24:25], 0, v[0:1]
	global_load_lds_dwordx4 v[140:141], off
	v_lshl_add_u64 v[140:141], s[24:25], 0, v[130:131]
	s_mov_b32 m0, s49
	s_nop 0
	global_load_lds_dwordx4 v[140:141], off
	s_waitcnt vmcnt(6)
	s_barrier
	s_setprio 1
	v_mfma_f32_16x16x32_f16 v[54:57], v[218:221], v[172:175], v[54:57]
	v_mfma_f32_16x16x32_f16 v[50:53], v[226:229], v[172:175], v[50:53]
	v_mfma_f32_16x16x32_f16 v[38:41], v[218:221], v[180:183], v[38:41]
	v_mfma_f32_16x16x32_f16 v[34:37], v[226:229], v[180:183], v[34:37]
	v_mfma_f32_16x16x32_f16 v[22:25], v[218:221], v[202:205], v[22:25]
	v_mfma_f32_16x16x32_f16 v[18:21], v[226:229], v[202:205], v[18:21]
	v_mfma_f32_16x16x32_f16 v[6:9], v[218:221], v[210:213], v[6:9]
	v_mfma_f32_16x16x32_f16 v[2:5], v[226:229], v[210:213], v[2:5]
	v_mfma_f32_16x16x32_f16 v[54:57], v[222:225], v[176:179], v[54:57]
	v_mfma_f32_16x16x32_f16 v[50:53], v[230:233], v[176:179], v[50:53]
	v_mfma_f32_16x16x32_f16 v[38:41], v[222:225], v[184:187], v[38:41]
	v_mfma_f32_16x16x32_f16 v[34:37], v[230:233], v[184:187], v[34:37]
	v_mfma_f32_16x16x32_f16 v[22:25], v[222:225], v[206:209], v[22:25]
	v_mfma_f32_16x16x32_f16 v[18:21], v[230:233], v[206:209], v[18:21]
	v_mfma_f32_16x16x32_f16 v[6:9], v[222:225], v[214:217], v[6:9]
	v_mfma_f32_16x16x32_f16 v[2:5], v[230:233], v[214:217], v[2:5]
	s_setprio 0
	s_add_i32 s53, s53, 2
	s_add_u32 s22, s22, 0x100
	s_addc_u32 s23, s23, 0
	s_add_u32 s51, s51, 0x100
	s_addc_u32 s52, s52, 0
	s_cmp_gt_u32 s53, 61
	s_barrier
	s_cbranch_scc0 .LBB0_2542
	s_ashr_i32 s9, s8, 31
	s_lshl_b64 s[8:9], s[8:9], 8
	s_lshl_b32 s3, s2, 8
	v_lshl_add_u64 v[140:141], s[8:9], 0, v[132:133]
	s_ashr_i32 s8, s3, 31
	v_mov_b32_e32 v153, s8
	v_or_b32_e32 v152, s3, v134
	v_lshlrev_b64 v[154:155], 10, v[140:141]
	v_lshl_add_u64 v[156:157], v[154:155], 0, v[152:153]
	v_lshl_add_u64 v[154:155], v[156:157], 1, s[10:11]
	global_load_dwordx4 v[160:163], v[154:155], off
	s_mov_b64 s[8:9], -1
	s_and_b64 vcc, exec, s[0:1]
	s_waitcnt vmcnt(0)
	v_cvt_f32_f16_e32 v164, v160
	v_cvt_f32_f16_sdwa v165, v160 dst_sel:DWORD dst_unused:UNUSED_PAD src0_sel:WORD_1
	v_cvt_f32_f16_e32 v160, v161
	v_cvt_f32_f16_sdwa v161, v161 dst_sel:DWORD dst_unused:UNUSED_PAD src0_sel:WORD_1
	v_pk_add_f32 v[126:127], v[126:127], v[164:165]
	v_cvt_f32_f16_e32 v164, v162
	v_cvt_f32_f16_sdwa v165, v162 dst_sel:DWORD dst_unused:UNUSED_PAD src0_sel:WORD_1
	v_pk_add_f32 v[128:129], v[128:129], v[160:161]
	v_cvt_f32_f16_e32 v160, v163
	v_cvt_f32_f16_sdwa v161, v163 dst_sel:DWORD dst_unused:UNUSED_PAD src0_sel:WORD_1
	v_pk_add_f32 v[122:123], v[122:123], v[164:165]
	v_pk_add_f32 v[124:125], v[124:125], v[160:161]
	s_cbranch_vccz .LBB0_2545
	v_cvt_pk_f16_f32 v163, v124, v125
	v_cvt_pk_f16_f32 v162, v122, v123
	v_cvt_pk_f16_f32 v161, v128, v129
	v_cvt_pk_f16_f32 v160, v126, v127
	global_store_dwordx4 v[154:155], v[160:163], off
	s_mov_b64 s[8:9], 0
